# Barrier that ends each MFMA burst signalled two MFMAs early in all GEMM main loops
# baseline (speedup 1.0000x reference)
; #define PG8_STAGE(bufoff, gbase, voff) do { _Pragma("unroll") for (int _i = 0; _i < 2; ++_i) \
;         __builtin_amdgcn_global_load_lds((const unsigned*)((const char*)(gbase) + (voff)[_i]), (PG8_LAS unsigned*)(lds + (bufoff) + ldsw + _i * 8192), 16, 0, 0); } while (0)
; #define PG8_LDA(dst, b, h) do { _Pragma("unroll") for (int m = 0; m < 4; ++m) _Pragma("unroll") for (int k = 0; k < 2; ++k) dst[m][k] = *(const PG8_LAS bf16x8*)(lds + PG8_SA(b, h) + aoff + m * 2048 + k * 1024); } while (0)
; #define PG8_LDB(dst, b, h) do { _Pragma("unroll") for (int n = 0; n < 2; ++n) _Pragma("unroll") for (int k = 0; k < 2; ++k) dst[n][k] = *(const PG8_LAS bf16x8*)(lds + PG8_SB(b, h) + boff + n * 2048 + k * 1024); } while (0)
; #define PG8_MMA(ai, bj, At, Bt) do { __builtin_amdgcn_s_setprio(1); _Pragma("unroll") for (int m = 0; m < 4; ++m) _Pragma("unroll") for (int n = 0; n < 2; ++n) _Pragma("unroll") for (int k = 0; k < 2; ++k) \
;         acc[ai][bj][m][n] = __builtin_amdgcn_mfma_f32_16x16x32_bf16(Bt[n][k], At[m][k], acc[ai][bj][m][n], 0, 0, 0); __builtin_amdgcn_s_setprio(0); } while (0)
; #define PG8_WAIT_V(n) asm volatile("s_waitcnt vmcnt(" #n ")" ::: "memory")
; #define PG8_WAIT_L(n) asm volatile("s_waitcnt lgkmcnt(" #n ")" ::: "memory")
; #define PG8_BAR __builtin_amdgcn_s_barrier()
; #define PG8_SCHED __builtin_amdgcn_sched_barrier(0)
; template <class Epi, class Sched, bool ALIGN_EPI = false, bool SP2 = false>
; __device__ __forceinline__ void gemm_phase(PG8_LAS unsigned char* lds, const Gemm g, const Sched& S, const Epi& E) {
;     ...
;             const char* a1 = cA + (size_t)(t + 1) * kstep;
;             const char* a2 = last ? nA : cA + (size_t)(t + 2) * kstep; const char* b2 = last ? nB : cB + (size_t)(t + 2) * kstep;
;             const char* a3 = a2 + kstep; const char* b3 = b2 + kstep;
;             if constexpr (SP2) {
;             PG8_LDB(B0, 0, 0); PG8_LDB(B1, 0, 1); PG8_SCHED; PG8_LDA(At, 0, 0); PG8_STAGE(PG8_SA(1, 1), a1 + hstep, voffA);
;             PG8_WAIT_V(8); PG8_WAIT_L(0); PG8_BAR; PG8_MMA(0, 0, At, B0); PG8_MMA(0, 1, At, B1); PG8_BAR; PG8_SCHED;
;             PG8_LDA(At, 0, 1); PG8_STAGE(PG8_SB(0, 0), b2, voffB); PG8_STAGE(PG8_SB(0, 1), b2 + hstep, voffB); PG8_STAGE(PG8_SA(0, 0), a2, voffA);
;             PG8_WAIT_V(8); PG8_WAIT_L(0); PG8_BAR; PG8_MMA(1, 0, At, B0); PG8_MMA(1, 1, At, B1); PG8_BAR; PG8_SCHED;
.LBB0_200:
	ds_read_b128 v[148:151], v164
	ds_read_b128 v[152:155], v164 offset:1024
	ds_read_b128 v[156:159], v164 offset:2048
	ds_read_b128 v[168:171], v164 offset:3072
	ds_read_b128 v[172:175], v165
	ds_read_b128 v[176:179], v165 offset:1024
	ds_read_b128 v[180:183], v165 offset:2048
	ds_read_b128 v[184:187], v165 offset:3072
	s_add_u32 s52, s70, 0xfff80080
	s_addc_u32 s53, s71, -1
	s_cmp_eq_u32 s93, 28
	s_cselect_b32 s75, s39, s53
	s_cselect_b32 s74, s69, s52
	s_cselect_b32 s73, s35, s92
	s_cselect_b32 s72, s90, s91
	v_lshl_add_u64 v[220:221], s[70:71], 0, v[138:139]
	s_add_i32 m0, s33, 0xc000
	ds_read_b128 v[188:191], v166
	ds_read_b128 v[192:195], v166 offset:1024
	ds_read_b128 v[196:199], v166 offset:2048
	ds_read_b128 v[200:203], v166 offset:3072
	ds_read_b128 v[204:207], v166 offset:4096
	ds_read_b128 v[208:211], v166 offset:5120
	ds_read_b128 v[212:215], v166 offset:6144
	ds_read_b128 v[216:219], v166 offset:7168
	global_load_lds_dwordx4 v[220:221], off
	v_lshl_add_u64 v[220:221], s[70:71], 0, v[140:141]
	s_add_i32 m0, s33, 0xe000
	s_nop 0
	global_load_lds_dwordx4 v[220:221], off
	s_waitcnt vmcnt(8)
	s_waitcnt lgkmcnt(0)
	s_barrier
	s_setprio 1
	s_waitcnt lgkmcnt(0)
	v_mfma_f32_16x16x32_bf16 v[124:127], v[148:151], v[188:191], v[124:127]
	v_mfma_f32_16x16x32_bf16 v[120:123], v[156:159], v[188:191], v[120:123]
	v_mfma_f32_16x16x32_bf16 v[116:119], v[148:151], v[196:199], v[116:119]
	v_mfma_f32_16x16x32_bf16 v[108:111], v[156:159], v[196:199], v[108:111]
	v_mfma_f32_16x16x32_bf16 v[100:103], v[148:151], v[204:207], v[100:103]
	v_mfma_f32_16x16x32_bf16 v[92:95], v[156:159], v[204:207], v[92:95]
	v_mfma_f32_16x16x32_bf16 v[84:87], v[148:151], v[212:215], v[84:87]
	v_mfma_f32_16x16x32_bf16 v[76:79], v[156:159], v[212:215], v[76:79]
	v_mfma_f32_16x16x32_bf16 v[124:127], v[152:155], v[192:195], v[124:127]
	v_mfma_f32_16x16x32_bf16 v[120:123], v[168:171], v[192:195], v[120:123]
	v_mfma_f32_16x16x32_bf16 v[116:119], v[152:155], v[200:203], v[116:119]
	v_mfma_f32_16x16x32_bf16 v[108:111], v[168:171], v[200:203], v[108:111]
	v_mfma_f32_16x16x32_bf16 v[100:103], v[152:155], v[208:211], v[100:103]
	v_mfma_f32_16x16x32_bf16 v[92:95], v[168:171], v[208:211], v[92:95]
	v_mfma_f32_16x16x32_bf16 v[84:87], v[152:155], v[216:219], v[84:87]
	v_mfma_f32_16x16x32_bf16 v[76:79], v[168:171], v[216:219], v[76:79]
	s_setprio 0
	s_setprio 1
	v_mfma_f32_16x16x32_bf16 v[112:115], v[172:175], v[188:191], v[112:115]
	v_mfma_f32_16x16x32_bf16 v[104:107], v[180:183], v[188:191], v[104:107]
	v_mfma_f32_16x16x32_bf16 v[96:99], v[172:175], v[196:199], v[96:99]
	v_mfma_f32_16x16x32_bf16 v[88:91], v[180:183], v[196:199], v[88:91]
	v_mfma_f32_16x16x32_bf16 v[80:83], v[172:175], v[204:207], v[80:83]
	v_mfma_f32_16x16x32_bf16 v[72:75], v[180:183], v[204:207], v[72:75]
	v_mfma_f32_16x16x32_bf16 v[68:71], v[172:175], v[212:215], v[68:71]
	v_mfma_f32_16x16x32_bf16 v[64:67], v[180:183], v[212:215], v[64:67]
	v_mfma_f32_16x16x32_bf16 v[112:115], v[176:179], v[192:195], v[112:115]
	v_mfma_f32_16x16x32_bf16 v[104:107], v[184:187], v[192:195], v[104:107]
	v_mfma_f32_16x16x32_bf16 v[96:99], v[176:179], v[200:203], v[96:99]
	v_mfma_f32_16x16x32_bf16 v[88:91], v[184:187], v[200:203], v[88:91]
	v_mfma_f32_16x16x32_bf16 v[80:83], v[176:179], v[208:211], v[80:83]
	v_mfma_f32_16x16x32_bf16 v[72:75], v[184:187], v[208:211], v[72:75]
	s_barrier
	v_mfma_f32_16x16x32_bf16 v[68:71], v[176:179], v[216:219], v[68:71]
	v_mfma_f32_16x16x32_bf16 v[64:67], v[184:187], v[216:219], v[64:67]
	s_setprio 0
	s_add_i32 s52, s84, s3
	v_lshl_add_u64 v[220:221], s[72:73], 0, v[132:133]
	s_mov_b32 m0, s52
	ds_read_b128 v[188:191], v166 offset:16384
	ds_read_b128 v[192:195], v166 offset:17408
	ds_read_b128 v[196:199], v166 offset:18432
	ds_read_b128 v[200:203], v166 offset:19456
	ds_read_b128 v[204:207], v166 offset:20480
	ds_read_b128 v[208:211], v166 offset:21504
	ds_read_b128 v[212:215], v166 offset:22528
	ds_read_b128 v[216:219], v166 offset:23552
	global_load_lds_dwordx4 v[220:221], off
	s_add_i32 m0, s52, 0x2000
	s_add_u32 s96, s72, 0x80000
	v_lshl_add_u64 v[222:223], s[72:73], 0, v[128:129]
	s_addc_u32 s97, s73, 0
	s_add_i32 s52, s85, s3
	global_load_lds_dwordx4 v[222:223], off
	v_lshl_add_u64 v[224:225], s[96:97], 0, v[132:133]
	s_mov_b32 m0, s52
	v_lshl_add_u64 v[226:227], s[74:75], 0, v[130:131]
	global_load_lds_dwordx4 v[224:225], off
	v_lshl_add_u64 v[224:225], s[96:97], 0, v[128:129]
	s_add_i32 m0, s52, 0x2000
	s_nop 0
	global_load_lds_dwordx4 v[224:225], off
	v_lshl_add_u64 v[224:225], s[74:75], 0, v[134:135]
	s_mov_b32 m0, s33
	s_nop 0
	global_load_lds_dwordx4 v[224:225], off
	s_mov_b32 m0, s76
	s_nop 0
	global_load_lds_dwordx4 v[226:227], off
	s_waitcnt vmcnt(8)
	s_waitcnt lgkmcnt(0)
	s_barrier
; #define PG8_STAGE(bufoff, gbase, voff) do { _Pragma("unroll") for (int _i = 0; _i < 2; ++_i) \
;         __builtin_amdgcn_global_load_lds((const unsigned*)((const char*)(gbase) + (voff)[_i]), (PG8_LAS unsigned*)(lds + (bufoff) + ldsw + _i * 8192), 16, 0, 0); } while (0)
; #define PG8_LDA(dst, b, h) do { _Pragma("unroll") for (int m = 0; m < 4; ++m) _Pragma("unroll") for (int k = 0; k < 2; ++k) dst[m][k] = *(const PG8_LAS bf16x8*)(lds + PG8_SA(b, h) + aoff + m * 2048 + k * 1024); } while (0)
; #define PG8_LDB(dst, b, h) do { _Pragma("unroll") for (int n = 0; n < 2; ++n) _Pragma("unroll") for (int k = 0; k < 2; ++k) dst[n][k] = *(const PG8_LAS bf16x8*)(lds + PG8_SB(b, h) + boff + n * 2048 + k * 1024); } while (0)
; #define PG8_MMA(ai, bj, At, Bt) do { __builtin_amdgcn_s_setprio(1); _Pragma("unroll") for (int m = 0; m < 4; ++m) _Pragma("unroll") for (int n = 0; n < 2; ++n) _Pragma("unroll") for (int k = 0; k < 2; ++k) \
;         acc[ai][bj][m][n] = __builtin_amdgcn_mfma_f32_16x16x32_bf16(Bt[n][k], At[m][k], acc[ai][bj][m][n], 0, 0, 0); __builtin_amdgcn_s_setprio(0); } while (0)
; #define PG8_WAIT_V(n) asm volatile("s_waitcnt vmcnt(" #n ")" ::: "memory")
; #define PG8_WAIT_L(n) asm volatile("s_waitcnt lgkmcnt(" #n ")" ::: "memory")
; #define PG8_BAR __builtin_amdgcn_s_barrier()
; #define PG8_SCHED __builtin_amdgcn_sched_barrier(0)
; template <class Epi, class Sched, bool ALIGN_EPI = false, bool SP2 = false>
; __device__ __forceinline__ void gemm_phase(PG8_LAS unsigned char* lds, const Gemm g, const Sched& S, const Epi& E) {
;     ...
;             PG8_WAIT_V(8); PG8_WAIT_L(0); PG8_BAR; PG8_MMA(1, 0, At, B0); PG8_MMA(1, 1, At, B1); PG8_BAR; PG8_SCHED;
;             PG8_LDB(B0, 1, 0); PG8_LDB(B1, 1, 1); PG8_SCHED; PG8_LDA(At, 1, 0); PG8_STAGE(PG8_SA(0, 1), a2 + hstep, voffA);
;             PG8_WAIT_V(8); PG8_WAIT_L(0); PG8_BAR; PG8_MMA(0, 0, At, B0); PG8_MMA(0, 1, At, B1); PG8_BAR; PG8_SCHED;
	s_setprio 1
	s_waitcnt lgkmcnt(0)
	v_mfma_f32_16x16x32_bf16 v[60:63], v[148:151], v[188:191], v[60:63]
	v_mfma_f32_16x16x32_bf16 v[56:59], v[156:159], v[188:191], v[56:59]
	v_mfma_f32_16x16x32_bf16 v[52:55], v[148:151], v[196:199], v[52:55]
	v_mfma_f32_16x16x32_bf16 v[44:47], v[156:159], v[196:199], v[44:47]
	v_mfma_f32_16x16x32_bf16 v[36:39], v[148:151], v[204:207], v[36:39]
	v_mfma_f32_16x16x32_bf16 v[28:31], v[156:159], v[204:207], v[28:31]
	v_mfma_f32_16x16x32_bf16 v[20:23], v[148:151], v[212:215], v[20:23]
	v_mfma_f32_16x16x32_bf16 v[12:15], v[156:159], v[212:215], v[12:15]
	v_mfma_f32_16x16x32_bf16 v[60:63], v[152:155], v[192:195], v[60:63]
	v_mfma_f32_16x16x32_bf16 v[56:59], v[168:171], v[192:195], v[56:59]
	v_mfma_f32_16x16x32_bf16 v[52:55], v[152:155], v[200:203], v[52:55]
	v_mfma_f32_16x16x32_bf16 v[44:47], v[168:171], v[200:203], v[44:47]
	v_mfma_f32_16x16x32_bf16 v[36:39], v[152:155], v[208:211], v[36:39]
	v_mfma_f32_16x16x32_bf16 v[28:31], v[168:171], v[208:211], v[28:31]
	v_mfma_f32_16x16x32_bf16 v[20:23], v[152:155], v[216:219], v[20:23]
	v_mfma_f32_16x16x32_bf16 v[12:15], v[168:171], v[216:219], v[12:15]
	s_setprio 0
	s_setprio 1
	v_mfma_f32_16x16x32_bf16 v[48:51], v[172:175], v[188:191], v[48:51]
	v_mfma_f32_16x16x32_bf16 v[40:43], v[180:183], v[188:191], v[40:43]
	v_mfma_f32_16x16x32_bf16 v[32:35], v[172:175], v[196:199], v[32:35]
	v_mfma_f32_16x16x32_bf16 v[24:27], v[180:183], v[196:199], v[24:27]
	v_mfma_f32_16x16x32_bf16 v[16:19], v[172:175], v[204:207], v[16:19]
	v_mfma_f32_16x16x32_bf16 v[8:11], v[180:183], v[204:207], v[8:11]
	v_mfma_f32_16x16x32_bf16 v[4:7], v[172:175], v[212:215], v[4:7]
	v_mfma_f32_16x16x32_bf16 v[0:3], v[180:183], v[212:215], v[0:3]
	v_mfma_f32_16x16x32_bf16 v[48:51], v[176:179], v[192:195], v[48:51]
	v_mfma_f32_16x16x32_bf16 v[40:43], v[184:187], v[192:195], v[40:43]
	v_mfma_f32_16x16x32_bf16 v[32:35], v[176:179], v[200:203], v[32:35]
	v_mfma_f32_16x16x32_bf16 v[24:27], v[184:187], v[200:203], v[24:27]
	v_mfma_f32_16x16x32_bf16 v[16:19], v[176:179], v[208:211], v[16:19]
	v_mfma_f32_16x16x32_bf16 v[8:11], v[184:187], v[208:211], v[8:11]
	s_barrier
	v_mfma_f32_16x16x32_bf16 v[4:7], v[176:179], v[216:219], v[4:7]
	v_mfma_f32_16x16x32_bf16 v[0:3], v[184:187], v[216:219], v[0:3]
	s_setprio 0
	s_add_i32 s52, 0, 0x18000
	v_add_u32_e32 v136, s52, v161
	s_add_i32 s53, 0, 0x1c000
	ds_read_b128 v[148:151], v136
	ds_read_b128 v[152:155], v136 offset:1024
	ds_read_b128 v[156:159], v136 offset:2048
	ds_read_b128 v[168:171], v136 offset:3072
	v_add_u32_e32 v136, s53, v161
	ds_read_b128 v[172:175], v136
	ds_read_b128 v[176:179], v136 offset:1024
	ds_read_b128 v[180:183], v136 offset:2048
	ds_read_b128 v[184:187], v136 offset:3072
	s_add_u32 s74, s74, 0x80000
	s_addc_u32 s75, s75, 0
	s_mov_b32 m0, s77
	v_lshl_add_u64 v[228:229], s[74:75], 0, v[134:135]
	ds_read_b128 v[188:191], v166 offset:32768
	ds_read_b128 v[192:195], v166 offset:33792
	ds_read_b128 v[196:199], v166 offset:34816
	ds_read_b128 v[200:203], v166 offset:35840
	ds_read_b128 v[204:207], v166 offset:36864
	ds_read_b128 v[208:211], v166 offset:37888
	ds_read_b128 v[212:215], v166 offset:38912
	ds_read_b128 v[216:219], v166 offset:39936
	global_load_lds_dwordx4 v[228:229], off
	v_lshl_add_u64 v[228:229], s[74:75], 0, v[130:131]
	s_mov_b32 m0, s78
	s_nop 0
	global_load_lds_dwordx4 v[228:229], off
	s_waitcnt vmcnt(8)
	s_waitcnt lgkmcnt(0)
	s_barrier
	s_setprio 1
	s_waitcnt lgkmcnt(0)
	v_mfma_f32_16x16x32_bf16 v[124:127], v[148:151], v[188:191], v[124:127]
	v_mfma_f32_16x16x32_bf16 v[120:123], v[156:159], v[188:191], v[120:123]
	v_mfma_f32_16x16x32_bf16 v[116:119], v[148:151], v[196:199], v[116:119]
	v_mfma_f32_16x16x32_bf16 v[108:111], v[156:159], v[196:199], v[108:111]
	v_mfma_f32_16x16x32_bf16 v[100:103], v[148:151], v[204:207], v[100:103]
	v_mfma_f32_16x16x32_bf16 v[92:95], v[156:159], v[204:207], v[92:95]
	v_mfma_f32_16x16x32_bf16 v[84:87], v[148:151], v[212:215], v[84:87]
	v_mfma_f32_16x16x32_bf16 v[76:79], v[156:159], v[212:215], v[76:79]
	v_mfma_f32_16x16x32_bf16 v[124:127], v[152:155], v[192:195], v[124:127]
	v_mfma_f32_16x16x32_bf16 v[120:123], v[168:171], v[192:195], v[120:123]
	v_mfma_f32_16x16x32_bf16 v[116:119], v[152:155], v[200:203], v[116:119]
	v_mfma_f32_16x16x32_bf16 v[108:111], v[168:171], v[200:203], v[108:111]
	v_mfma_f32_16x16x32_bf16 v[100:103], v[152:155], v[208:211], v[100:103]
	v_mfma_f32_16x16x32_bf16 v[92:95], v[168:171], v[208:211], v[92:95]
	v_mfma_f32_16x16x32_bf16 v[84:87], v[152:155], v[216:219], v[84:87]
	v_mfma_f32_16x16x32_bf16 v[76:79], v[168:171], v[216:219], v[76:79]
	s_setprio 0
	s_setprio 1
	v_mfma_f32_16x16x32_bf16 v[112:115], v[172:175], v[188:191], v[112:115]
	v_mfma_f32_16x16x32_bf16 v[104:107], v[180:183], v[188:191], v[104:107]
	v_mfma_f32_16x16x32_bf16 v[96:99], v[172:175], v[196:199], v[96:99]
	v_mfma_f32_16x16x32_bf16 v[88:91], v[180:183], v[196:199], v[88:91]
	v_mfma_f32_16x16x32_bf16 v[80:83], v[172:175], v[204:207], v[80:83]
	v_mfma_f32_16x16x32_bf16 v[72:75], v[180:183], v[204:207], v[72:75]
	v_mfma_f32_16x16x32_bf16 v[68:71], v[172:175], v[212:215], v[68:71]
	v_mfma_f32_16x16x32_bf16 v[64:67], v[180:183], v[212:215], v[64:67]
	v_mfma_f32_16x16x32_bf16 v[112:115], v[176:179], v[192:195], v[112:115]
	v_mfma_f32_16x16x32_bf16 v[104:107], v[184:187], v[192:195], v[104:107]
	v_mfma_f32_16x16x32_bf16 v[96:99], v[176:179], v[200:203], v[96:99]
	v_mfma_f32_16x16x32_bf16 v[88:91], v[184:187], v[200:203], v[88:91]
	v_mfma_f32_16x16x32_bf16 v[80:83], v[176:179], v[208:211], v[80:83]
	v_mfma_f32_16x16x32_bf16 v[72:75], v[184:187], v[208:211], v[72:75]
	s_barrier
; #define PG8_STAGE(bufoff, gbase, voff) do { _Pragma("unroll") for (int _i = 0; _i < 2; ++_i) \
;         __builtin_amdgcn_global_load_lds((const unsigned*)((const char*)(gbase) + (voff)[_i]), (PG8_LAS unsigned*)(lds + (bufoff) + ldsw + _i * 8192), 16, 0, 0); } while (0)
; #define PG8_LDA(dst, b, h) do { _Pragma("unroll") for (int m = 0; m < 4; ++m) _Pragma("unroll") for (int k = 0; k < 2; ++k) dst[m][k] = *(const PG8_LAS bf16x8*)(lds + PG8_SA(b, h) + aoff + m * 2048 + k * 1024); } while (0)
; #define PG8_MMA(ai, bj, At, Bt) do { __builtin_amdgcn_s_setprio(1); _Pragma("unroll") for (int m = 0; m < 4; ++m) _Pragma("unroll") for (int n = 0; n < 2; ++n) _Pragma("unroll") for (int k = 0; k < 2; ++k) \
;         acc[ai][bj][m][n] = __builtin_amdgcn_mfma_f32_16x16x32_bf16(Bt[n][k], At[m][k], acc[ai][bj][m][n], 0, 0, 0); __builtin_amdgcn_s_setprio(0); } while (0)
; #define PG8_WAIT_V(n) asm volatile("s_waitcnt vmcnt(" #n ")" ::: "memory")
; #define PG8_WAIT_L(n) asm volatile("s_waitcnt lgkmcnt(" #n ")" ::: "memory")
; #define PG8_BAR __builtin_amdgcn_s_barrier()
; #define PG8_SCHED __builtin_amdgcn_sched_barrier(0)
; template <class Epi, class Sched, bool ALIGN_EPI = false, bool SP2 = false>
; __device__ __forceinline__ void gemm_phase(PG8_LAS unsigned char* lds, const Gemm g, const Sched& S, const Epi& E) {
;     ...
;             PG8_WAIT_V(8); PG8_WAIT_L(0); PG8_BAR; PG8_MMA(0, 0, At, B0); PG8_MMA(0, 1, At, B1); PG8_BAR; PG8_SCHED;
;             PG8_LDA(At, 1, 1); PG8_STAGE(PG8_SB(1, 0), b3, voffB); PG8_STAGE(PG8_SB(1, 1), b3 + hstep, voffB); PG8_STAGE(PG8_SA(1, 0), a3, voffA);
;             PG8_WAIT_V(8); PG8_WAIT_L(0); PG8_BAR; PG8_MMA(1, 0, At, B0); PG8_MMA(1, 1, At, B1); PG8_BAR; PG8_SCHED;
;     ...
;         if constexpr (ALIGN_EPI) { if (wr == 0) PG8_BAR; }
	v_mfma_f32_16x16x32_bf16 v[68:71], v[176:179], v[216:219], v[68:71]
	v_mfma_f32_16x16x32_bf16 v[64:67], v[184:187], v[216:219], v[64:67]
	s_setprio 0
	s_add_i32 s52, s52, s3
	v_lshl_add_u64 v[220:221], v[220:221], 0, s[12:13]
	s_mov_b32 m0, s52
	ds_read_b128 v[188:191], v166 offset:49152
	ds_read_b128 v[192:195], v166 offset:50176
	ds_read_b128 v[196:199], v166 offset:51200
	ds_read_b128 v[200:203], v166 offset:52224
	ds_read_b128 v[204:207], v166 offset:53248
	ds_read_b128 v[208:211], v166 offset:54272
	ds_read_b128 v[212:215], v166 offset:55296
	ds_read_b128 v[216:219], v166 offset:56320
	global_load_lds_dwordx4 v[220:221], off
	s_add_i32 m0, s52, 0x2000
	s_add_u32 s72, s72, 0x80080
	v_lshl_add_u64 v[220:221], v[222:223], 0, s[12:13]
	s_addc_u32 s73, s73, 0
	s_add_i32 s52, s53, s3
	global_load_lds_dwordx4 v[220:221], off
	v_lshl_add_u64 v[220:221], s[72:73], 0, v[132:133]
	s_mov_b32 m0, s52
	s_nop 0
	global_load_lds_dwordx4 v[220:221], off
	v_lshl_add_u64 v[220:221], s[72:73], 0, v[128:129]
	s_add_i32 m0, s52, 0x2000
	s_nop 0
	global_load_lds_dwordx4 v[220:221], off
	v_lshl_add_u64 v[220:221], v[224:225], 0, s[12:13]
	s_mov_b32 m0, s80
	s_nop 0
	global_load_lds_dwordx4 v[220:221], off
	v_lshl_add_u64 v[220:221], v[226:227], 0, s[12:13]
	s_mov_b32 m0, s81
	s_nop 0
	global_load_lds_dwordx4 v[220:221], off
	s_waitcnt vmcnt(8)
	s_waitcnt lgkmcnt(0)
	s_barrier
	s_setprio 1
	s_waitcnt lgkmcnt(0)
	v_mfma_f32_16x16x32_bf16 v[60:63], v[148:151], v[188:191], v[60:63]
	v_mfma_f32_16x16x32_bf16 v[56:59], v[156:159], v[188:191], v[56:59]
	v_mfma_f32_16x16x32_bf16 v[52:55], v[148:151], v[196:199], v[52:55]
	v_mfma_f32_16x16x32_bf16 v[44:47], v[156:159], v[196:199], v[44:47]
	v_mfma_f32_16x16x32_bf16 v[36:39], v[148:151], v[204:207], v[36:39]
	v_mfma_f32_16x16x32_bf16 v[28:31], v[156:159], v[204:207], v[28:31]
	v_mfma_f32_16x16x32_bf16 v[20:23], v[148:151], v[212:215], v[20:23]
	v_mfma_f32_16x16x32_bf16 v[12:15], v[156:159], v[212:215], v[12:15]
	v_mfma_f32_16x16x32_bf16 v[60:63], v[152:155], v[192:195], v[60:63]
	v_mfma_f32_16x16x32_bf16 v[56:59], v[168:171], v[192:195], v[56:59]
	v_mfma_f32_16x16x32_bf16 v[52:55], v[152:155], v[200:203], v[52:55]
	v_mfma_f32_16x16x32_bf16 v[44:47], v[168:171], v[200:203], v[44:47]
	v_mfma_f32_16x16x32_bf16 v[36:39], v[152:155], v[208:211], v[36:39]
	v_mfma_f32_16x16x32_bf16 v[28:31], v[168:171], v[208:211], v[28:31]
	v_mfma_f32_16x16x32_bf16 v[20:23], v[152:155], v[216:219], v[20:23]
	v_mfma_f32_16x16x32_bf16 v[12:15], v[168:171], v[216:219], v[12:15]
	s_setprio 0
	s_setprio 1
	v_mfma_f32_16x16x32_bf16 v[48:51], v[172:175], v[188:191], v[48:51]
	v_mfma_f32_16x16x32_bf16 v[40:43], v[180:183], v[188:191], v[40:43]
	v_mfma_f32_16x16x32_bf16 v[32:35], v[172:175], v[196:199], v[32:35]
	v_mfma_f32_16x16x32_bf16 v[24:27], v[180:183], v[196:199], v[24:27]
	v_mfma_f32_16x16x32_bf16 v[16:19], v[172:175], v[204:207], v[16:19]
	v_mfma_f32_16x16x32_bf16 v[8:11], v[180:183], v[204:207], v[8:11]
	v_mfma_f32_16x16x32_bf16 v[4:7], v[172:175], v[212:215], v[4:7]
	v_mfma_f32_16x16x32_bf16 v[0:3], v[180:183], v[212:215], v[0:3]
	v_mfma_f32_16x16x32_bf16 v[48:51], v[176:179], v[192:195], v[48:51]
	v_mfma_f32_16x16x32_bf16 v[40:43], v[184:187], v[192:195], v[40:43]
	v_mfma_f32_16x16x32_bf16 v[32:35], v[176:179], v[200:203], v[32:35]
	v_mfma_f32_16x16x32_bf16 v[24:27], v[184:187], v[200:203], v[24:27]
	v_mfma_f32_16x16x32_bf16 v[16:19], v[176:179], v[208:211], v[16:19]
	v_mfma_f32_16x16x32_bf16 v[8:11], v[184:187], v[208:211], v[8:11]
	s_barrier
	v_mfma_f32_16x16x32_bf16 v[4:7], v[176:179], v[216:219], v[4:7]
	v_mfma_f32_16x16x32_bf16 v[0:3], v[184:187], v[216:219], v[0:3]
	s_setprio 0
	s_add_i32 s93, s93, 2
	s_add_u32 s70, s70, 0x100
	s_addc_u32 s71, s71, 0
	s_add_u32 s91, s91, 0x100
	s_addc_u32 s92, s92, 0
	s_cmp_gt_u32 s93, 29
	s_cbranch_scc0 .LBB0_200
	s_and_b64 vcc, exec, s[14:15]
	s_cbranch_vccz .LBB0_203
	s_barrier

; #define PG8_STAGE(bufoff, gbase, voff) do { _Pragma("unroll") for (int _i = 0; _i < 2; ++_i) \
;         __builtin_amdgcn_global_load_lds((const unsigned*)((const char*)(gbase) + (voff)[_i]), (PG8_LAS unsigned*)(lds + (bufoff) + ldsw + _i * 8192), 16, 0, 0); } while (0)
; #define PG8_LDA(dst, b, h) do { _Pragma("unroll") for (int m = 0; m < 4; ++m) _Pragma("unroll") for (int k = 0; k < 2; ++k) dst[m][k] = *(const PG8_LAS bf16x8*)(lds + PG8_SA(b, h) + aoff + m * 2048 + k * 1024); } while (0)
; #define PG8_LDB(dst, b, h) do { _Pragma("unroll") for (int n = 0; n < 2; ++n) _Pragma("unroll") for (int k = 0; k < 2; ++k) dst[n][k] = *(const PG8_LAS bf16x8*)(lds + PG8_SB(b, h) + boff + n * 2048 + k * 1024); } while (0)
; #define PG8_MMA(ai, bj, At, Bt) do { __builtin_amdgcn_s_setprio(1); _Pragma("unroll") for (int m = 0; m < 4; ++m) _Pragma("unroll") for (int n = 0; n < 2; ++n) _Pragma("unroll") for (int k = 0; k < 2; ++k) \
;         acc[ai][bj][m][n] = __builtin_amdgcn_mfma_f32_16x16x32_bf16(Bt[n][k], At[m][k], acc[ai][bj][m][n], 0, 0, 0); __builtin_amdgcn_s_setprio(0); } while (0)
; #define PG8_WAIT_V(n) asm volatile("s_waitcnt vmcnt(" #n ")" ::: "memory")
; #define PG8_WAIT_L(n) asm volatile("s_waitcnt lgkmcnt(" #n ")" ::: "memory")
; #define PG8_BAR __builtin_amdgcn_s_barrier()
; #define PG8_SCHED __builtin_amdgcn_sched_barrier(0)
; template <class Epi, class Sched, bool ALIGN_EPI = false, bool SP2 = false>
; __device__ __forceinline__ void gemm_phase(PG8_LAS unsigned char* lds, const Gemm g, const Sched& S, const Epi& E) {
;     ...
;             const char* a1 = cA + (size_t)(t + 1) * kstep;
;             const char* a2 = last ? nA : cA + (size_t)(t + 2) * kstep; const char* b2 = last ? nB : cB + (size_t)(t + 2) * kstep;
;             const char* a3 = a2 + kstep; const char* b3 = b2 + kstep;
;             if constexpr (SP2) {
;             PG8_LDB(B0, 0, 0); PG8_LDB(B1, 0, 1); PG8_SCHED; PG8_LDA(At, 0, 0); PG8_STAGE(PG8_SA(1, 1), a1 + hstep, voffA);
;             PG8_WAIT_V(8); PG8_WAIT_L(0); PG8_BAR; PG8_MMA(0, 0, At, B0); PG8_MMA(0, 1, At, B1); PG8_BAR; PG8_SCHED;
;             PG8_LDA(At, 0, 1); PG8_STAGE(PG8_SB(0, 0), b2, voffB); PG8_STAGE(PG8_SB(0, 1), b2 + hstep, voffB); PG8_STAGE(PG8_SA(0, 0), a2, voffA);
;             PG8_WAIT_V(8); PG8_WAIT_L(0); PG8_BAR; PG8_MMA(1, 0, At, B0); PG8_MMA(1, 1, At, B1); PG8_BAR; PG8_SCHED;
.LBB0_374:
	ds_read_b128 v[128:131], v230
	ds_read_b128 v[132:135], v230 offset:1024
	ds_read_b128 v[158:161], v230 offset:2048
	ds_read_b128 v[162:165], v230 offset:3072
	ds_read_b128 v[166:169], v231
	ds_read_b128 v[170:173], v231 offset:1024
	ds_read_b128 v[174:177], v231 offset:2048
	ds_read_b128 v[178:181], v231 offset:3072
	s_add_u32 s52, s76, 0xfff80080
	s_addc_u32 s53, s77, -1
	s_cmp_eq_u32 vcc_hi, 28
	s_cselect_b32 s81, s11, s53
	s_cselect_b32 s80, s55, s52
	s_cselect_b32 s79, s51, vcc_lo
	s_cselect_b32 s78, s73, s75
	v_lshl_add_u64 v[214:215], s[76:77], 0, v[150:151]
	s_add_i32 m0, s28, 0xc000
	ds_read_b128 v[182:185], v232
	ds_read_b128 v[186:189], v232 offset:1024
	ds_read_b128 v[190:193], v232 offset:2048
	ds_read_b128 v[194:197], v232 offset:3072
	ds_read_b128 v[198:201], v232 offset:4096
	ds_read_b128 v[202:205], v232 offset:5120
	ds_read_b128 v[206:209], v232 offset:6144
	ds_read_b128 v[210:213], v232 offset:7168
	global_load_lds_dwordx4 v[214:215], off
	v_lshl_add_u64 v[214:215], s[76:77], 0, v[152:153]
	s_add_i32 m0, s28, 0xe000
	s_nop 0
	global_load_lds_dwordx4 v[214:215], off
	s_waitcnt vmcnt(8)
	s_waitcnt lgkmcnt(0)
	s_barrier
	s_setprio 1
	s_waitcnt lgkmcnt(0)
	v_mfma_f32_16x16x32_bf16 v[124:127], v[128:131], v[182:185], v[124:127]
	v_mfma_f32_16x16x32_bf16 v[120:123], v[158:161], v[182:185], v[120:123]
	v_mfma_f32_16x16x32_bf16 v[116:119], v[128:131], v[190:193], v[116:119]
	v_mfma_f32_16x16x32_bf16 v[112:115], v[158:161], v[190:193], v[112:115]
	v_mfma_f32_16x16x32_bf16 v[108:111], v[128:131], v[198:201], v[108:111]
	v_mfma_f32_16x16x32_bf16 v[104:107], v[158:161], v[198:201], v[104:107]
	v_mfma_f32_16x16x32_bf16 v[100:103], v[128:131], v[206:209], v[100:103]
	v_mfma_f32_16x16x32_bf16 v[96:99], v[158:161], v[206:209], v[96:99]
	v_mfma_f32_16x16x32_bf16 v[124:127], v[132:135], v[186:189], v[124:127]
	v_mfma_f32_16x16x32_bf16 v[120:123], v[162:165], v[186:189], v[120:123]
	v_mfma_f32_16x16x32_bf16 v[116:119], v[132:135], v[194:197], v[116:119]
	v_mfma_f32_16x16x32_bf16 v[112:115], v[162:165], v[194:197], v[112:115]
	v_mfma_f32_16x16x32_bf16 v[108:111], v[132:135], v[202:205], v[108:111]
	v_mfma_f32_16x16x32_bf16 v[104:107], v[162:165], v[202:205], v[104:107]
	v_mfma_f32_16x16x32_bf16 v[100:103], v[132:135], v[210:213], v[100:103]
	v_mfma_f32_16x16x32_bf16 v[96:99], v[162:165], v[210:213], v[96:99]
	s_setprio 0
	s_setprio 1
	v_mfma_f32_16x16x32_bf16 v[60:63], v[166:169], v[182:185], v[60:63]
	v_mfma_f32_16x16x32_bf16 v[56:59], v[174:177], v[182:185], v[56:59]
	v_mfma_f32_16x16x32_bf16 v[52:55], v[166:169], v[190:193], v[52:55]
	v_mfma_f32_16x16x32_bf16 v[48:51], v[174:177], v[190:193], v[48:51]
	v_mfma_f32_16x16x32_bf16 v[44:47], v[166:169], v[198:201], v[44:47]
	v_mfma_f32_16x16x32_bf16 v[40:43], v[174:177], v[198:201], v[40:43]
	v_mfma_f32_16x16x32_bf16 v[36:39], v[166:169], v[206:209], v[36:39]
	v_mfma_f32_16x16x32_bf16 v[32:35], v[174:177], v[206:209], v[32:35]
	v_mfma_f32_16x16x32_bf16 v[60:63], v[170:173], v[186:189], v[60:63]
	v_mfma_f32_16x16x32_bf16 v[56:59], v[178:181], v[186:189], v[56:59]
	v_mfma_f32_16x16x32_bf16 v[52:55], v[170:173], v[194:197], v[52:55]
	v_mfma_f32_16x16x32_bf16 v[48:51], v[178:181], v[194:197], v[48:51]
	v_mfma_f32_16x16x32_bf16 v[44:47], v[170:173], v[202:205], v[44:47]
	v_mfma_f32_16x16x32_bf16 v[40:43], v[178:181], v[202:205], v[40:43]
	s_barrier
	v_mfma_f32_16x16x32_bf16 v[36:39], v[170:173], v[210:213], v[36:39]
	v_mfma_f32_16x16x32_bf16 v[32:35], v[178:181], v[210:213], v[32:35]
	s_setprio 0
	s_add_i32 s52, s93, s3
	v_lshl_add_u64 v[214:215], s[78:79], 0, v[138:139]
	s_mov_b32 m0, s52
	ds_read_b128 v[182:185], v232 offset:16384
	ds_read_b128 v[186:189], v232 offset:17408
	ds_read_b128 v[190:193], v232 offset:18432
	ds_read_b128 v[194:197], v232 offset:19456
	ds_read_b128 v[198:201], v232 offset:20480
	ds_read_b128 v[202:205], v232 offset:21504
	ds_read_b128 v[206:209], v232 offset:22528
	ds_read_b128 v[210:213], v232 offset:23552
	global_load_lds_dwordx4 v[214:215], off
	s_add_i32 m0, s52, 0x2000
	s_add_u32 s52, s78, 0x80000
	v_lshl_add_u64 v[216:217], s[78:79], 0, v[142:143]
	s_addc_u32 s53, s79, 0
	s_add_i32 s56, s10, s3
	global_load_lds_dwordx4 v[216:217], off
	v_lshl_add_u64 v[218:219], s[52:53], 0, v[138:139]
	s_mov_b32 m0, s56
	v_lshl_add_u64 v[220:221], s[80:81], 0, v[140:141]
	global_load_lds_dwordx4 v[218:219], off
	v_lshl_add_u64 v[218:219], s[52:53], 0, v[142:143]
	s_add_i32 m0, s56, 0x2000
	s_nop 0
	global_load_lds_dwordx4 v[218:219], off
	v_lshl_add_u64 v[218:219], s[80:81], 0, v[136:137]
	s_mov_b32 m0, s28
	s_nop 0
	global_load_lds_dwordx4 v[218:219], off
	s_mov_b32 m0, s29
	s_nop 0
	global_load_lds_dwordx4 v[220:221], off
	s_waitcnt vmcnt(8)
	s_waitcnt lgkmcnt(0)
	s_barrier
; #define PG8_STAGE(bufoff, gbase, voff) do { _Pragma("unroll") for (int _i = 0; _i < 2; ++_i) \
;         __builtin_amdgcn_global_load_lds((const unsigned*)((const char*)(gbase) + (voff)[_i]), (PG8_LAS unsigned*)(lds + (bufoff) + ldsw + _i * 8192), 16, 0, 0); } while (0)
; #define PG8_LDA(dst, b, h) do { _Pragma("unroll") for (int m = 0; m < 4; ++m) _Pragma("unroll") for (int k = 0; k < 2; ++k) dst[m][k] = *(const PG8_LAS bf16x8*)(lds + PG8_SA(b, h) + aoff + m * 2048 + k * 1024); } while (0)
; #define PG8_LDB(dst, b, h) do { _Pragma("unroll") for (int n = 0; n < 2; ++n) _Pragma("unroll") for (int k = 0; k < 2; ++k) dst[n][k] = *(const PG8_LAS bf16x8*)(lds + PG8_SB(b, h) + boff + n * 2048 + k * 1024); } while (0)
; #define PG8_MMA(ai, bj, At, Bt) do { __builtin_amdgcn_s_setprio(1); _Pragma("unroll") for (int m = 0; m < 4; ++m) _Pragma("unroll") for (int n = 0; n < 2; ++n) _Pragma("unroll") for (int k = 0; k < 2; ++k) \
;         acc[ai][bj][m][n] = __builtin_amdgcn_mfma_f32_16x16x32_bf16(Bt[n][k], At[m][k], acc[ai][bj][m][n], 0, 0, 0); __builtin_amdgcn_s_setprio(0); } while (0)
; #define PG8_WAIT_V(n) asm volatile("s_waitcnt vmcnt(" #n ")" ::: "memory")
; #define PG8_WAIT_L(n) asm volatile("s_waitcnt lgkmcnt(" #n ")" ::: "memory")
; #define PG8_BAR __builtin_amdgcn_s_barrier()
; #define PG8_SCHED __builtin_amdgcn_sched_barrier(0)
; template <class Epi, class Sched, bool ALIGN_EPI = false, bool SP2 = false>
; __device__ __forceinline__ void gemm_phase(PG8_LAS unsigned char* lds, const Gemm g, const Sched& S, const Epi& E) {
;     ...
;             PG8_WAIT_V(8); PG8_WAIT_L(0); PG8_BAR; PG8_MMA(1, 0, At, B0); PG8_MMA(1, 1, At, B1); PG8_BAR; PG8_SCHED;
;             PG8_LDB(B0, 1, 0); PG8_LDB(B1, 1, 1); PG8_SCHED; PG8_LDA(At, 1, 0); PG8_STAGE(PG8_SA(0, 1), a2 + hstep, voffA);
;             PG8_WAIT_V(8); PG8_WAIT_L(0); PG8_BAR; PG8_MMA(0, 0, At, B0); PG8_MMA(0, 1, At, B1); PG8_BAR; PG8_SCHED;
	s_setprio 1
	s_waitcnt lgkmcnt(0)
	v_mfma_f32_16x16x32_bf16 v[92:95], v[128:131], v[182:185], v[92:95]
	v_mfma_f32_16x16x32_bf16 v[88:91], v[158:161], v[182:185], v[88:91]
	v_mfma_f32_16x16x32_bf16 v[84:87], v[128:131], v[190:193], v[84:87]
	v_mfma_f32_16x16x32_bf16 v[80:83], v[158:161], v[190:193], v[80:83]
	v_mfma_f32_16x16x32_bf16 v[76:79], v[128:131], v[198:201], v[76:79]
	v_mfma_f32_16x16x32_bf16 v[72:75], v[158:161], v[198:201], v[72:75]
	v_mfma_f32_16x16x32_bf16 v[68:71], v[128:131], v[206:209], v[68:71]
	v_mfma_f32_16x16x32_bf16 v[64:67], v[158:161], v[206:209], v[64:67]
	v_mfma_f32_16x16x32_bf16 v[92:95], v[132:135], v[186:189], v[92:95]
	v_mfma_f32_16x16x32_bf16 v[88:91], v[162:165], v[186:189], v[88:91]
	v_mfma_f32_16x16x32_bf16 v[84:87], v[132:135], v[194:197], v[84:87]
	v_mfma_f32_16x16x32_bf16 v[80:83], v[162:165], v[194:197], v[80:83]
	v_mfma_f32_16x16x32_bf16 v[76:79], v[132:135], v[202:205], v[76:79]
	v_mfma_f32_16x16x32_bf16 v[72:75], v[162:165], v[202:205], v[72:75]
	v_mfma_f32_16x16x32_bf16 v[68:71], v[132:135], v[210:213], v[68:71]
	v_mfma_f32_16x16x32_bf16 v[64:67], v[162:165], v[210:213], v[64:67]
	s_setprio 0
	s_setprio 1
	v_mfma_f32_16x16x32_bf16 v[28:31], v[166:169], v[182:185], v[28:31]
	v_mfma_f32_16x16x32_bf16 v[24:27], v[174:177], v[182:185], v[24:27]
	v_mfma_f32_16x16x32_bf16 v[20:23], v[166:169], v[190:193], v[20:23]
	v_mfma_f32_16x16x32_bf16 v[16:19], v[174:177], v[190:193], v[16:19]
	v_mfma_f32_16x16x32_bf16 v[12:15], v[166:169], v[198:201], v[12:15]
	v_mfma_f32_16x16x32_bf16 v[8:11], v[174:177], v[198:201], v[8:11]
	v_mfma_f32_16x16x32_bf16 v[4:7], v[166:169], v[206:209], v[4:7]
	v_mfma_f32_16x16x32_bf16 v[0:3], v[174:177], v[206:209], v[0:3]
	v_mfma_f32_16x16x32_bf16 v[28:31], v[170:173], v[186:189], v[28:31]
	v_mfma_f32_16x16x32_bf16 v[24:27], v[178:181], v[186:189], v[24:27]
	v_mfma_f32_16x16x32_bf16 v[20:23], v[170:173], v[194:197], v[20:23]
	v_mfma_f32_16x16x32_bf16 v[16:19], v[178:181], v[194:197], v[16:19]
	v_mfma_f32_16x16x32_bf16 v[12:15], v[170:173], v[202:205], v[12:15]
	v_mfma_f32_16x16x32_bf16 v[8:11], v[178:181], v[202:205], v[8:11]
	s_barrier
	v_mfma_f32_16x16x32_bf16 v[4:7], v[170:173], v[210:213], v[4:7]
	v_mfma_f32_16x16x32_bf16 v[0:3], v[178:181], v[210:213], v[0:3]
	s_setprio 0
	s_add_i32 s56, 0, 0x18000
	s_add_i32 s57, 0, 0x1c000
	v_add_u32_e32 v162, s56, v228
	v_add_u32_e32 v178, s57, v228
	ds_read_b128 v[128:131], v162
	ds_read_b128 v[132:135], v162 offset:1024
	ds_read_b128 v[158:161], v162 offset:2048
	ds_read_b128 v[162:165], v162 offset:3072
	ds_read_b128 v[166:169], v178
	ds_read_b128 v[170:173], v178 offset:1024
	ds_read_b128 v[174:177], v178 offset:2048
	ds_read_b128 v[178:181], v178 offset:3072
	s_add_u32 s52, s80, 0x80000
	s_addc_u32 s53, s81, 0
	s_mov_b32 m0, s33
	v_lshl_add_u64 v[234:235], s[52:53], 0, v[136:137]
	ds_read_b128 v[182:185], v232 offset:32768
	ds_read_b128 v[186:189], v232 offset:33792
	ds_read_b128 v[190:193], v232 offset:34816
	ds_read_b128 v[194:197], v232 offset:35840
	ds_read_b128 v[198:201], v232 offset:36864
	ds_read_b128 v[202:205], v232 offset:37888
	ds_read_b128 v[206:209], v232 offset:38912
	ds_read_b128 v[210:213], v232 offset:39936
	global_load_lds_dwordx4 v[234:235], off
	v_lshl_add_u64 v[234:235], s[52:53], 0, v[140:141]
	s_mov_b32 m0, s38
	s_nop 0
	global_load_lds_dwordx4 v[234:235], off
	s_waitcnt vmcnt(8)
	s_waitcnt lgkmcnt(0)
	s_barrier
	s_setprio 1
	s_waitcnt lgkmcnt(0)
	v_mfma_f32_16x16x32_bf16 v[124:127], v[128:131], v[182:185], v[124:127]
	v_mfma_f32_16x16x32_bf16 v[120:123], v[158:161], v[182:185], v[120:123]
	v_mfma_f32_16x16x32_bf16 v[116:119], v[128:131], v[190:193], v[116:119]
	v_mfma_f32_16x16x32_bf16 v[112:115], v[158:161], v[190:193], v[112:115]
	v_mfma_f32_16x16x32_bf16 v[108:111], v[128:131], v[198:201], v[108:111]
	v_mfma_f32_16x16x32_bf16 v[104:107], v[158:161], v[198:201], v[104:107]
	v_mfma_f32_16x16x32_bf16 v[100:103], v[128:131], v[206:209], v[100:103]
	v_mfma_f32_16x16x32_bf16 v[96:99], v[158:161], v[206:209], v[96:99]
	v_mfma_f32_16x16x32_bf16 v[124:127], v[132:135], v[186:189], v[124:127]
	v_mfma_f32_16x16x32_bf16 v[120:123], v[162:165], v[186:189], v[120:123]
	v_mfma_f32_16x16x32_bf16 v[116:119], v[132:135], v[194:197], v[116:119]
	v_mfma_f32_16x16x32_bf16 v[112:115], v[162:165], v[194:197], v[112:115]
	v_mfma_f32_16x16x32_bf16 v[108:111], v[132:135], v[202:205], v[108:111]
	v_mfma_f32_16x16x32_bf16 v[104:107], v[162:165], v[202:205], v[104:107]
	v_mfma_f32_16x16x32_bf16 v[100:103], v[132:135], v[210:213], v[100:103]
	v_mfma_f32_16x16x32_bf16 v[96:99], v[162:165], v[210:213], v[96:99]
	s_setprio 0
	s_setprio 1
	v_mfma_f32_16x16x32_bf16 v[60:63], v[166:169], v[182:185], v[60:63]
	v_mfma_f32_16x16x32_bf16 v[56:59], v[174:177], v[182:185], v[56:59]
	v_mfma_f32_16x16x32_bf16 v[52:55], v[166:169], v[190:193], v[52:55]
	v_mfma_f32_16x16x32_bf16 v[48:51], v[174:177], v[190:193], v[48:51]
	v_mfma_f32_16x16x32_bf16 v[44:47], v[166:169], v[198:201], v[44:47]
	v_mfma_f32_16x16x32_bf16 v[40:43], v[174:177], v[198:201], v[40:43]
	v_mfma_f32_16x16x32_bf16 v[36:39], v[166:169], v[206:209], v[36:39]
	v_mfma_f32_16x16x32_bf16 v[32:35], v[174:177], v[206:209], v[32:35]
	v_mfma_f32_16x16x32_bf16 v[60:63], v[170:173], v[186:189], v[60:63]
	v_mfma_f32_16x16x32_bf16 v[56:59], v[178:181], v[186:189], v[56:59]
	v_mfma_f32_16x16x32_bf16 v[52:55], v[170:173], v[194:197], v[52:55]
	v_mfma_f32_16x16x32_bf16 v[48:51], v[178:181], v[194:197], v[48:51]
	v_mfma_f32_16x16x32_bf16 v[44:47], v[170:173], v[202:205], v[44:47]
	v_mfma_f32_16x16x32_bf16 v[40:43], v[178:181], v[202:205], v[40:43]
	s_barrier
; #define PG8_STAGE(bufoff, gbase, voff) do { _Pragma("unroll") for (int _i = 0; _i < 2; ++_i) \
;         __builtin_amdgcn_global_load_lds((const unsigned*)((const char*)(gbase) + (voff)[_i]), (PG8_LAS unsigned*)(lds + (bufoff) + ldsw + _i * 8192), 16, 0, 0); } while (0)
; #define PG8_LDA(dst, b, h) do { _Pragma("unroll") for (int m = 0; m < 4; ++m) _Pragma("unroll") for (int k = 0; k < 2; ++k) dst[m][k] = *(const PG8_LAS bf16x8*)(lds + PG8_SA(b, h) + aoff + m * 2048 + k * 1024); } while (0)
; #define PG8_MMA(ai, bj, At, Bt) do { __builtin_amdgcn_s_setprio(1); _Pragma("unroll") for (int m = 0; m < 4; ++m) _Pragma("unroll") for (int n = 0; n < 2; ++n) _Pragma("unroll") for (int k = 0; k < 2; ++k) \
;         acc[ai][bj][m][n] = __builtin_amdgcn_mfma_f32_16x16x32_bf16(Bt[n][k], At[m][k], acc[ai][bj][m][n], 0, 0, 0); __builtin_amdgcn_s_setprio(0); } while (0)
; #define PG8_WAIT_V(n) asm volatile("s_waitcnt vmcnt(" #n ")" ::: "memory")
; #define PG8_WAIT_L(n) asm volatile("s_waitcnt lgkmcnt(" #n ")" ::: "memory")
; #define PG8_BAR __builtin_amdgcn_s_barrier()
; #define PG8_SCHED __builtin_amdgcn_sched_barrier(0)
; template <class Epi, class Sched, bool ALIGN_EPI = false, bool SP2 = false>
; __device__ __forceinline__ void gemm_phase(PG8_LAS unsigned char* lds, const Gemm g, const Sched& S, const Epi& E) {
;     ...
;             PG8_WAIT_V(8); PG8_WAIT_L(0); PG8_BAR; PG8_MMA(0, 0, At, B0); PG8_MMA(0, 1, At, B1); PG8_BAR; PG8_SCHED;
;             PG8_LDA(At, 1, 1); PG8_STAGE(PG8_SB(1, 0), b3, voffB); PG8_STAGE(PG8_SB(1, 1), b3 + hstep, voffB); PG8_STAGE(PG8_SA(1, 0), a3, voffA);
;             PG8_WAIT_V(8); PG8_WAIT_L(0); PG8_BAR; PG8_MMA(1, 0, At, B0); PG8_MMA(1, 1, At, B1); PG8_BAR; PG8_SCHED;
;     ...
;         if constexpr (ALIGN_EPI) { if (wr == 0) PG8_BAR; }
	v_mfma_f32_16x16x32_bf16 v[36:39], v[170:173], v[210:213], v[36:39]
	v_mfma_f32_16x16x32_bf16 v[32:35], v[178:181], v[210:213], v[32:35]
	s_setprio 0
	s_add_i32 s52, s56, s3
	v_lshl_add_u64 v[214:215], v[214:215], 0, s[14:15]
	s_mov_b32 m0, s52
	ds_read_b128 v[182:185], v232 offset:49152
	ds_read_b128 v[186:189], v232 offset:50176
	ds_read_b128 v[190:193], v232 offset:51200
	ds_read_b128 v[194:197], v232 offset:52224
	ds_read_b128 v[198:201], v232 offset:53248
	ds_read_b128 v[202:205], v232 offset:54272
	ds_read_b128 v[206:209], v232 offset:55296
	ds_read_b128 v[210:213], v232 offset:56320
	global_load_lds_dwordx4 v[214:215], off
	s_add_i32 m0, s52, 0x2000
	s_add_u32 s52, s78, 0x80080
	v_lshl_add_u64 v[214:215], v[216:217], 0, s[14:15]
	s_addc_u32 s53, s79, 0
	s_add_i32 s56, s57, s3
	global_load_lds_dwordx4 v[214:215], off
	v_lshl_add_u64 v[214:215], s[52:53], 0, v[138:139]
	s_mov_b32 m0, s56
	s_nop 0
	global_load_lds_dwordx4 v[214:215], off
	v_lshl_add_u64 v[214:215], s[52:53], 0, v[142:143]
	s_add_i32 m0, s56, 0x2000
	s_nop 0
	global_load_lds_dwordx4 v[214:215], off
	v_lshl_add_u64 v[214:215], v[218:219], 0, s[14:15]
	s_mov_b32 m0, s88
	s_nop 0
	global_load_lds_dwordx4 v[214:215], off
	v_lshl_add_u64 v[214:215], v[220:221], 0, s[14:15]
	s_mov_b32 m0, s89
	s_nop 0
	global_load_lds_dwordx4 v[214:215], off
	s_waitcnt vmcnt(8)
	s_waitcnt lgkmcnt(0)
	s_barrier
	s_setprio 1
	s_waitcnt lgkmcnt(0)
	v_mfma_f32_16x16x32_bf16 v[92:95], v[128:131], v[182:185], v[92:95]
	v_mfma_f32_16x16x32_bf16 v[88:91], v[158:161], v[182:185], v[88:91]
	v_mfma_f32_16x16x32_bf16 v[84:87], v[128:131], v[190:193], v[84:87]
	v_mfma_f32_16x16x32_bf16 v[80:83], v[158:161], v[190:193], v[80:83]
	v_mfma_f32_16x16x32_bf16 v[76:79], v[128:131], v[198:201], v[76:79]
	v_mfma_f32_16x16x32_bf16 v[72:75], v[158:161], v[198:201], v[72:75]
	v_mfma_f32_16x16x32_bf16 v[68:71], v[128:131], v[206:209], v[68:71]
	v_mfma_f32_16x16x32_bf16 v[64:67], v[158:161], v[206:209], v[64:67]
	v_mfma_f32_16x16x32_bf16 v[92:95], v[132:135], v[186:189], v[92:95]
	v_mfma_f32_16x16x32_bf16 v[88:91], v[162:165], v[186:189], v[88:91]
	v_mfma_f32_16x16x32_bf16 v[84:87], v[132:135], v[194:197], v[84:87]
	v_mfma_f32_16x16x32_bf16 v[80:83], v[162:165], v[194:197], v[80:83]
	v_mfma_f32_16x16x32_bf16 v[76:79], v[132:135], v[202:205], v[76:79]
	v_mfma_f32_16x16x32_bf16 v[72:75], v[162:165], v[202:205], v[72:75]
	v_mfma_f32_16x16x32_bf16 v[68:71], v[132:135], v[210:213], v[68:71]
	v_mfma_f32_16x16x32_bf16 v[64:67], v[162:165], v[210:213], v[64:67]
	s_setprio 0
	s_setprio 1
	v_mfma_f32_16x16x32_bf16 v[28:31], v[166:169], v[182:185], v[28:31]
	v_mfma_f32_16x16x32_bf16 v[24:27], v[174:177], v[182:185], v[24:27]
	v_mfma_f32_16x16x32_bf16 v[20:23], v[166:169], v[190:193], v[20:23]
	v_mfma_f32_16x16x32_bf16 v[16:19], v[174:177], v[190:193], v[16:19]
	v_mfma_f32_16x16x32_bf16 v[12:15], v[166:169], v[198:201], v[12:15]
	v_mfma_f32_16x16x32_bf16 v[8:11], v[174:177], v[198:201], v[8:11]
	v_mfma_f32_16x16x32_bf16 v[4:7], v[166:169], v[206:209], v[4:7]
	v_mfma_f32_16x16x32_bf16 v[0:3], v[174:177], v[206:209], v[0:3]
	v_mfma_f32_16x16x32_bf16 v[28:31], v[170:173], v[186:189], v[28:31]
	v_mfma_f32_16x16x32_bf16 v[24:27], v[178:181], v[186:189], v[24:27]
	v_mfma_f32_16x16x32_bf16 v[20:23], v[170:173], v[194:197], v[20:23]
	v_mfma_f32_16x16x32_bf16 v[16:19], v[178:181], v[194:197], v[16:19]
	v_mfma_f32_16x16x32_bf16 v[12:15], v[170:173], v[202:205], v[12:15]
	v_mfma_f32_16x16x32_bf16 v[8:11], v[178:181], v[202:205], v[8:11]
	s_barrier
	v_mfma_f32_16x16x32_bf16 v[4:7], v[170:173], v[210:213], v[4:7]
	v_mfma_f32_16x16x32_bf16 v[0:3], v[178:181], v[210:213], v[0:3]
	s_setprio 0
	s_add_i32 vcc_hi, vcc_hi, 2
	s_add_u32 s76, s76, 0x100
	s_addc_u32 s77, s77, 0
	s_add_u32 s75, s75, 0x100
	s_addc_u32 vcc_lo, vcc_lo, 0
	s_cmp_gt_u32 vcc_hi, 29
	s_cbranch_scc0 .LBB0_374
	s_and_b64 vcc, exec, s[48:49]
	s_cbranch_vccz .LBB0_377
	s_barrier

; #define PG8_STAGE(bufoff, gbase, voff) do { _Pragma("unroll") for (int _i = 0; _i < 2; ++_i) \
;         __builtin_amdgcn_global_load_lds((const unsigned*)((const char*)(gbase) + (voff)[_i]), (PG8_LAS unsigned*)(lds + (bufoff) + ldsw + _i * 8192), 16, 0, 0); } while (0)
; #define PG8_LDA(dst, b, h) do { _Pragma("unroll") for (int m = 0; m < 4; ++m) _Pragma("unroll") for (int k = 0; k < 2; ++k) dst[m][k] = *(const PG8_LAS bf16x8*)(lds + PG8_SA(b, h) + aoff + m * 2048 + k * 1024); } while (0)
; #define PG8_LDB(dst, b, h) do { _Pragma("unroll") for (int n = 0; n < 2; ++n) _Pragma("unroll") for (int k = 0; k < 2; ++k) dst[n][k] = *(const PG8_LAS bf16x8*)(lds + PG8_SB(b, h) + boff + n * 2048 + k * 1024); } while (0)
; #define PG8_MMA(ai, bj, At, Bt) do { __builtin_amdgcn_s_setprio(1); _Pragma("unroll") for (int m = 0; m < 4; ++m) _Pragma("unroll") for (int n = 0; n < 2; ++n) _Pragma("unroll") for (int k = 0; k < 2; ++k) \
;         acc[ai][bj][m][n] = __builtin_amdgcn_mfma_f32_16x16x32_bf16(Bt[n][k], At[m][k], acc[ai][bj][m][n], 0, 0, 0); __builtin_amdgcn_s_setprio(0); } while (0)
; #define PG8_WAIT_V(n) asm volatile("s_waitcnt vmcnt(" #n ")" ::: "memory")
; #define PG8_WAIT_L(n) asm volatile("s_waitcnt lgkmcnt(" #n ")" ::: "memory")
; #define PG8_BAR __builtin_amdgcn_s_barrier()
; #define PG8_SCHED __builtin_amdgcn_sched_barrier(0)
; template <class Epi, class Sched, bool ALIGN_EPI = false, bool SP2 = false>
; __device__ __forceinline__ void gemm_phase(PG8_LAS unsigned char* lds, const Gemm g, const Sched& S, const Epi& E) {
;     ...
;         for (int t = 0; t < nt; t += 2) {
;             const bool last = (t == nt - 2);
;             const char* a1 = cA + (size_t)(t + 1) * kstep;
;             const char* a2 = last ? nA : cA + (size_t)(t + 2) * kstep; const char* b2 = last ? nB : cB + (size_t)(t + 2) * kstep;
;             const char* a3 = a2 + kstep; const char* b3 = b2 + kstep;
;             if constexpr (SP2) {
;             PG8_LDB(B0, 0, 0); PG8_LDB(B1, 0, 1); PG8_SCHED; PG8_LDA(At, 0, 0); PG8_STAGE(PG8_SA(1, 1), a1 + hstep, voffA);
;             PG8_WAIT_V(8); PG8_WAIT_L(0); PG8_BAR; PG8_MMA(0, 0, At, B0); PG8_MMA(0, 1, At, B1); PG8_BAR; PG8_SCHED;
.LBB0_410:
	ds_read_b128 v[166:169], v145
	ds_read_b128 v[170:173], v145 offset:1024
	ds_read_b128 v[174:177], v145 offset:2048
	ds_read_b128 v[178:181], v145 offset:3072
	ds_read_b128 v[182:185], v149
	ds_read_b128 v[186:189], v149 offset:1024
	ds_read_b128 v[190:193], v149 offset:2048
	ds_read_b128 v[194:197], v149 offset:3072
	s_add_u32 s52, s74, 0xfff80080
	s_addc_u32 s53, s75, -1
	s_cmp_eq_u32 s51, 4
	s_cselect_b32 s79, s55, s53
	s_cselect_b32 s78, s54, s52
	s_cselect_b32 s77, s69, s49
	s_cselect_b32 s76, s68, s37
	s_mov_b32 m0, s80
	v_lshl_add_u64 v[230:231], s[74:75], 0, v[160:161]
	ds_read_b128 v[198:201], v164
	ds_read_b128 v[202:205], v164 offset:1024
	ds_read_b128 v[206:209], v164 offset:2048
	ds_read_b128 v[210:213], v164 offset:3072
	ds_read_b128 v[214:217], v164 offset:4096
	ds_read_b128 v[218:221], v164 offset:5120
	ds_read_b128 v[222:225], v164 offset:6144
	ds_read_b128 v[226:229], v164 offset:7168
	global_load_lds_dwordx4 v[230:231], off
	v_lshl_add_u64 v[230:231], s[74:75], 0, v[162:163]
	s_mov_b32 m0, s81
	s_nop 0
	global_load_lds_dwordx4 v[230:231], off
	s_waitcnt vmcnt(8)
	s_waitcnt lgkmcnt(0)
	s_barrier
	s_setprio 1
	s_waitcnt lgkmcnt(0)
	v_mfma_f32_16x16x32_bf16 v[124:127], v[166:169], v[198:201], v[124:127]
	v_mfma_f32_16x16x32_bf16 v[120:123], v[174:177], v[198:201], v[120:123]
	v_mfma_f32_16x16x32_bf16 v[116:119], v[166:169], v[206:209], v[116:119]
	v_mfma_f32_16x16x32_bf16 v[108:111], v[174:177], v[206:209], v[108:111]
	v_mfma_f32_16x16x32_bf16 v[100:103], v[166:169], v[214:217], v[100:103]
	v_mfma_f32_16x16x32_bf16 v[92:95], v[174:177], v[214:217], v[92:95]
	v_mfma_f32_16x16x32_bf16 v[84:87], v[166:169], v[222:225], v[84:87]
	v_mfma_f32_16x16x32_bf16 v[76:79], v[174:177], v[222:225], v[76:79]
	v_mfma_f32_16x16x32_bf16 v[124:127], v[170:173], v[202:205], v[124:127]
	v_mfma_f32_16x16x32_bf16 v[120:123], v[178:181], v[202:205], v[120:123]
	v_mfma_f32_16x16x32_bf16 v[116:119], v[170:173], v[210:213], v[116:119]
	v_mfma_f32_16x16x32_bf16 v[108:111], v[178:181], v[210:213], v[108:111]
	v_mfma_f32_16x16x32_bf16 v[100:103], v[170:173], v[218:221], v[100:103]
	v_mfma_f32_16x16x32_bf16 v[92:95], v[178:181], v[218:221], v[92:95]
	v_mfma_f32_16x16x32_bf16 v[84:87], v[170:173], v[226:229], v[84:87]
	v_mfma_f32_16x16x32_bf16 v[76:79], v[178:181], v[226:229], v[76:79]
	s_setprio 0
	s_setprio 1
	v_mfma_f32_16x16x32_bf16 v[112:115], v[182:185], v[198:201], v[112:115]
	v_mfma_f32_16x16x32_bf16 v[104:107], v[190:193], v[198:201], v[104:107]
	v_mfma_f32_16x16x32_bf16 v[96:99], v[182:185], v[206:209], v[96:99]
	v_mfma_f32_16x16x32_bf16 v[88:91], v[190:193], v[206:209], v[88:91]
	v_mfma_f32_16x16x32_bf16 v[80:83], v[182:185], v[214:217], v[80:83]
	v_mfma_f32_16x16x32_bf16 v[72:75], v[190:193], v[214:217], v[72:75]
	v_mfma_f32_16x16x32_bf16 v[68:71], v[182:185], v[222:225], v[68:71]
	v_mfma_f32_16x16x32_bf16 v[64:67], v[190:193], v[222:225], v[64:67]
	v_mfma_f32_16x16x32_bf16 v[112:115], v[186:189], v[202:205], v[112:115]
	v_mfma_f32_16x16x32_bf16 v[104:107], v[194:197], v[202:205], v[104:107]
	v_mfma_f32_16x16x32_bf16 v[96:99], v[186:189], v[210:213], v[96:99]
	v_mfma_f32_16x16x32_bf16 v[88:91], v[194:197], v[210:213], v[88:91]
	v_mfma_f32_16x16x32_bf16 v[80:83], v[186:189], v[218:221], v[80:83]
	v_mfma_f32_16x16x32_bf16 v[72:75], v[194:197], v[218:221], v[72:75]
	s_barrier
	v_mfma_f32_16x16x32_bf16 v[68:71], v[186:189], v[226:229], v[68:71]
	v_mfma_f32_16x16x32_bf16 v[64:67], v[194:197], v[226:229], v[64:67]
	s_setprio 0
	s_mov_b32 m0, s84
	v_lshl_add_u64 v[230:231], s[76:77], 0, v[138:139]
	s_add_u32 s52, s76, 0x80000
	ds_read_b128 v[198:201], v164 offset:16384
	ds_read_b128 v[202:205], v164 offset:17408
	ds_read_b128 v[206:209], v164 offset:18432
	ds_read_b128 v[210:213], v164 offset:19456
	ds_read_b128 v[214:217], v164 offset:20480
	ds_read_b128 v[218:221], v164 offset:21504
	ds_read_b128 v[222:225], v164 offset:22528
	ds_read_b128 v[226:229], v164 offset:23552
	global_load_lds_dwordx4 v[230:231], off
	v_lshl_add_u64 v[232:233], s[76:77], 0, v[142:143]
	s_mov_b32 m0, s85
	s_addc_u32 s53, s77, 0
	global_load_lds_dwordx4 v[232:233], off
	v_lshl_add_u64 v[234:235], s[52:53], 0, v[138:139]
	s_mov_b32 m0, s86
	v_lshl_add_u64 v[236:237], s[78:79], 0, v[140:141]
	global_load_lds_dwordx4 v[234:235], off
	v_lshl_add_u64 v[234:235], s[52:53], 0, v[142:143]
	s_mov_b32 m0, s87
	s_nop 0
	global_load_lds_dwordx4 v[234:235], off
	v_lshl_add_u64 v[234:235], s[78:79], 0, v[136:137]
	s_mov_b32 m0, s10
	s_nop 0
	global_load_lds_dwordx4 v[234:235], off
	s_mov_b32 m0, s11
	s_nop 0
	global_load_lds_dwordx4 v[236:237], off
	s_waitcnt vmcnt(8)
	s_waitcnt lgkmcnt(0)
	s_barrier
; #define PG8_STAGE(bufoff, gbase, voff) do { _Pragma("unroll") for (int _i = 0; _i < 2; ++_i) \
;         __builtin_amdgcn_global_load_lds((const unsigned*)((const char*)(gbase) + (voff)[_i]), (PG8_LAS unsigned*)(lds + (bufoff) + ldsw + _i * 8192), 16, 0, 0); } while (0)
; #define PG8_LDA(dst, b, h) do { _Pragma("unroll") for (int m = 0; m < 4; ++m) _Pragma("unroll") for (int k = 0; k < 2; ++k) dst[m][k] = *(const PG8_LAS bf16x8*)(lds + PG8_SA(b, h) + aoff + m * 2048 + k * 1024); } while (0)
; #define PG8_LDB(dst, b, h) do { _Pragma("unroll") for (int n = 0; n < 2; ++n) _Pragma("unroll") for (int k = 0; k < 2; ++k) dst[n][k] = *(const PG8_LAS bf16x8*)(lds + PG8_SB(b, h) + boff + n * 2048 + k * 1024); } while (0)
; #define PG8_MMA(ai, bj, At, Bt) do { __builtin_amdgcn_s_setprio(1); _Pragma("unroll") for (int m = 0; m < 4; ++m) _Pragma("unroll") for (int n = 0; n < 2; ++n) _Pragma("unroll") for (int k = 0; k < 2; ++k) \
;         acc[ai][bj][m][n] = __builtin_amdgcn_mfma_f32_16x16x32_bf16(Bt[n][k], At[m][k], acc[ai][bj][m][n], 0, 0, 0); __builtin_amdgcn_s_setprio(0); } while (0)
; #define PG8_WAIT_V(n) asm volatile("s_waitcnt vmcnt(" #n ")" ::: "memory")
; #define PG8_WAIT_L(n) asm volatile("s_waitcnt lgkmcnt(" #n ")" ::: "memory")
; #define PG8_BAR __builtin_amdgcn_s_barrier()
; #define PG8_SCHED __builtin_amdgcn_sched_barrier(0)
; template <class Epi, class Sched, bool ALIGN_EPI = false, bool SP2 = false>
; __device__ __forceinline__ void gemm_phase(PG8_LAS unsigned char* lds, const Gemm g, const Sched& S, const Epi& E) {
;     ...
;             PG8_WAIT_V(8); PG8_WAIT_L(0); PG8_BAR; PG8_MMA(1, 0, At, B0); PG8_MMA(1, 1, At, B1); PG8_BAR; PG8_SCHED;
;             PG8_LDB(B0, 1, 0); PG8_LDB(B1, 1, 1); PG8_SCHED; PG8_LDA(At, 1, 0); PG8_STAGE(PG8_SA(0, 1), a2 + hstep, voffA);
;             PG8_WAIT_V(8); PG8_WAIT_L(0); PG8_BAR; PG8_MMA(0, 0, At, B0); PG8_MMA(0, 1, At, B1); PG8_BAR; PG8_SCHED;
	s_setprio 1
	s_waitcnt lgkmcnt(0)
	v_mfma_f32_16x16x32_bf16 v[60:63], v[166:169], v[198:201], v[60:63]
	v_mfma_f32_16x16x32_bf16 v[56:59], v[174:177], v[198:201], v[56:59]
	v_mfma_f32_16x16x32_bf16 v[52:55], v[166:169], v[206:209], v[52:55]
	v_mfma_f32_16x16x32_bf16 v[44:47], v[174:177], v[206:209], v[44:47]
	v_mfma_f32_16x16x32_bf16 v[36:39], v[166:169], v[214:217], v[36:39]
	v_mfma_f32_16x16x32_bf16 v[28:31], v[174:177], v[214:217], v[28:31]
	v_mfma_f32_16x16x32_bf16 v[20:23], v[166:169], v[222:225], v[20:23]
	v_mfma_f32_16x16x32_bf16 v[12:15], v[174:177], v[222:225], v[12:15]
	v_mfma_f32_16x16x32_bf16 v[60:63], v[170:173], v[202:205], v[60:63]
	v_mfma_f32_16x16x32_bf16 v[56:59], v[178:181], v[202:205], v[56:59]
	v_mfma_f32_16x16x32_bf16 v[52:55], v[170:173], v[210:213], v[52:55]
	v_mfma_f32_16x16x32_bf16 v[44:47], v[178:181], v[210:213], v[44:47]
	v_mfma_f32_16x16x32_bf16 v[36:39], v[170:173], v[218:221], v[36:39]
	v_mfma_f32_16x16x32_bf16 v[28:31], v[178:181], v[218:221], v[28:31]
	v_mfma_f32_16x16x32_bf16 v[20:23], v[170:173], v[226:229], v[20:23]
	v_mfma_f32_16x16x32_bf16 v[12:15], v[178:181], v[226:229], v[12:15]
	s_setprio 0
	s_setprio 1
	v_mfma_f32_16x16x32_bf16 v[48:51], v[182:185], v[198:201], v[48:51]
	v_mfma_f32_16x16x32_bf16 v[40:43], v[190:193], v[198:201], v[40:43]
	v_mfma_f32_16x16x32_bf16 v[32:35], v[182:185], v[206:209], v[32:35]
	v_mfma_f32_16x16x32_bf16 v[24:27], v[190:193], v[206:209], v[24:27]
	v_mfma_f32_16x16x32_bf16 v[16:19], v[182:185], v[214:217], v[16:19]
	v_mfma_f32_16x16x32_bf16 v[8:11], v[190:193], v[214:217], v[8:11]
	v_mfma_f32_16x16x32_bf16 v[4:7], v[182:185], v[222:225], v[4:7]
	v_mfma_f32_16x16x32_bf16 v[0:3], v[190:193], v[222:225], v[0:3]
	v_mfma_f32_16x16x32_bf16 v[48:51], v[186:189], v[202:205], v[48:51]
	v_mfma_f32_16x16x32_bf16 v[40:43], v[194:197], v[202:205], v[40:43]
	v_mfma_f32_16x16x32_bf16 v[32:35], v[186:189], v[210:213], v[32:35]
	v_mfma_f32_16x16x32_bf16 v[24:27], v[194:197], v[210:213], v[24:27]
	v_mfma_f32_16x16x32_bf16 v[16:19], v[186:189], v[218:221], v[16:19]
	v_mfma_f32_16x16x32_bf16 v[8:11], v[194:197], v[218:221], v[8:11]
	s_barrier
	v_mfma_f32_16x16x32_bf16 v[4:7], v[186:189], v[226:229], v[4:7]
	v_mfma_f32_16x16x32_bf16 v[0:3], v[194:197], v[226:229], v[0:3]
	s_setprio 0
	ds_read_b128 v[166:169], v148
	ds_read_b128 v[170:173], v148 offset:1024
	ds_read_b128 v[174:177], v148 offset:2048
	ds_read_b128 v[178:181], v148 offset:3072
	ds_read_b128 v[182:185], v165
	ds_read_b128 v[186:189], v165 offset:1024
	ds_read_b128 v[190:193], v165 offset:2048
	ds_read_b128 v[194:197], v165 offset:3072
	s_add_u32 s52, s78, 0x80000
	s_addc_u32 s53, s79, 0
	s_mov_b32 m0, s28
	v_lshl_add_u64 v[238:239], s[52:53], 0, v[136:137]
	ds_read_b128 v[198:201], v164 offset:32768
	ds_read_b128 v[202:205], v164 offset:33792
	ds_read_b128 v[206:209], v164 offset:34816
	ds_read_b128 v[210:213], v164 offset:35840
	ds_read_b128 v[214:217], v164 offset:36864
	ds_read_b128 v[218:221], v164 offset:37888
	ds_read_b128 v[222:225], v164 offset:38912
	ds_read_b128 v[226:229], v164 offset:39936
	global_load_lds_dwordx4 v[238:239], off
	v_lshl_add_u64 v[238:239], s[52:53], 0, v[140:141]
	s_mov_b32 m0, s29
	s_nop 0
	global_load_lds_dwordx4 v[238:239], off
	s_waitcnt vmcnt(8)
	s_waitcnt lgkmcnt(0)
	s_barrier
	s_setprio 1
	s_waitcnt lgkmcnt(0)
	v_mfma_f32_16x16x32_bf16 v[124:127], v[166:169], v[198:201], v[124:127]
	v_mfma_f32_16x16x32_bf16 v[120:123], v[174:177], v[198:201], v[120:123]
	v_mfma_f32_16x16x32_bf16 v[116:119], v[166:169], v[206:209], v[116:119]
	v_mfma_f32_16x16x32_bf16 v[108:111], v[174:177], v[206:209], v[108:111]
	v_mfma_f32_16x16x32_bf16 v[100:103], v[166:169], v[214:217], v[100:103]
	v_mfma_f32_16x16x32_bf16 v[92:95], v[174:177], v[214:217], v[92:95]
	v_mfma_f32_16x16x32_bf16 v[84:87], v[166:169], v[222:225], v[84:87]
	v_mfma_f32_16x16x32_bf16 v[76:79], v[174:177], v[222:225], v[76:79]
	v_mfma_f32_16x16x32_bf16 v[124:127], v[170:173], v[202:205], v[124:127]
	v_mfma_f32_16x16x32_bf16 v[120:123], v[178:181], v[202:205], v[120:123]
	v_mfma_f32_16x16x32_bf16 v[116:119], v[170:173], v[210:213], v[116:119]
	v_mfma_f32_16x16x32_bf16 v[108:111], v[178:181], v[210:213], v[108:111]
	v_mfma_f32_16x16x32_bf16 v[100:103], v[170:173], v[218:221], v[100:103]
	v_mfma_f32_16x16x32_bf16 v[92:95], v[178:181], v[218:221], v[92:95]
	v_mfma_f32_16x16x32_bf16 v[84:87], v[170:173], v[226:229], v[84:87]
	v_mfma_f32_16x16x32_bf16 v[76:79], v[178:181], v[226:229], v[76:79]
	s_setprio 0
	s_setprio 1
	v_mfma_f32_16x16x32_bf16 v[112:115], v[182:185], v[198:201], v[112:115]
	v_mfma_f32_16x16x32_bf16 v[104:107], v[190:193], v[198:201], v[104:107]
	v_mfma_f32_16x16x32_bf16 v[96:99], v[182:185], v[206:209], v[96:99]
	v_mfma_f32_16x16x32_bf16 v[88:91], v[190:193], v[206:209], v[88:91]
	v_mfma_f32_16x16x32_bf16 v[80:83], v[182:185], v[214:217], v[80:83]
	v_mfma_f32_16x16x32_bf16 v[72:75], v[190:193], v[214:217], v[72:75]
	v_mfma_f32_16x16x32_bf16 v[68:71], v[182:185], v[222:225], v[68:71]
	v_mfma_f32_16x16x32_bf16 v[64:67], v[190:193], v[222:225], v[64:67]
	v_mfma_f32_16x16x32_bf16 v[112:115], v[186:189], v[202:205], v[112:115]
	v_mfma_f32_16x16x32_bf16 v[104:107], v[194:197], v[202:205], v[104:107]
	v_mfma_f32_16x16x32_bf16 v[96:99], v[186:189], v[210:213], v[96:99]
	v_mfma_f32_16x16x32_bf16 v[88:91], v[194:197], v[210:213], v[88:91]
	v_mfma_f32_16x16x32_bf16 v[80:83], v[186:189], v[218:221], v[80:83]
	v_mfma_f32_16x16x32_bf16 v[72:75], v[194:197], v[218:221], v[72:75]
	s_barrier
; #define PG8_STAGE(bufoff, gbase, voff) do { _Pragma("unroll") for (int _i = 0; _i < 2; ++_i) \
;         __builtin_amdgcn_global_load_lds((const unsigned*)((const char*)(gbase) + (voff)[_i]), (PG8_LAS unsigned*)(lds + (bufoff) + ldsw + _i * 8192), 16, 0, 0); } while (0)
; #define PG8_LDA(dst, b, h) do { _Pragma("unroll") for (int m = 0; m < 4; ++m) _Pragma("unroll") for (int k = 0; k < 2; ++k) dst[m][k] = *(const PG8_LAS bf16x8*)(lds + PG8_SA(b, h) + aoff + m * 2048 + k * 1024); } while (0)
; #define PG8_MMA(ai, bj, At, Bt) do { __builtin_amdgcn_s_setprio(1); _Pragma("unroll") for (int m = 0; m < 4; ++m) _Pragma("unroll") for (int n = 0; n < 2; ++n) _Pragma("unroll") for (int k = 0; k < 2; ++k) \
;         acc[ai][bj][m][n] = __builtin_amdgcn_mfma_f32_16x16x32_bf16(Bt[n][k], At[m][k], acc[ai][bj][m][n], 0, 0, 0); __builtin_amdgcn_s_setprio(0); } while (0)
; #define PG8_WAIT_V(n) asm volatile("s_waitcnt vmcnt(" #n ")" ::: "memory")
; #define PG8_WAIT_L(n) asm volatile("s_waitcnt lgkmcnt(" #n ")" ::: "memory")
; #define PG8_BAR __builtin_amdgcn_s_barrier()
; #define PG8_SCHED __builtin_amdgcn_sched_barrier(0)
; template <class Epi, class Sched, bool ALIGN_EPI = false, bool SP2 = false>
; __device__ __forceinline__ void gemm_phase(PG8_LAS unsigned char* lds, const Gemm g, const Sched& S, const Epi& E) {
;     ...
;             PG8_WAIT_V(8); PG8_WAIT_L(0); PG8_BAR; PG8_MMA(0, 0, At, B0); PG8_MMA(0, 1, At, B1); PG8_BAR; PG8_SCHED;
;             PG8_LDA(At, 1, 1); PG8_STAGE(PG8_SB(1, 0), b3, voffB); PG8_STAGE(PG8_SB(1, 1), b3 + hstep, voffB); PG8_STAGE(PG8_SA(1, 0), a3, voffA);
;             PG8_WAIT_V(8); PG8_WAIT_L(0); PG8_BAR; PG8_MMA(1, 0, At, B0); PG8_MMA(1, 1, At, B1); PG8_BAR; PG8_SCHED;
;     ...
;         if constexpr (ALIGN_EPI) { if (wr == 0) PG8_BAR; }
	v_mfma_f32_16x16x32_bf16 v[68:71], v[186:189], v[226:229], v[68:71]
	v_mfma_f32_16x16x32_bf16 v[64:67], v[194:197], v[226:229], v[64:67]
	s_setprio 0
	s_mov_b32 m0, s89
	v_lshl_add_u64 v[230:231], v[230:231], 0, s[12:13]
	ds_read_b128 v[198:201], v164 offset:49152
	ds_read_b128 v[202:205], v164 offset:50176
	ds_read_b128 v[206:209], v164 offset:51200
	ds_read_b128 v[210:213], v164 offset:52224
	ds_read_b128 v[214:217], v164 offset:53248
	ds_read_b128 v[218:221], v164 offset:54272
	ds_read_b128 v[222:225], v164 offset:55296
	ds_read_b128 v[226:229], v164 offset:56320
	global_load_lds_dwordx4 v[230:231], off
	s_add_i32 m0, s89, 0x2000
	s_add_u32 s52, s76, 0x80080
	v_lshl_add_u64 v[230:231], v[232:233], 0, s[12:13]
	s_addc_u32 s53, s77, 0
	s_add_i32 s56, s88, s3
	global_load_lds_dwordx4 v[230:231], off
	v_lshl_add_u64 v[230:231], s[52:53], 0, v[138:139]
	s_mov_b32 m0, s56
	s_nop 0
	global_load_lds_dwordx4 v[230:231], off
	v_lshl_add_u64 v[230:231], s[52:53], 0, v[142:143]
	s_add_i32 m0, s56, 0x2000
	s_nop 0
	global_load_lds_dwordx4 v[230:231], off
	v_lshl_add_u64 v[230:231], v[234:235], 0, s[12:13]
	s_mov_b32 m0, s38
	s_nop 0
	global_load_lds_dwordx4 v[230:231], off
	v_lshl_add_u64 v[230:231], v[236:237], 0, s[12:13]
	s_mov_b32 m0, s39
	s_nop 0
	global_load_lds_dwordx4 v[230:231], off
	s_waitcnt vmcnt(8)
	s_waitcnt lgkmcnt(0)
	s_barrier
	s_setprio 1
	s_waitcnt lgkmcnt(0)
	v_mfma_f32_16x16x32_bf16 v[60:63], v[166:169], v[198:201], v[60:63]
	v_mfma_f32_16x16x32_bf16 v[56:59], v[174:177], v[198:201], v[56:59]
	v_mfma_f32_16x16x32_bf16 v[52:55], v[166:169], v[206:209], v[52:55]
	v_mfma_f32_16x16x32_bf16 v[44:47], v[174:177], v[206:209], v[44:47]
	v_mfma_f32_16x16x32_bf16 v[36:39], v[166:169], v[214:217], v[36:39]
	v_mfma_f32_16x16x32_bf16 v[28:31], v[174:177], v[214:217], v[28:31]
	v_mfma_f32_16x16x32_bf16 v[20:23], v[166:169], v[222:225], v[20:23]
	v_mfma_f32_16x16x32_bf16 v[12:15], v[174:177], v[222:225], v[12:15]
	v_mfma_f32_16x16x32_bf16 v[60:63], v[170:173], v[202:205], v[60:63]
	v_mfma_f32_16x16x32_bf16 v[56:59], v[178:181], v[202:205], v[56:59]
	v_mfma_f32_16x16x32_bf16 v[52:55], v[170:173], v[210:213], v[52:55]
	v_mfma_f32_16x16x32_bf16 v[44:47], v[178:181], v[210:213], v[44:47]
	v_mfma_f32_16x16x32_bf16 v[36:39], v[170:173], v[218:221], v[36:39]
	v_mfma_f32_16x16x32_bf16 v[28:31], v[178:181], v[218:221], v[28:31]
	v_mfma_f32_16x16x32_bf16 v[20:23], v[170:173], v[226:229], v[20:23]
	v_mfma_f32_16x16x32_bf16 v[12:15], v[178:181], v[226:229], v[12:15]
	s_setprio 0
	s_setprio 1
	v_mfma_f32_16x16x32_bf16 v[48:51], v[182:185], v[198:201], v[48:51]
	v_mfma_f32_16x16x32_bf16 v[40:43], v[190:193], v[198:201], v[40:43]
	v_mfma_f32_16x16x32_bf16 v[32:35], v[182:185], v[206:209], v[32:35]
	v_mfma_f32_16x16x32_bf16 v[24:27], v[190:193], v[206:209], v[24:27]
	v_mfma_f32_16x16x32_bf16 v[16:19], v[182:185], v[214:217], v[16:19]
	v_mfma_f32_16x16x32_bf16 v[8:11], v[190:193], v[214:217], v[8:11]
	v_mfma_f32_16x16x32_bf16 v[4:7], v[182:185], v[222:225], v[4:7]
	v_mfma_f32_16x16x32_bf16 v[0:3], v[190:193], v[222:225], v[0:3]
	v_mfma_f32_16x16x32_bf16 v[48:51], v[186:189], v[202:205], v[48:51]
	v_mfma_f32_16x16x32_bf16 v[40:43], v[194:197], v[202:205], v[40:43]
	v_mfma_f32_16x16x32_bf16 v[32:35], v[186:189], v[210:213], v[32:35]
	v_mfma_f32_16x16x32_bf16 v[24:27], v[194:197], v[210:213], v[24:27]
	v_mfma_f32_16x16x32_bf16 v[16:19], v[186:189], v[218:221], v[16:19]
	v_mfma_f32_16x16x32_bf16 v[8:11], v[194:197], v[218:221], v[8:11]
	s_barrier
	v_mfma_f32_16x16x32_bf16 v[4:7], v[186:189], v[226:229], v[4:7]
	v_mfma_f32_16x16x32_bf16 v[0:3], v[194:197], v[226:229], v[0:3]
	s_setprio 0
	s_add_i32 s51, s51, 2
	s_add_u32 s74, s74, 0x100
	s_addc_u32 s75, s75, 0
	s_add_u32 s37, s37, 0x100
	s_addc_u32 s49, s49, 0
	s_cmp_gt_u32 s51, 5
	s_cbranch_scc0 .LBB0_410
	s_and_b64 vcc, exec, s[14:15]
	s_cbranch_vccz .LBB0_413
	s_barrier

; #define PG8_STAGE(bufoff, gbase, voff) do { _Pragma("unroll") for (int _i = 0; _i < 2; ++_i) \
;         __builtin_amdgcn_global_load_lds((const unsigned*)((const char*)(gbase) + (voff)[_i]), (PG8_LAS unsigned*)(lds + (bufoff) + ldsw + _i * 8192), 16, 0, 0); } while (0)
; #define PG8_LDA(dst, b, h) do { _Pragma("unroll") for (int m = 0; m < 4; ++m) _Pragma("unroll") for (int k = 0; k < 2; ++k) dst[m][k] = *(const PG8_LAS bf16x8*)(lds + PG8_SA(b, h) + aoff + m * 2048 + k * 1024); } while (0)
; #define PG8_LDB(dst, b, h) do { _Pragma("unroll") for (int n = 0; n < 2; ++n) _Pragma("unroll") for (int k = 0; k < 2; ++k) dst[n][k] = *(const PG8_LAS bf16x8*)(lds + PG8_SB(b, h) + boff + n * 2048 + k * 1024); } while (0)
; #define PG8_MMA(ai, bj, At, Bt) do { __builtin_amdgcn_s_setprio(1); _Pragma("unroll") for (int m = 0; m < 4; ++m) _Pragma("unroll") for (int n = 0; n < 2; ++n) _Pragma("unroll") for (int k = 0; k < 2; ++k) \
;         acc[ai][bj][m][n] = __builtin_amdgcn_mfma_f32_16x16x32_bf16(Bt[n][k], At[m][k], acc[ai][bj][m][n], 0, 0, 0); __builtin_amdgcn_s_setprio(0); } while (0)
; #define PG8_WAIT_V(n) asm volatile("s_waitcnt vmcnt(" #n ")" ::: "memory")
; #define PG8_WAIT_L(n) asm volatile("s_waitcnt lgkmcnt(" #n ")" ::: "memory")
; #define PG8_BAR __builtin_amdgcn_s_barrier()
; #define PG8_SCHED __builtin_amdgcn_sched_barrier(0)
; template <class Epi, class Sched, bool ALIGN_EPI = false, bool SP2 = false>
; __device__ __forceinline__ void gemm_phase(PG8_LAS unsigned char* lds, const Gemm g, const Sched& S, const Epi& E) {
;     ...
;         for (int t = 0; t < nt; t += 2) {
;             const bool last = (t == nt - 2);
;             const char* a1 = cA + (size_t)(t + 1) * kstep;
;             const char* a2 = last ? nA : cA + (size_t)(t + 2) * kstep; const char* b2 = last ? nB : cB + (size_t)(t + 2) * kstep;
;             const char* a3 = a2 + kstep; const char* b3 = b2 + kstep;
;             if constexpr (SP2) {
;             PG8_LDB(B0, 0, 0); PG8_LDB(B1, 0, 1); PG8_SCHED; PG8_LDA(At, 0, 0); PG8_STAGE(PG8_SA(1, 1), a1 + hstep, voffA);
;             PG8_WAIT_V(8); PG8_WAIT_L(0); PG8_BAR; PG8_MMA(0, 0, At, B0); PG8_MMA(0, 1, At, B1); PG8_BAR; PG8_SCHED;
.LBB0_545:
	ds_read_b128 v[112:115], v174
	ds_read_b128 v[116:119], v174 offset:1024
	ds_read_b128 v[120:123], v174 offset:2048
	ds_read_b128 v[124:127], v174 offset:3072
	ds_read_b128 v[164:167], v175
	ds_read_b128 v[168:171], v175 offset:1024
	ds_read_b128 v[178:181], v175 offset:2048
	ds_read_b128 v[182:185], v175 offset:3072
	s_add_u32 s52, s68, 0xfff80080
	s_addc_u32 s53, s69, -1
	s_cmp_eq_u32 s88, 28
	s_cselect_b32 s73, s41, s53
	s_cselect_b32 s72, s84, s52
	s_cselect_b32 s71, s37, s87
	s_cselect_b32 s70, s85, s86
	v_lshl_add_u64 v[218:219], s[68:69], 0, v[156:157]
	s_add_i32 m0, s39, 0xc000
	ds_read_b128 v[186:189], v176
	ds_read_b128 v[190:193], v176 offset:1024
	ds_read_b128 v[194:197], v176 offset:2048
	ds_read_b128 v[198:201], v176 offset:3072
	ds_read_b128 v[202:205], v176 offset:4096
	ds_read_b128 v[206:209], v176 offset:5120
	ds_read_b128 v[210:213], v176 offset:6144
	ds_read_b128 v[214:217], v176 offset:7168
	global_load_lds_dwordx4 v[218:219], off
	v_lshl_add_u64 v[218:219], s[68:69], 0, v[158:159]
	s_add_i32 m0, s39, 0xe000
	s_nop 0
	global_load_lds_dwordx4 v[218:219], off
	s_waitcnt vmcnt(8)
	s_waitcnt lgkmcnt(0)
	s_barrier
	s_setprio 1
	s_waitcnt lgkmcnt(0)
	v_mfma_f32_16x16x32_bf16 v[140:143], v[112:115], v[186:189], v[140:143]
	v_mfma_f32_16x16x32_bf16 v[136:139], v[120:123], v[186:189], v[136:139]
	v_mfma_f32_16x16x32_bf16 v[108:111], v[112:115], v[194:197], v[108:111]
	v_mfma_f32_16x16x32_bf16 v[104:107], v[120:123], v[194:197], v[104:107]
	v_mfma_f32_16x16x32_bf16 v[92:95], v[112:115], v[202:205], v[92:95]
	v_mfma_f32_16x16x32_bf16 v[88:91], v[120:123], v[202:205], v[88:91]
	v_mfma_f32_16x16x32_bf16 v[76:79], v[112:115], v[210:213], v[76:79]
	v_mfma_f32_16x16x32_bf16 v[72:75], v[120:123], v[210:213], v[72:75]
	v_mfma_f32_16x16x32_bf16 v[140:143], v[116:119], v[190:193], v[140:143]
	v_mfma_f32_16x16x32_bf16 v[136:139], v[124:127], v[190:193], v[136:139]
	v_mfma_f32_16x16x32_bf16 v[108:111], v[116:119], v[198:201], v[108:111]
	v_mfma_f32_16x16x32_bf16 v[104:107], v[124:127], v[198:201], v[104:107]
	v_mfma_f32_16x16x32_bf16 v[92:95], v[116:119], v[206:209], v[92:95]
	v_mfma_f32_16x16x32_bf16 v[88:91], v[124:127], v[206:209], v[88:91]
	v_mfma_f32_16x16x32_bf16 v[76:79], v[116:119], v[214:217], v[76:79]
	v_mfma_f32_16x16x32_bf16 v[72:75], v[124:127], v[214:217], v[72:75]
	s_setprio 0
	s_setprio 1
	v_mfma_f32_16x16x32_bf16 v[132:135], v[164:167], v[186:189], v[132:135]
	v_mfma_f32_16x16x32_bf16 v[128:131], v[178:181], v[186:189], v[128:131]
	v_mfma_f32_16x16x32_bf16 v[100:103], v[164:167], v[194:197], v[100:103]
	v_mfma_f32_16x16x32_bf16 v[96:99], v[178:181], v[194:197], v[96:99]
	v_mfma_f32_16x16x32_bf16 v[84:87], v[164:167], v[202:205], v[84:87]
	v_mfma_f32_16x16x32_bf16 v[80:83], v[178:181], v[202:205], v[80:83]
	v_mfma_f32_16x16x32_bf16 v[68:71], v[164:167], v[210:213], v[68:71]
	v_mfma_f32_16x16x32_bf16 v[64:67], v[178:181], v[210:213], v[64:67]
	v_mfma_f32_16x16x32_bf16 v[132:135], v[168:171], v[190:193], v[132:135]
	v_mfma_f32_16x16x32_bf16 v[128:131], v[182:185], v[190:193], v[128:131]
	v_mfma_f32_16x16x32_bf16 v[100:103], v[168:171], v[198:201], v[100:103]
	v_mfma_f32_16x16x32_bf16 v[96:99], v[182:185], v[198:201], v[96:99]
	v_mfma_f32_16x16x32_bf16 v[84:87], v[168:171], v[206:209], v[84:87]
	v_mfma_f32_16x16x32_bf16 v[80:83], v[182:185], v[206:209], v[80:83]
	s_barrier
	v_mfma_f32_16x16x32_bf16 v[68:71], v[168:171], v[214:217], v[68:71]
	v_mfma_f32_16x16x32_bf16 v[64:67], v[182:185], v[214:217], v[64:67]
	s_setprio 0
	s_add_i32 s52, s81, s29
	v_lshl_add_u64 v[218:219], s[70:71], 0, v[152:153]
	s_mov_b32 m0, s52
	ds_read_b128 v[186:189], v176 offset:16384
	ds_read_b128 v[190:193], v176 offset:17408
	ds_read_b128 v[194:197], v176 offset:18432
	ds_read_b128 v[198:201], v176 offset:19456
	ds_read_b128 v[202:205], v176 offset:20480
	ds_read_b128 v[206:209], v176 offset:21504
	ds_read_b128 v[210:213], v176 offset:22528
	ds_read_b128 v[214:217], v176 offset:23552
	global_load_lds_dwordx4 v[218:219], off
	s_add_i32 m0, s52, 0x2000
	s_add_u32 s52, s70, 0x80000
	v_lshl_add_u64 v[220:221], s[70:71], 0, v[148:149]
	s_addc_u32 s53, s71, 0
	s_add_i32 s56, s82, s29
	global_load_lds_dwordx4 v[220:221], off
	v_lshl_add_u64 v[222:223], s[52:53], 0, v[152:153]
	s_mov_b32 m0, s56
	v_lshl_add_u64 v[224:225], s[72:73], 0, v[150:151]
	global_load_lds_dwordx4 v[222:223], off
	v_lshl_add_u64 v[222:223], s[52:53], 0, v[148:149]
	s_add_i32 m0, s56, 0x2000
	s_nop 0
	global_load_lds_dwordx4 v[222:223], off
	v_lshl_add_u64 v[222:223], s[72:73], 0, v[154:155]
	s_mov_b32 m0, s39
	s_nop 0
	global_load_lds_dwordx4 v[222:223], off
	s_mov_b32 m0, s55
	s_nop 0
	global_load_lds_dwordx4 v[224:225], off
	s_waitcnt vmcnt(8)
	s_waitcnt lgkmcnt(0)
	s_barrier
; #define PG8_STAGE(bufoff, gbase, voff) do { _Pragma("unroll") for (int _i = 0; _i < 2; ++_i) \
;         __builtin_amdgcn_global_load_lds((const unsigned*)((const char*)(gbase) + (voff)[_i]), (PG8_LAS unsigned*)(lds + (bufoff) + ldsw + _i * 8192), 16, 0, 0); } while (0)
; #define PG8_LDA(dst, b, h) do { _Pragma("unroll") for (int m = 0; m < 4; ++m) _Pragma("unroll") for (int k = 0; k < 2; ++k) dst[m][k] = *(const PG8_LAS bf16x8*)(lds + PG8_SA(b, h) + aoff + m * 2048 + k * 1024); } while (0)
; #define PG8_LDB(dst, b, h) do { _Pragma("unroll") for (int n = 0; n < 2; ++n) _Pragma("unroll") for (int k = 0; k < 2; ++k) dst[n][k] = *(const PG8_LAS bf16x8*)(lds + PG8_SB(b, h) + boff + n * 2048 + k * 1024); } while (0)
; #define PG8_MMA(ai, bj, At, Bt) do { __builtin_amdgcn_s_setprio(1); _Pragma("unroll") for (int m = 0; m < 4; ++m) _Pragma("unroll") for (int n = 0; n < 2; ++n) _Pragma("unroll") for (int k = 0; k < 2; ++k) \
;         acc[ai][bj][m][n] = __builtin_amdgcn_mfma_f32_16x16x32_bf16(Bt[n][k], At[m][k], acc[ai][bj][m][n], 0, 0, 0); __builtin_amdgcn_s_setprio(0); } while (0)
; #define PG8_WAIT_V(n) asm volatile("s_waitcnt vmcnt(" #n ")" ::: "memory")
; #define PG8_WAIT_L(n) asm volatile("s_waitcnt lgkmcnt(" #n ")" ::: "memory")
; #define PG8_BAR __builtin_amdgcn_s_barrier()
; #define PG8_SCHED __builtin_amdgcn_sched_barrier(0)
; template <class Epi, class Sched, bool ALIGN_EPI = false, bool SP2 = false>
; __device__ __forceinline__ void gemm_phase(PG8_LAS unsigned char* lds, const Gemm g, const Sched& S, const Epi& E) {
;     ...
;             PG8_WAIT_V(8); PG8_WAIT_L(0); PG8_BAR; PG8_MMA(1, 0, At, B0); PG8_MMA(1, 1, At, B1); PG8_BAR; PG8_SCHED;
;             PG8_LDB(B0, 1, 0); PG8_LDB(B1, 1, 1); PG8_SCHED; PG8_LDA(At, 1, 0); PG8_STAGE(PG8_SA(0, 1), a2 + hstep, voffA);
;             PG8_WAIT_V(8); PG8_WAIT_L(0); PG8_BAR; PG8_MMA(0, 0, At, B0); PG8_MMA(0, 1, At, B1); PG8_BAR; PG8_SCHED;
	s_setprio 1
	s_waitcnt lgkmcnt(0)
	v_mfma_f32_16x16x32_bf16 v[60:63], v[112:115], v[186:189], v[60:63]
	v_mfma_f32_16x16x32_bf16 v[56:59], v[120:123], v[186:189], v[56:59]
	v_mfma_f32_16x16x32_bf16 v[44:47], v[112:115], v[194:197], v[44:47]
	v_mfma_f32_16x16x32_bf16 v[40:43], v[120:123], v[194:197], v[40:43]
	v_mfma_f32_16x16x32_bf16 v[28:31], v[112:115], v[202:205], v[28:31]
	v_mfma_f32_16x16x32_bf16 v[24:27], v[120:123], v[202:205], v[24:27]
	v_mfma_f32_16x16x32_bf16 v[12:15], v[112:115], v[210:213], v[12:15]
	v_mfma_f32_16x16x32_bf16 v[8:11], v[120:123], v[210:213], v[8:11]
	v_mfma_f32_16x16x32_bf16 v[60:63], v[116:119], v[190:193], v[60:63]
	v_mfma_f32_16x16x32_bf16 v[56:59], v[124:127], v[190:193], v[56:59]
	v_mfma_f32_16x16x32_bf16 v[44:47], v[116:119], v[198:201], v[44:47]
	v_mfma_f32_16x16x32_bf16 v[40:43], v[124:127], v[198:201], v[40:43]
	v_mfma_f32_16x16x32_bf16 v[28:31], v[116:119], v[206:209], v[28:31]
	v_mfma_f32_16x16x32_bf16 v[24:27], v[124:127], v[206:209], v[24:27]
	v_mfma_f32_16x16x32_bf16 v[12:15], v[116:119], v[214:217], v[12:15]
	v_mfma_f32_16x16x32_bf16 v[8:11], v[124:127], v[214:217], v[8:11]
	s_setprio 0
	s_setprio 1
	v_mfma_f32_16x16x32_bf16 v[52:55], v[164:167], v[186:189], v[52:55]
	v_mfma_f32_16x16x32_bf16 v[48:51], v[178:181], v[186:189], v[48:51]
	v_mfma_f32_16x16x32_bf16 v[36:39], v[164:167], v[194:197], v[36:39]
	v_mfma_f32_16x16x32_bf16 v[32:35], v[178:181], v[194:197], v[32:35]
	v_mfma_f32_16x16x32_bf16 v[20:23], v[164:167], v[202:205], v[20:23]
	v_mfma_f32_16x16x32_bf16 v[16:19], v[178:181], v[202:205], v[16:19]
	v_mfma_f32_16x16x32_bf16 v[4:7], v[164:167], v[210:213], v[4:7]
	v_mfma_f32_16x16x32_bf16 v[0:3], v[178:181], v[210:213], v[0:3]
	v_mfma_f32_16x16x32_bf16 v[52:55], v[168:171], v[190:193], v[52:55]
	v_mfma_f32_16x16x32_bf16 v[48:51], v[182:185], v[190:193], v[48:51]
	v_mfma_f32_16x16x32_bf16 v[36:39], v[168:171], v[198:201], v[36:39]
	v_mfma_f32_16x16x32_bf16 v[32:35], v[182:185], v[198:201], v[32:35]
	v_mfma_f32_16x16x32_bf16 v[20:23], v[168:171], v[206:209], v[20:23]
	v_mfma_f32_16x16x32_bf16 v[16:19], v[182:185], v[206:209], v[16:19]
	s_barrier
	v_mfma_f32_16x16x32_bf16 v[4:7], v[168:171], v[214:217], v[4:7]
	v_mfma_f32_16x16x32_bf16 v[0:3], v[182:185], v[214:217], v[0:3]
	s_setprio 0
	s_add_i32 s56, 0, 0x18000
	s_add_i32 s57, 0, 0x1c000
	v_add_u32_e32 v124, s56, v172
	v_add_u32_e32 v177, s57, v172
	ds_read_b128 v[112:115], v124
	ds_read_b128 v[116:119], v124 offset:1024
	ds_read_b128 v[120:123], v124 offset:2048
	ds_read_b128 v[124:127], v124 offset:3072
	ds_read_b128 v[164:167], v177
	ds_read_b128 v[168:171], v177 offset:1024
	ds_read_b128 v[178:181], v177 offset:2048
	ds_read_b128 v[182:185], v177 offset:3072
	s_add_u32 s52, s72, 0x80000
	s_addc_u32 s53, s73, 0
	s_mov_b32 m0, s74
	v_lshl_add_u64 v[226:227], s[52:53], 0, v[154:155]
	ds_read_b128 v[186:189], v176 offset:32768
	ds_read_b128 v[190:193], v176 offset:33792
	ds_read_b128 v[194:197], v176 offset:34816
	ds_read_b128 v[198:201], v176 offset:35840
	ds_read_b128 v[202:205], v176 offset:36864
	ds_read_b128 v[206:209], v176 offset:37888
	ds_read_b128 v[210:213], v176 offset:38912
	ds_read_b128 v[214:217], v176 offset:39936
	global_load_lds_dwordx4 v[226:227], off
	v_lshl_add_u64 v[226:227], s[52:53], 0, v[150:151]
	s_mov_b32 m0, s75
	s_nop 0
	global_load_lds_dwordx4 v[226:227], off
	s_waitcnt vmcnt(8)
	s_waitcnt lgkmcnt(0)
	s_barrier
	s_setprio 1
	s_waitcnt lgkmcnt(0)
	v_mfma_f32_16x16x32_bf16 v[140:143], v[112:115], v[186:189], v[140:143]
	v_mfma_f32_16x16x32_bf16 v[136:139], v[120:123], v[186:189], v[136:139]
	v_mfma_f32_16x16x32_bf16 v[108:111], v[112:115], v[194:197], v[108:111]
	v_mfma_f32_16x16x32_bf16 v[104:107], v[120:123], v[194:197], v[104:107]
	v_mfma_f32_16x16x32_bf16 v[92:95], v[112:115], v[202:205], v[92:95]
	v_mfma_f32_16x16x32_bf16 v[88:91], v[120:123], v[202:205], v[88:91]
	v_mfma_f32_16x16x32_bf16 v[76:79], v[112:115], v[210:213], v[76:79]
	v_mfma_f32_16x16x32_bf16 v[72:75], v[120:123], v[210:213], v[72:75]
	v_mfma_f32_16x16x32_bf16 v[140:143], v[116:119], v[190:193], v[140:143]
	v_mfma_f32_16x16x32_bf16 v[136:139], v[124:127], v[190:193], v[136:139]
	v_mfma_f32_16x16x32_bf16 v[108:111], v[116:119], v[198:201], v[108:111]
	v_mfma_f32_16x16x32_bf16 v[104:107], v[124:127], v[198:201], v[104:107]
	v_mfma_f32_16x16x32_bf16 v[92:95], v[116:119], v[206:209], v[92:95]
	v_mfma_f32_16x16x32_bf16 v[88:91], v[124:127], v[206:209], v[88:91]
	v_mfma_f32_16x16x32_bf16 v[76:79], v[116:119], v[214:217], v[76:79]
	v_mfma_f32_16x16x32_bf16 v[72:75], v[124:127], v[214:217], v[72:75]
	s_setprio 0
	s_setprio 1
	v_mfma_f32_16x16x32_bf16 v[132:135], v[164:167], v[186:189], v[132:135]
	v_mfma_f32_16x16x32_bf16 v[128:131], v[178:181], v[186:189], v[128:131]
	v_mfma_f32_16x16x32_bf16 v[100:103], v[164:167], v[194:197], v[100:103]
	v_mfma_f32_16x16x32_bf16 v[96:99], v[178:181], v[194:197], v[96:99]
	v_mfma_f32_16x16x32_bf16 v[84:87], v[164:167], v[202:205], v[84:87]
	v_mfma_f32_16x16x32_bf16 v[80:83], v[178:181], v[202:205], v[80:83]
	v_mfma_f32_16x16x32_bf16 v[68:71], v[164:167], v[210:213], v[68:71]
	v_mfma_f32_16x16x32_bf16 v[64:67], v[178:181], v[210:213], v[64:67]
	v_mfma_f32_16x16x32_bf16 v[132:135], v[168:171], v[190:193], v[132:135]
	v_mfma_f32_16x16x32_bf16 v[128:131], v[182:185], v[190:193], v[128:131]
	v_mfma_f32_16x16x32_bf16 v[100:103], v[168:171], v[198:201], v[100:103]
	v_mfma_f32_16x16x32_bf16 v[96:99], v[182:185], v[198:201], v[96:99]
	v_mfma_f32_16x16x32_bf16 v[84:87], v[168:171], v[206:209], v[84:87]
	v_mfma_f32_16x16x32_bf16 v[80:83], v[182:185], v[206:209], v[80:83]
	s_barrier
; #define PG8_STAGE(bufoff, gbase, voff) do { _Pragma("unroll") for (int _i = 0; _i < 2; ++_i) \
;         __builtin_amdgcn_global_load_lds((const unsigned*)((const char*)(gbase) + (voff)[_i]), (PG8_LAS unsigned*)(lds + (bufoff) + ldsw + _i * 8192), 16, 0, 0); } while (0)
; #define PG8_LDA(dst, b, h) do { _Pragma("unroll") for (int m = 0; m < 4; ++m) _Pragma("unroll") for (int k = 0; k < 2; ++k) dst[m][k] = *(const PG8_LAS bf16x8*)(lds + PG8_SA(b, h) + aoff + m * 2048 + k * 1024); } while (0)
; #define PG8_MMA(ai, bj, At, Bt) do { __builtin_amdgcn_s_setprio(1); _Pragma("unroll") for (int m = 0; m < 4; ++m) _Pragma("unroll") for (int n = 0; n < 2; ++n) _Pragma("unroll") for (int k = 0; k < 2; ++k) \
;         acc[ai][bj][m][n] = __builtin_amdgcn_mfma_f32_16x16x32_bf16(Bt[n][k], At[m][k], acc[ai][bj][m][n], 0, 0, 0); __builtin_amdgcn_s_setprio(0); } while (0)
; #define PG8_WAIT_V(n) asm volatile("s_waitcnt vmcnt(" #n ")" ::: "memory")
; #define PG8_WAIT_L(n) asm volatile("s_waitcnt lgkmcnt(" #n ")" ::: "memory")
; #define PG8_BAR __builtin_amdgcn_s_barrier()
; #define PG8_SCHED __builtin_amdgcn_sched_barrier(0)
; template <class Epi, class Sched, bool ALIGN_EPI = false, bool SP2 = false>
; __device__ __forceinline__ void gemm_phase(PG8_LAS unsigned char* lds, const Gemm g, const Sched& S, const Epi& E) {
;     ...
;             PG8_WAIT_V(8); PG8_WAIT_L(0); PG8_BAR; PG8_MMA(0, 0, At, B0); PG8_MMA(0, 1, At, B1); PG8_BAR; PG8_SCHED;
;             PG8_LDA(At, 1, 1); PG8_STAGE(PG8_SB(1, 0), b3, voffB); PG8_STAGE(PG8_SB(1, 1), b3 + hstep, voffB); PG8_STAGE(PG8_SA(1, 0), a3, voffA);
;             PG8_WAIT_V(8); PG8_WAIT_L(0); PG8_BAR; PG8_MMA(1, 0, At, B0); PG8_MMA(1, 1, At, B1); PG8_BAR; PG8_SCHED;
;     ...
;         if constexpr (ALIGN_EPI) { if (wr == 0) PG8_BAR; }
	v_mfma_f32_16x16x32_bf16 v[68:71], v[168:171], v[214:217], v[68:71]
	v_mfma_f32_16x16x32_bf16 v[64:67], v[182:185], v[214:217], v[64:67]
	s_setprio 0
	s_add_i32 s52, s56, s29
	v_lshl_add_u64 v[218:219], v[218:219], 0, s[12:13]
	s_mov_b32 m0, s52
	ds_read_b128 v[186:189], v176 offset:49152
	ds_read_b128 v[190:193], v176 offset:50176
	ds_read_b128 v[194:197], v176 offset:51200
	ds_read_b128 v[198:201], v176 offset:52224
	ds_read_b128 v[202:205], v176 offset:53248
	ds_read_b128 v[206:209], v176 offset:54272
	ds_read_b128 v[210:213], v176 offset:55296
	ds_read_b128 v[214:217], v176 offset:56320
	global_load_lds_dwordx4 v[218:219], off
	s_add_i32 m0, s52, 0x2000
	s_add_u32 s52, s70, 0x80080
	v_lshl_add_u64 v[218:219], v[220:221], 0, s[12:13]
	s_addc_u32 s53, s71, 0
	s_add_i32 s56, s57, s29
	global_load_lds_dwordx4 v[218:219], off
	v_lshl_add_u64 v[218:219], s[52:53], 0, v[152:153]
	s_mov_b32 m0, s56
	s_nop 0
	global_load_lds_dwordx4 v[218:219], off
	v_lshl_add_u64 v[218:219], s[52:53], 0, v[148:149]
	s_add_i32 m0, s56, 0x2000
	s_nop 0
	global_load_lds_dwordx4 v[218:219], off
	v_lshl_add_u64 v[218:219], v[222:223], 0, s[12:13]
	s_mov_b32 m0, s77
	s_nop 0
	global_load_lds_dwordx4 v[218:219], off
	v_lshl_add_u64 v[218:219], v[224:225], 0, s[12:13]
	s_mov_b32 m0, s78
	s_nop 0
	global_load_lds_dwordx4 v[218:219], off
	s_waitcnt vmcnt(8)
	s_waitcnt lgkmcnt(0)
	s_barrier
	s_setprio 1
	s_waitcnt lgkmcnt(0)
	v_mfma_f32_16x16x32_bf16 v[60:63], v[112:115], v[186:189], v[60:63]
	v_mfma_f32_16x16x32_bf16 v[56:59], v[120:123], v[186:189], v[56:59]
	v_mfma_f32_16x16x32_bf16 v[44:47], v[112:115], v[194:197], v[44:47]
	v_mfma_f32_16x16x32_bf16 v[40:43], v[120:123], v[194:197], v[40:43]
	v_mfma_f32_16x16x32_bf16 v[28:31], v[112:115], v[202:205], v[28:31]
	v_mfma_f32_16x16x32_bf16 v[24:27], v[120:123], v[202:205], v[24:27]
	v_mfma_f32_16x16x32_bf16 v[12:15], v[112:115], v[210:213], v[12:15]
	v_mfma_f32_16x16x32_bf16 v[8:11], v[120:123], v[210:213], v[8:11]
	v_mfma_f32_16x16x32_bf16 v[60:63], v[116:119], v[190:193], v[60:63]
	v_mfma_f32_16x16x32_bf16 v[56:59], v[124:127], v[190:193], v[56:59]
	v_mfma_f32_16x16x32_bf16 v[44:47], v[116:119], v[198:201], v[44:47]
	v_mfma_f32_16x16x32_bf16 v[40:43], v[124:127], v[198:201], v[40:43]
	v_mfma_f32_16x16x32_bf16 v[28:31], v[116:119], v[206:209], v[28:31]
	v_mfma_f32_16x16x32_bf16 v[24:27], v[124:127], v[206:209], v[24:27]
	v_mfma_f32_16x16x32_bf16 v[12:15], v[116:119], v[214:217], v[12:15]
	v_mfma_f32_16x16x32_bf16 v[8:11], v[124:127], v[214:217], v[8:11]
	s_setprio 0
	s_setprio 1
	v_mfma_f32_16x16x32_bf16 v[52:55], v[164:167], v[186:189], v[52:55]
	v_mfma_f32_16x16x32_bf16 v[48:51], v[178:181], v[186:189], v[48:51]
	v_mfma_f32_16x16x32_bf16 v[36:39], v[164:167], v[194:197], v[36:39]
	v_mfma_f32_16x16x32_bf16 v[32:35], v[178:181], v[194:197], v[32:35]
	v_mfma_f32_16x16x32_bf16 v[20:23], v[164:167], v[202:205], v[20:23]
	v_mfma_f32_16x16x32_bf16 v[16:19], v[178:181], v[202:205], v[16:19]
	v_mfma_f32_16x16x32_bf16 v[4:7], v[164:167], v[210:213], v[4:7]
	v_mfma_f32_16x16x32_bf16 v[0:3], v[178:181], v[210:213], v[0:3]
	v_mfma_f32_16x16x32_bf16 v[52:55], v[168:171], v[190:193], v[52:55]
	v_mfma_f32_16x16x32_bf16 v[48:51], v[182:185], v[190:193], v[48:51]
	v_mfma_f32_16x16x32_bf16 v[36:39], v[168:171], v[198:201], v[36:39]
	v_mfma_f32_16x16x32_bf16 v[32:35], v[182:185], v[198:201], v[32:35]
	v_mfma_f32_16x16x32_bf16 v[20:23], v[168:171], v[206:209], v[20:23]
	v_mfma_f32_16x16x32_bf16 v[16:19], v[182:185], v[206:209], v[16:19]
	s_barrier
	v_mfma_f32_16x16x32_bf16 v[4:7], v[168:171], v[214:217], v[4:7]
	v_mfma_f32_16x16x32_bf16 v[0:3], v[182:185], v[214:217], v[0:3]
	s_setprio 0
	s_add_i32 s88, s88, 2
	s_add_u32 s68, s68, 0x100
	s_addc_u32 s69, s69, 0
	s_add_u32 s86, s86, 0x100
	s_addc_u32 s87, s87, 0
	s_cmp_gt_u32 s88, 29
	s_cbranch_scc0 .LBB0_545
	s_and_b64 vcc, exec, s[14:15]
	s_cbranch_vccz .LBB0_548
	s_barrier

; #define PG8_STAGE(bufoff, gbase, voff) do { _Pragma("unroll") for (int _i = 0; _i < 2; ++_i) \
;         __builtin_amdgcn_global_load_lds((const unsigned*)((const char*)(gbase) + (voff)[_i]), (PG8_LAS unsigned*)(lds + (bufoff) + ldsw + _i * 8192), 16, 0, 0); } while (0)
; #define PG8_LDA(dst, b, h) do { _Pragma("unroll") for (int m = 0; m < 4; ++m) _Pragma("unroll") for (int k = 0; k < 2; ++k) dst[m][k] = *(const PG8_LAS bf16x8*)(lds + PG8_SA(b, h) + aoff + m * 2048 + k * 1024); } while (0)
; #define PG8_LDB(dst, b, h) do { _Pragma("unroll") for (int n = 0; n < 2; ++n) _Pragma("unroll") for (int k = 0; k < 2; ++k) dst[n][k] = *(const PG8_LAS bf16x8*)(lds + PG8_SB(b, h) + boff + n * 2048 + k * 1024); } while (0)
; #define PG8_MMA(ai, bj, At, Bt) do { __builtin_amdgcn_s_setprio(1); _Pragma("unroll") for (int m = 0; m < 4; ++m) _Pragma("unroll") for (int n = 0; n < 2; ++n) _Pragma("unroll") for (int k = 0; k < 2; ++k) \
;         acc[ai][bj][m][n] = __builtin_amdgcn_mfma_f32_16x16x32_bf16(Bt[n][k], At[m][k], acc[ai][bj][m][n], 0, 0, 0); __builtin_amdgcn_s_setprio(0); } while (0)
; #define PG8_WAIT_V(n) asm volatile("s_waitcnt vmcnt(" #n ")" ::: "memory")
; #define PG8_WAIT_L(n) asm volatile("s_waitcnt lgkmcnt(" #n ")" ::: "memory")
; #define PG8_BAR __builtin_amdgcn_s_barrier()
; #define PG8_SCHED __builtin_amdgcn_sched_barrier(0)
; template <class Epi, class Sched, bool ALIGN_EPI = false, bool SP2 = false>
; __device__ __forceinline__ void gemm_phase(PG8_LAS unsigned char* lds, const Gemm g, const Sched& S, const Epi& E) {
;     ...
;         for (int t = 0; t < nt; t += 2) {
;             const bool last = (t == nt - 2);
;             const char* a1 = cA + (size_t)(t + 1) * kstep;
;             const char* a2 = last ? nA : cA + (size_t)(t + 2) * kstep; const char* b2 = last ? nB : cB + (size_t)(t + 2) * kstep;
;             const char* a3 = a2 + kstep; const char* b3 = b2 + kstep;
;             if constexpr (SP2) {
;             PG8_LDB(B0, 0, 0); PG8_LDB(B1, 0, 1); PG8_SCHED; PG8_LDA(At, 0, 0); PG8_STAGE(PG8_SA(1, 1), a1 + hstep, voffA);
;             PG8_WAIT_V(8); PG8_WAIT_L(0); PG8_BAR; PG8_MMA(0, 0, At, B0); PG8_MMA(0, 1, At, B1); PG8_BAR; PG8_SCHED;
.LBB0_624:
	ds_read_b128 v[128:131], v214
	ds_read_b128 v[132:135], v214 offset:1024
	ds_read_b128 v[158:161], v214 offset:2048
	ds_read_b128 v[162:165], v214 offset:3072
	ds_read_b128 v[166:169], v215
	ds_read_b128 v[170:173], v215 offset:1024
	ds_read_b128 v[174:177], v215 offset:2048
	ds_read_b128 v[178:181], v215 offset:3072
	s_add_u32 s52, s74, 0xffe00080
	s_addc_u32 s53, s75, -1
	s_cmpk_eq_i32 vcc_hi, 0x7c
	s_cselect_b32 s79, s51, s53
	s_cselect_b32 s78, s71, s52
	s_cselect_b32 s77, s49, vcc_lo
	s_cselect_b32 s76, s73, s93
	v_lshl_add_u64 v[226:227], s[74:75], 0, v[150:151]
	s_add_i32 m0, s83, 0xc000
	ds_read_b128 v[182:185], v216
	ds_read_b128 v[186:189], v216 offset:1024
	ds_read_b128 v[190:193], v216 offset:2048
	ds_read_b128 v[194:197], v216 offset:3072
	ds_read_b128 v[198:201], v216 offset:4096
	ds_read_b128 v[202:205], v216 offset:5120
	ds_read_b128 v[218:221], v216 offset:6144
	ds_read_b128 v[222:225], v216 offset:7168
	global_load_lds_dwordx4 v[226:227], off
	v_lshl_add_u64 v[226:227], s[74:75], 0, v[152:153]
	s_add_i32 m0, s83, 0xe000
	s_nop 0
	global_load_lds_dwordx4 v[226:227], off
	s_waitcnt vmcnt(8)
	s_waitcnt lgkmcnt(0)
	s_barrier
	s_setprio 1
	s_waitcnt lgkmcnt(0)
	v_mfma_f32_16x16x32_bf16 v[124:127], v[128:131], v[182:185], v[124:127]
	v_mfma_f32_16x16x32_bf16 v[120:123], v[158:161], v[182:185], v[120:123]
	v_mfma_f32_16x16x32_bf16 v[116:119], v[128:131], v[190:193], v[116:119]
	v_mfma_f32_16x16x32_bf16 v[112:115], v[158:161], v[190:193], v[112:115]
	v_mfma_f32_16x16x32_bf16 v[108:111], v[128:131], v[198:201], v[108:111]
	v_mfma_f32_16x16x32_bf16 v[104:107], v[158:161], v[198:201], v[104:107]
	v_mfma_f32_16x16x32_bf16 v[100:103], v[128:131], v[218:221], v[100:103]
	v_mfma_f32_16x16x32_bf16 v[96:99], v[158:161], v[218:221], v[96:99]
	v_mfma_f32_16x16x32_bf16 v[124:127], v[132:135], v[186:189], v[124:127]
	v_mfma_f32_16x16x32_bf16 v[120:123], v[162:165], v[186:189], v[120:123]
	v_mfma_f32_16x16x32_bf16 v[116:119], v[132:135], v[194:197], v[116:119]
	v_mfma_f32_16x16x32_bf16 v[112:115], v[162:165], v[194:197], v[112:115]
	v_mfma_f32_16x16x32_bf16 v[108:111], v[132:135], v[202:205], v[108:111]
	v_mfma_f32_16x16x32_bf16 v[104:107], v[162:165], v[202:205], v[104:107]
	v_mfma_f32_16x16x32_bf16 v[100:103], v[132:135], v[222:225], v[100:103]
	v_mfma_f32_16x16x32_bf16 v[96:99], v[162:165], v[222:225], v[96:99]
	s_setprio 0
	s_setprio 1
	v_mfma_f32_16x16x32_bf16 v[60:63], v[166:169], v[182:185], v[60:63]
	v_mfma_f32_16x16x32_bf16 v[56:59], v[174:177], v[182:185], v[56:59]
	v_mfma_f32_16x16x32_bf16 v[52:55], v[166:169], v[190:193], v[52:55]
	v_mfma_f32_16x16x32_bf16 v[48:51], v[174:177], v[190:193], v[48:51]
	v_mfma_f32_16x16x32_bf16 v[44:47], v[166:169], v[198:201], v[44:47]
	v_mfma_f32_16x16x32_bf16 v[40:43], v[174:177], v[198:201], v[40:43]
	v_mfma_f32_16x16x32_bf16 v[36:39], v[166:169], v[218:221], v[36:39]
	v_mfma_f32_16x16x32_bf16 v[32:35], v[174:177], v[218:221], v[32:35]
	v_mfma_f32_16x16x32_bf16 v[60:63], v[170:173], v[186:189], v[60:63]
	v_mfma_f32_16x16x32_bf16 v[56:59], v[178:181], v[186:189], v[56:59]
	v_mfma_f32_16x16x32_bf16 v[52:55], v[170:173], v[194:197], v[52:55]
	v_mfma_f32_16x16x32_bf16 v[48:51], v[178:181], v[194:197], v[48:51]
	v_mfma_f32_16x16x32_bf16 v[44:47], v[170:173], v[202:205], v[44:47]
	v_mfma_f32_16x16x32_bf16 v[40:43], v[178:181], v[202:205], v[40:43]
	s_barrier
	v_mfma_f32_16x16x32_bf16 v[36:39], v[170:173], v[222:225], v[36:39]
	v_mfma_f32_16x16x32_bf16 v[32:35], v[178:181], v[222:225], v[32:35]
	s_setprio 0
	s_add_i32 s52, s33, s82
	v_lshl_add_u64 v[226:227], s[76:77], 0, v[138:139]
	s_mov_b32 m0, s52
	ds_read_b128 v[182:185], v216 offset:16384
	ds_read_b128 v[186:189], v216 offset:17408
	ds_read_b128 v[190:193], v216 offset:18432
	ds_read_b128 v[194:197], v216 offset:19456
	ds_read_b128 v[198:201], v216 offset:20480
	ds_read_b128 v[202:205], v216 offset:21504
	ds_read_b128 v[218:221], v216 offset:22528
	ds_read_b128 v[222:225], v216 offset:23552
	global_load_lds_dwordx4 v[226:227], off
	s_add_i32 m0, s52, 0x2000
	s_add_u32 s52, s76, 0x200000
	v_lshl_add_u64 v[228:229], s[76:77], 0, v[142:143]
	s_addc_u32 s53, s77, 0
	s_add_i32 s56, s92, s82
	global_load_lds_dwordx4 v[228:229], off
	v_lshl_add_u64 v[230:231], s[52:53], 0, v[138:139]
	s_mov_b32 m0, s56
	v_lshl_add_u64 v[232:233], s[78:79], 0, v[140:141]
	global_load_lds_dwordx4 v[230:231], off
	v_lshl_add_u64 v[230:231], s[52:53], 0, v[142:143]
	s_add_i32 m0, s56, 0x2000
	s_nop 0
	global_load_lds_dwordx4 v[230:231], off
	v_lshl_add_u64 v[230:231], s[78:79], 0, v[136:137]
	s_mov_b32 m0, s83
	s_nop 0
	global_load_lds_dwordx4 v[230:231], off
	s_mov_b32 m0, s84
	s_nop 0
	global_load_lds_dwordx4 v[232:233], off
	s_waitcnt vmcnt(8)
	s_waitcnt lgkmcnt(0)
	s_barrier
; #define PG8_STAGE(bufoff, gbase, voff) do { _Pragma("unroll") for (int _i = 0; _i < 2; ++_i) \
;         __builtin_amdgcn_global_load_lds((const unsigned*)((const char*)(gbase) + (voff)[_i]), (PG8_LAS unsigned*)(lds + (bufoff) + ldsw + _i * 8192), 16, 0, 0); } while (0)
; #define PG8_LDA(dst, b, h) do { _Pragma("unroll") for (int m = 0; m < 4; ++m) _Pragma("unroll") for (int k = 0; k < 2; ++k) dst[m][k] = *(const PG8_LAS bf16x8*)(lds + PG8_SA(b, h) + aoff + m * 2048 + k * 1024); } while (0)
; #define PG8_LDB(dst, b, h) do { _Pragma("unroll") for (int n = 0; n < 2; ++n) _Pragma("unroll") for (int k = 0; k < 2; ++k) dst[n][k] = *(const PG8_LAS bf16x8*)(lds + PG8_SB(b, h) + boff + n * 2048 + k * 1024); } while (0)
; #define PG8_MMA(ai, bj, At, Bt) do { __builtin_amdgcn_s_setprio(1); _Pragma("unroll") for (int m = 0; m < 4; ++m) _Pragma("unroll") for (int n = 0; n < 2; ++n) _Pragma("unroll") for (int k = 0; k < 2; ++k) \
;         acc[ai][bj][m][n] = __builtin_amdgcn_mfma_f32_16x16x32_bf16(Bt[n][k], At[m][k], acc[ai][bj][m][n], 0, 0, 0); __builtin_amdgcn_s_setprio(0); } while (0)
; #define PG8_WAIT_V(n) asm volatile("s_waitcnt vmcnt(" #n ")" ::: "memory")
; #define PG8_WAIT_L(n) asm volatile("s_waitcnt lgkmcnt(" #n ")" ::: "memory")
; #define PG8_BAR __builtin_amdgcn_s_barrier()
; #define PG8_SCHED __builtin_amdgcn_sched_barrier(0)
; template <class Epi, class Sched, bool ALIGN_EPI = false, bool SP2 = false>
; __device__ __forceinline__ void gemm_phase(PG8_LAS unsigned char* lds, const Gemm g, const Sched& S, const Epi& E) {
;     ...
;             PG8_WAIT_V(8); PG8_WAIT_L(0); PG8_BAR; PG8_MMA(1, 0, At, B0); PG8_MMA(1, 1, At, B1); PG8_BAR; PG8_SCHED;
;             PG8_LDB(B0, 1, 0); PG8_LDB(B1, 1, 1); PG8_SCHED; PG8_LDA(At, 1, 0); PG8_STAGE(PG8_SA(0, 1), a2 + hstep, voffA);
;             PG8_WAIT_V(8); PG8_WAIT_L(0); PG8_BAR; PG8_MMA(0, 0, At, B0); PG8_MMA(0, 1, At, B1); PG8_BAR; PG8_SCHED;
	s_setprio 1
	s_waitcnt lgkmcnt(0)
	v_mfma_f32_16x16x32_bf16 v[92:95], v[128:131], v[182:185], v[92:95]
	v_mfma_f32_16x16x32_bf16 v[88:91], v[158:161], v[182:185], v[88:91]
	v_mfma_f32_16x16x32_bf16 v[84:87], v[128:131], v[190:193], v[84:87]
	v_mfma_f32_16x16x32_bf16 v[80:83], v[158:161], v[190:193], v[80:83]
	v_mfma_f32_16x16x32_bf16 v[76:79], v[128:131], v[198:201], v[76:79]
	v_mfma_f32_16x16x32_bf16 v[72:75], v[158:161], v[198:201], v[72:75]
	v_mfma_f32_16x16x32_bf16 v[68:71], v[128:131], v[218:221], v[68:71]
	v_mfma_f32_16x16x32_bf16 v[64:67], v[158:161], v[218:221], v[64:67]
	v_mfma_f32_16x16x32_bf16 v[92:95], v[132:135], v[186:189], v[92:95]
	v_mfma_f32_16x16x32_bf16 v[88:91], v[162:165], v[186:189], v[88:91]
	v_mfma_f32_16x16x32_bf16 v[84:87], v[132:135], v[194:197], v[84:87]
	v_mfma_f32_16x16x32_bf16 v[80:83], v[162:165], v[194:197], v[80:83]
	v_mfma_f32_16x16x32_bf16 v[76:79], v[132:135], v[202:205], v[76:79]
	v_mfma_f32_16x16x32_bf16 v[72:75], v[162:165], v[202:205], v[72:75]
	v_mfma_f32_16x16x32_bf16 v[68:71], v[132:135], v[222:225], v[68:71]
	v_mfma_f32_16x16x32_bf16 v[64:67], v[162:165], v[222:225], v[64:67]
	s_setprio 0
	s_setprio 1
	v_mfma_f32_16x16x32_bf16 v[28:31], v[166:169], v[182:185], v[28:31]
	v_mfma_f32_16x16x32_bf16 v[24:27], v[174:177], v[182:185], v[24:27]
	v_mfma_f32_16x16x32_bf16 v[20:23], v[166:169], v[190:193], v[20:23]
	v_mfma_f32_16x16x32_bf16 v[16:19], v[174:177], v[190:193], v[16:19]
	v_mfma_f32_16x16x32_bf16 v[12:15], v[166:169], v[198:201], v[12:15]
	v_mfma_f32_16x16x32_bf16 v[8:11], v[174:177], v[198:201], v[8:11]
	v_mfma_f32_16x16x32_bf16 v[4:7], v[166:169], v[218:221], v[4:7]
	v_mfma_f32_16x16x32_bf16 v[0:3], v[174:177], v[218:221], v[0:3]
	v_mfma_f32_16x16x32_bf16 v[28:31], v[170:173], v[186:189], v[28:31]
	v_mfma_f32_16x16x32_bf16 v[24:27], v[178:181], v[186:189], v[24:27]
	v_mfma_f32_16x16x32_bf16 v[20:23], v[170:173], v[194:197], v[20:23]
	v_mfma_f32_16x16x32_bf16 v[16:19], v[178:181], v[194:197], v[16:19]
	v_mfma_f32_16x16x32_bf16 v[12:15], v[170:173], v[202:205], v[12:15]
	v_mfma_f32_16x16x32_bf16 v[8:11], v[178:181], v[202:205], v[8:11]
	s_barrier
	v_mfma_f32_16x16x32_bf16 v[4:7], v[170:173], v[222:225], v[4:7]
	v_mfma_f32_16x16x32_bf16 v[0:3], v[178:181], v[222:225], v[0:3]
	s_setprio 0
	s_add_i32 s56, 0, 0x18000
	s_add_i32 s57, 0, 0x1c000
	v_add_u32_e32 v162, s56, v212
	v_add_u32_e32 v178, s57, v212
	ds_read_b128 v[128:131], v162
	ds_read_b128 v[132:135], v162 offset:1024
	ds_read_b128 v[158:161], v162 offset:2048
	ds_read_b128 v[162:165], v162 offset:3072
	ds_read_b128 v[166:169], v178
	ds_read_b128 v[170:173], v178 offset:1024
	ds_read_b128 v[174:177], v178 offset:2048
	ds_read_b128 v[178:181], v178 offset:3072
	s_add_u32 s52, s78, 0x200000
	s_addc_u32 s53, s79, 0
	s_mov_b32 m0, s85
	v_lshl_add_u64 v[234:235], s[52:53], 0, v[136:137]
	ds_read_b128 v[182:185], v216 offset:32768
	ds_read_b128 v[186:189], v216 offset:33792
	ds_read_b128 v[190:193], v216 offset:34816
	ds_read_b128 v[194:197], v216 offset:35840
	ds_read_b128 v[198:201], v216 offset:36864
	ds_read_b128 v[202:205], v216 offset:37888
	ds_read_b128 v[218:221], v216 offset:38912
	ds_read_b128 v[222:225], v216 offset:39936
	global_load_lds_dwordx4 v[234:235], off
	v_lshl_add_u64 v[234:235], s[52:53], 0, v[140:141]
	s_mov_b32 m0, s86
	s_nop 0
	global_load_lds_dwordx4 v[234:235], off
	s_waitcnt vmcnt(8)
	s_waitcnt lgkmcnt(0)
	s_barrier
	s_setprio 1
	s_waitcnt lgkmcnt(0)
	v_mfma_f32_16x16x32_bf16 v[124:127], v[128:131], v[182:185], v[124:127]
	v_mfma_f32_16x16x32_bf16 v[120:123], v[158:161], v[182:185], v[120:123]
	v_mfma_f32_16x16x32_bf16 v[116:119], v[128:131], v[190:193], v[116:119]
	v_mfma_f32_16x16x32_bf16 v[112:115], v[158:161], v[190:193], v[112:115]
	v_mfma_f32_16x16x32_bf16 v[108:111], v[128:131], v[198:201], v[108:111]
	v_mfma_f32_16x16x32_bf16 v[104:107], v[158:161], v[198:201], v[104:107]
	v_mfma_f32_16x16x32_bf16 v[100:103], v[128:131], v[218:221], v[100:103]
	v_mfma_f32_16x16x32_bf16 v[96:99], v[158:161], v[218:221], v[96:99]
	v_mfma_f32_16x16x32_bf16 v[124:127], v[132:135], v[186:189], v[124:127]
	v_mfma_f32_16x16x32_bf16 v[120:123], v[162:165], v[186:189], v[120:123]
	v_mfma_f32_16x16x32_bf16 v[116:119], v[132:135], v[194:197], v[116:119]
	v_mfma_f32_16x16x32_bf16 v[112:115], v[162:165], v[194:197], v[112:115]
	v_mfma_f32_16x16x32_bf16 v[108:111], v[132:135], v[202:205], v[108:111]
	v_mfma_f32_16x16x32_bf16 v[104:107], v[162:165], v[202:205], v[104:107]
	v_mfma_f32_16x16x32_bf16 v[100:103], v[132:135], v[222:225], v[100:103]
	v_mfma_f32_16x16x32_bf16 v[96:99], v[162:165], v[222:225], v[96:99]
	s_setprio 0
	s_setprio 1
	v_mfma_f32_16x16x32_bf16 v[60:63], v[166:169], v[182:185], v[60:63]
	v_mfma_f32_16x16x32_bf16 v[56:59], v[174:177], v[182:185], v[56:59]
	v_mfma_f32_16x16x32_bf16 v[52:55], v[166:169], v[190:193], v[52:55]
	v_mfma_f32_16x16x32_bf16 v[48:51], v[174:177], v[190:193], v[48:51]
	v_mfma_f32_16x16x32_bf16 v[44:47], v[166:169], v[198:201], v[44:47]
	v_mfma_f32_16x16x32_bf16 v[40:43], v[174:177], v[198:201], v[40:43]
	v_mfma_f32_16x16x32_bf16 v[36:39], v[166:169], v[218:221], v[36:39]
	v_mfma_f32_16x16x32_bf16 v[32:35], v[174:177], v[218:221], v[32:35]
	v_mfma_f32_16x16x32_bf16 v[60:63], v[170:173], v[186:189], v[60:63]
	v_mfma_f32_16x16x32_bf16 v[56:59], v[178:181], v[186:189], v[56:59]
	v_mfma_f32_16x16x32_bf16 v[52:55], v[170:173], v[194:197], v[52:55]
	v_mfma_f32_16x16x32_bf16 v[48:51], v[178:181], v[194:197], v[48:51]
	v_mfma_f32_16x16x32_bf16 v[44:47], v[170:173], v[202:205], v[44:47]
	v_mfma_f32_16x16x32_bf16 v[40:43], v[178:181], v[202:205], v[40:43]
	s_barrier
; #define PG8_STAGE(bufoff, gbase, voff) do { _Pragma("unroll") for (int _i = 0; _i < 2; ++_i) \
;         __builtin_amdgcn_global_load_lds((const unsigned*)((const char*)(gbase) + (voff)[_i]), (PG8_LAS unsigned*)(lds + (bufoff) + ldsw + _i * 8192), 16, 0, 0); } while (0)
; #define PG8_LDA(dst, b, h) do { _Pragma("unroll") for (int m = 0; m < 4; ++m) _Pragma("unroll") for (int k = 0; k < 2; ++k) dst[m][k] = *(const PG8_LAS bf16x8*)(lds + PG8_SA(b, h) + aoff + m * 2048 + k * 1024); } while (0)
; #define PG8_MMA(ai, bj, At, Bt) do { __builtin_amdgcn_s_setprio(1); _Pragma("unroll") for (int m = 0; m < 4; ++m) _Pragma("unroll") for (int n = 0; n < 2; ++n) _Pragma("unroll") for (int k = 0; k < 2; ++k) \
;         acc[ai][bj][m][n] = __builtin_amdgcn_mfma_f32_16x16x32_bf16(Bt[n][k], At[m][k], acc[ai][bj][m][n], 0, 0, 0); __builtin_amdgcn_s_setprio(0); } while (0)
; #define PG8_WAIT_V(n) asm volatile("s_waitcnt vmcnt(" #n ")" ::: "memory")
; #define PG8_WAIT_L(n) asm volatile("s_waitcnt lgkmcnt(" #n ")" ::: "memory")
; #define PG8_BAR __builtin_amdgcn_s_barrier()
; #define PG8_SCHED __builtin_amdgcn_sched_barrier(0)
; template <class Epi, class Sched, bool ALIGN_EPI = false, bool SP2 = false>
; __device__ __forceinline__ void gemm_phase(PG8_LAS unsigned char* lds, const Gemm g, const Sched& S, const Epi& E) {
;     ...
;             PG8_WAIT_V(8); PG8_WAIT_L(0); PG8_BAR; PG8_MMA(0, 0, At, B0); PG8_MMA(0, 1, At, B1); PG8_BAR; PG8_SCHED;
;             PG8_LDA(At, 1, 1); PG8_STAGE(PG8_SB(1, 0), b3, voffB); PG8_STAGE(PG8_SB(1, 1), b3 + hstep, voffB); PG8_STAGE(PG8_SA(1, 0), a3, voffA);
;             PG8_WAIT_V(8); PG8_WAIT_L(0); PG8_BAR; PG8_MMA(1, 0, At, B0); PG8_MMA(1, 1, At, B1); PG8_BAR; PG8_SCHED;
;     ...
;         if constexpr (ALIGN_EPI) { if (wr == 0) PG8_BAR; }
	v_mfma_f32_16x16x32_bf16 v[36:39], v[170:173], v[222:225], v[36:39]
	v_mfma_f32_16x16x32_bf16 v[32:35], v[178:181], v[222:225], v[32:35]
	s_setprio 0
	s_add_i32 s52, s56, s82
	v_lshl_add_u64 v[226:227], v[226:227], 0, s[36:37]
	s_mov_b32 m0, s52
	ds_read_b128 v[182:185], v216 offset:49152
	ds_read_b128 v[186:189], v216 offset:50176
	ds_read_b128 v[190:193], v216 offset:51200
	ds_read_b128 v[194:197], v216 offset:52224
	ds_read_b128 v[198:201], v216 offset:53248
	ds_read_b128 v[202:205], v216 offset:54272
	ds_read_b128 v[218:221], v216 offset:55296
	ds_read_b128 v[222:225], v216 offset:56320
	global_load_lds_dwordx4 v[226:227], off
	s_add_i32 m0, s52, 0x2000
	s_add_u32 s52, s76, 0x200080
	v_lshl_add_u64 v[226:227], v[228:229], 0, s[36:37]
	s_addc_u32 s53, s77, 0
	s_add_i32 s56, s57, s82
	global_load_lds_dwordx4 v[226:227], off
	v_lshl_add_u64 v[226:227], s[52:53], 0, v[138:139]
	s_mov_b32 m0, s56
	s_nop 0
	global_load_lds_dwordx4 v[226:227], off
	v_lshl_add_u64 v[226:227], s[52:53], 0, v[142:143]
	s_add_i32 m0, s56, 0x2000
	s_nop 0
	global_load_lds_dwordx4 v[226:227], off
	v_lshl_add_u64 v[226:227], v[230:231], 0, s[36:37]
	s_mov_b32 m0, s94
	s_nop 0
	global_load_lds_dwordx4 v[226:227], off
	v_lshl_add_u64 v[226:227], v[232:233], 0, s[36:37]
	s_mov_b32 m0, s95
	s_nop 0
	global_load_lds_dwordx4 v[226:227], off
	s_waitcnt vmcnt(8)
	s_waitcnt lgkmcnt(0)
	s_barrier
	s_setprio 1
	s_waitcnt lgkmcnt(0)
	v_mfma_f32_16x16x32_bf16 v[92:95], v[128:131], v[182:185], v[92:95]
	v_mfma_f32_16x16x32_bf16 v[88:91], v[158:161], v[182:185], v[88:91]
	v_mfma_f32_16x16x32_bf16 v[84:87], v[128:131], v[190:193], v[84:87]
	v_mfma_f32_16x16x32_bf16 v[80:83], v[158:161], v[190:193], v[80:83]
	v_mfma_f32_16x16x32_bf16 v[76:79], v[128:131], v[198:201], v[76:79]
	v_mfma_f32_16x16x32_bf16 v[72:75], v[158:161], v[198:201], v[72:75]
	v_mfma_f32_16x16x32_bf16 v[68:71], v[128:131], v[218:221], v[68:71]
	v_mfma_f32_16x16x32_bf16 v[64:67], v[158:161], v[218:221], v[64:67]
	v_mfma_f32_16x16x32_bf16 v[92:95], v[132:135], v[186:189], v[92:95]
	v_mfma_f32_16x16x32_bf16 v[88:91], v[162:165], v[186:189], v[88:91]
	v_mfma_f32_16x16x32_bf16 v[84:87], v[132:135], v[194:197], v[84:87]
	v_mfma_f32_16x16x32_bf16 v[80:83], v[162:165], v[194:197], v[80:83]
	v_mfma_f32_16x16x32_bf16 v[76:79], v[132:135], v[202:205], v[76:79]
	v_mfma_f32_16x16x32_bf16 v[72:75], v[162:165], v[202:205], v[72:75]
	v_mfma_f32_16x16x32_bf16 v[68:71], v[132:135], v[222:225], v[68:71]
	v_mfma_f32_16x16x32_bf16 v[64:67], v[162:165], v[222:225], v[64:67]
	s_setprio 0
	s_setprio 1
	v_mfma_f32_16x16x32_bf16 v[28:31], v[166:169], v[182:185], v[28:31]
	v_mfma_f32_16x16x32_bf16 v[24:27], v[174:177], v[182:185], v[24:27]
	v_mfma_f32_16x16x32_bf16 v[20:23], v[166:169], v[190:193], v[20:23]
	v_mfma_f32_16x16x32_bf16 v[16:19], v[174:177], v[190:193], v[16:19]
	v_mfma_f32_16x16x32_bf16 v[12:15], v[166:169], v[198:201], v[12:15]
	v_mfma_f32_16x16x32_bf16 v[8:11], v[174:177], v[198:201], v[8:11]
	v_mfma_f32_16x16x32_bf16 v[4:7], v[166:169], v[218:221], v[4:7]
	v_mfma_f32_16x16x32_bf16 v[0:3], v[174:177], v[218:221], v[0:3]
	v_mfma_f32_16x16x32_bf16 v[28:31], v[170:173], v[186:189], v[28:31]
	v_mfma_f32_16x16x32_bf16 v[24:27], v[178:181], v[186:189], v[24:27]
	v_mfma_f32_16x16x32_bf16 v[20:23], v[170:173], v[194:197], v[20:23]
	v_mfma_f32_16x16x32_bf16 v[16:19], v[178:181], v[194:197], v[16:19]
	v_mfma_f32_16x16x32_bf16 v[12:15], v[170:173], v[202:205], v[12:15]
	v_mfma_f32_16x16x32_bf16 v[8:11], v[178:181], v[202:205], v[8:11]
	s_barrier
	v_mfma_f32_16x16x32_bf16 v[4:7], v[170:173], v[222:225], v[4:7]
	v_mfma_f32_16x16x32_bf16 v[0:3], v[178:181], v[222:225], v[0:3]
	s_setprio 0
	s_add_i32 vcc_hi, vcc_hi, 2
	s_add_u32 s74, s74, 0x100
	s_addc_u32 s75, s75, 0
	s_add_u32 s93, s93, 0x100
	s_addc_u32 vcc_lo, vcc_lo, 0
	s_cmpk_gt_u32 vcc_hi, 0x7d
	s_cbranch_scc0 .LBB0_624
	s_and_b64 vcc, exec, s[40:41]
	s_cbranch_vccz .LBB0_627
	s_barrier

; #define PG8_STAGE(bufoff, gbase, voff) do { _Pragma("unroll") for (int _i = 0; _i < 2; ++_i) \
;         __builtin_amdgcn_global_load_lds((const unsigned*)((const char*)(gbase) + (voff)[_i]), (PG8_LAS unsigned*)(lds + (bufoff) + ldsw + _i * 8192), 16, 0, 0); } while (0)
; #define PG8_LDA(dst, b, h) do { _Pragma("unroll") for (int m = 0; m < 4; ++m) _Pragma("unroll") for (int k = 0; k < 2; ++k) dst[m][k] = *(const PG8_LAS bf16x8*)(lds + PG8_SA(b, h) + aoff + m * 2048 + k * 1024); } while (0)
; #define PG8_LDB(dst, b, h) do { _Pragma("unroll") for (int n = 0; n < 2; ++n) _Pragma("unroll") for (int k = 0; k < 2; ++k) dst[n][k] = *(const PG8_LAS bf16x8*)(lds + PG8_SB(b, h) + boff + n * 2048 + k * 1024); } while (0)
; #define PG8_MMA(ai, bj, At, Bt) do { __builtin_amdgcn_s_setprio(1); _Pragma("unroll") for (int m = 0; m < 4; ++m) _Pragma("unroll") for (int n = 0; n < 2; ++n) _Pragma("unroll") for (int k = 0; k < 2; ++k) \
;         acc[ai][bj][m][n] = __builtin_amdgcn_mfma_f32_16x16x32_bf16(Bt[n][k], At[m][k], acc[ai][bj][m][n], 0, 0, 0); __builtin_amdgcn_s_setprio(0); } while (0)
; #define PG8_WAIT_V(n) asm volatile("s_waitcnt vmcnt(" #n ")" ::: "memory")
; #define PG8_WAIT_L(n) asm volatile("s_waitcnt lgkmcnt(" #n ")" ::: "memory")
; #define PG8_BAR __builtin_amdgcn_s_barrier()
; #define PG8_SCHED __builtin_amdgcn_sched_barrier(0)
; template <class Epi, class Sched, bool ALIGN_EPI = false, bool SP2 = false>
; __device__ __forceinline__ void gemm_phase(PG8_LAS unsigned char* lds, const Gemm g, const Sched& S, const Epi& E) {
;     ...
;         for (int t = 0; t < nt; t += 2) {
;             const bool last = (t == nt - 2);
;             const char* a1 = cA + (size_t)(t + 1) * kstep;
;             const char* a2 = last ? nA : cA + (size_t)(t + 2) * kstep; const char* b2 = last ? nB : cB + (size_t)(t + 2) * kstep;
;             const char* a3 = a2 + kstep; const char* b3 = b2 + kstep;
;             if constexpr (SP2) {
;             PG8_LDB(B0, 0, 0); PG8_LDB(B1, 0, 1); PG8_SCHED; PG8_LDA(At, 0, 0); PG8_STAGE(PG8_SA(1, 1), a1 + hstep, voffA);
;             PG8_WAIT_V(8); PG8_WAIT_L(0); PG8_BAR; PG8_MMA(0, 0, At, B0); PG8_MMA(0, 1, At, B1); PG8_BAR; PG8_SCHED;
.LBB0_660:
	ds_read_b128 v[166:169], v145
	ds_read_b128 v[170:173], v145 offset:1024
	ds_read_b128 v[174:177], v145 offset:2048
	ds_read_b128 v[178:181], v145 offset:3072
	ds_read_b128 v[182:185], v149
	ds_read_b128 v[186:189], v149 offset:1024
	ds_read_b128 v[190:193], v149 offset:2048
	ds_read_b128 v[194:197], v149 offset:3072
	s_add_u32 s52, s72, 0xffe00080
	s_addc_u32 s53, s73, -1
	s_cmp_eq_u32 s49, 28
	s_cselect_b32 s77, s51, s53
	s_cselect_b32 s76, s50, s52
	s_cselect_b32 s75, s55, s41
	s_cselect_b32 s74, s54, s37
	s_mov_b32 m0, s82
	v_lshl_add_u64 v[230:231], s[72:73], 0, v[160:161]
	ds_read_b128 v[198:201], v164
	ds_read_b128 v[202:205], v164 offset:1024
	ds_read_b128 v[206:209], v164 offset:2048
	ds_read_b128 v[210:213], v164 offset:3072
	ds_read_b128 v[214:217], v164 offset:4096
	ds_read_b128 v[218:221], v164 offset:5120
	ds_read_b128 v[222:225], v164 offset:6144
	ds_read_b128 v[226:229], v164 offset:7168
	global_load_lds_dwordx4 v[230:231], off
	v_lshl_add_u64 v[230:231], s[72:73], 0, v[162:163]
	s_mov_b32 m0, s83
	s_nop 0
	global_load_lds_dwordx4 v[230:231], off
	s_waitcnt vmcnt(8)
	s_waitcnt lgkmcnt(0)
	s_barrier
	s_setprio 1
	s_waitcnt lgkmcnt(0)
	v_mfma_f32_16x16x32_bf16 v[124:127], v[166:169], v[198:201], v[124:127]
	v_mfma_f32_16x16x32_bf16 v[120:123], v[174:177], v[198:201], v[120:123]
	v_mfma_f32_16x16x32_bf16 v[116:119], v[166:169], v[206:209], v[116:119]
	v_mfma_f32_16x16x32_bf16 v[108:111], v[174:177], v[206:209], v[108:111]
	v_mfma_f32_16x16x32_bf16 v[100:103], v[166:169], v[214:217], v[100:103]
	v_mfma_f32_16x16x32_bf16 v[92:95], v[174:177], v[214:217], v[92:95]
	v_mfma_f32_16x16x32_bf16 v[84:87], v[166:169], v[222:225], v[84:87]
	v_mfma_f32_16x16x32_bf16 v[76:79], v[174:177], v[222:225], v[76:79]
	v_mfma_f32_16x16x32_bf16 v[124:127], v[170:173], v[202:205], v[124:127]
	v_mfma_f32_16x16x32_bf16 v[120:123], v[178:181], v[202:205], v[120:123]
	v_mfma_f32_16x16x32_bf16 v[116:119], v[170:173], v[210:213], v[116:119]
	v_mfma_f32_16x16x32_bf16 v[108:111], v[178:181], v[210:213], v[108:111]
	v_mfma_f32_16x16x32_bf16 v[100:103], v[170:173], v[218:221], v[100:103]
	v_mfma_f32_16x16x32_bf16 v[92:95], v[178:181], v[218:221], v[92:95]
	v_mfma_f32_16x16x32_bf16 v[84:87], v[170:173], v[226:229], v[84:87]
	v_mfma_f32_16x16x32_bf16 v[76:79], v[178:181], v[226:229], v[76:79]
	s_setprio 0
	s_setprio 1
	v_mfma_f32_16x16x32_bf16 v[112:115], v[182:185], v[198:201], v[112:115]
	v_mfma_f32_16x16x32_bf16 v[104:107], v[190:193], v[198:201], v[104:107]
	v_mfma_f32_16x16x32_bf16 v[96:99], v[182:185], v[206:209], v[96:99]
	v_mfma_f32_16x16x32_bf16 v[88:91], v[190:193], v[206:209], v[88:91]
	v_mfma_f32_16x16x32_bf16 v[80:83], v[182:185], v[214:217], v[80:83]
	v_mfma_f32_16x16x32_bf16 v[72:75], v[190:193], v[214:217], v[72:75]
	v_mfma_f32_16x16x32_bf16 v[68:71], v[182:185], v[222:225], v[68:71]
	v_mfma_f32_16x16x32_bf16 v[64:67], v[190:193], v[222:225], v[64:67]
	v_mfma_f32_16x16x32_bf16 v[112:115], v[186:189], v[202:205], v[112:115]
	v_mfma_f32_16x16x32_bf16 v[104:107], v[194:197], v[202:205], v[104:107]
	v_mfma_f32_16x16x32_bf16 v[96:99], v[186:189], v[210:213], v[96:99]
	v_mfma_f32_16x16x32_bf16 v[88:91], v[194:197], v[210:213], v[88:91]
	v_mfma_f32_16x16x32_bf16 v[80:83], v[186:189], v[218:221], v[80:83]
	v_mfma_f32_16x16x32_bf16 v[72:75], v[194:197], v[218:221], v[72:75]
	s_barrier
	v_mfma_f32_16x16x32_bf16 v[68:71], v[186:189], v[226:229], v[68:71]
	v_mfma_f32_16x16x32_bf16 v[64:67], v[194:197], v[226:229], v[64:67]
	s_setprio 0
	s_mov_b32 m0, s84
	v_lshl_add_u64 v[230:231], s[74:75], 0, v[138:139]
	s_add_u32 s52, s74, 0x200000
	ds_read_b128 v[198:201], v164 offset:16384
	ds_read_b128 v[202:205], v164 offset:17408
	ds_read_b128 v[206:209], v164 offset:18432
	ds_read_b128 v[210:213], v164 offset:19456
	ds_read_b128 v[214:217], v164 offset:20480
	ds_read_b128 v[218:221], v164 offset:21504
	ds_read_b128 v[222:225], v164 offset:22528
	ds_read_b128 v[226:229], v164 offset:23552
	global_load_lds_dwordx4 v[230:231], off
	v_lshl_add_u64 v[232:233], s[74:75], 0, v[142:143]
	s_mov_b32 m0, s85
	s_addc_u32 s53, s75, 0
	global_load_lds_dwordx4 v[232:233], off
	v_lshl_add_u64 v[234:235], s[52:53], 0, v[138:139]
	s_mov_b32 m0, s86
	v_lshl_add_u64 v[236:237], s[76:77], 0, v[140:141]
	global_load_lds_dwordx4 v[234:235], off
	v_lshl_add_u64 v[234:235], s[52:53], 0, v[142:143]
	s_mov_b32 m0, s87
	s_nop 0
	global_load_lds_dwordx4 v[234:235], off
	v_lshl_add_u64 v[234:235], s[76:77], 0, v[136:137]
	s_mov_b32 m0, s28
	s_nop 0
	global_load_lds_dwordx4 v[234:235], off
	s_mov_b32 m0, s29
	s_nop 0
	global_load_lds_dwordx4 v[236:237], off
	s_waitcnt vmcnt(8)
	s_waitcnt lgkmcnt(0)
	s_barrier
; #define PG8_STAGE(bufoff, gbase, voff) do { _Pragma("unroll") for (int _i = 0; _i < 2; ++_i) \
;         __builtin_amdgcn_global_load_lds((const unsigned*)((const char*)(gbase) + (voff)[_i]), (PG8_LAS unsigned*)(lds + (bufoff) + ldsw + _i * 8192), 16, 0, 0); } while (0)
; #define PG8_LDA(dst, b, h) do { _Pragma("unroll") for (int m = 0; m < 4; ++m) _Pragma("unroll") for (int k = 0; k < 2; ++k) dst[m][k] = *(const PG8_LAS bf16x8*)(lds + PG8_SA(b, h) + aoff + m * 2048 + k * 1024); } while (0)
; #define PG8_LDB(dst, b, h) do { _Pragma("unroll") for (int n = 0; n < 2; ++n) _Pragma("unroll") for (int k = 0; k < 2; ++k) dst[n][k] = *(const PG8_LAS bf16x8*)(lds + PG8_SB(b, h) + boff + n * 2048 + k * 1024); } while (0)
; #define PG8_MMA(ai, bj, At, Bt) do { __builtin_amdgcn_s_setprio(1); _Pragma("unroll") for (int m = 0; m < 4; ++m) _Pragma("unroll") for (int n = 0; n < 2; ++n) _Pragma("unroll") for (int k = 0; k < 2; ++k) \
;         acc[ai][bj][m][n] = __builtin_amdgcn_mfma_f32_16x16x32_bf16(Bt[n][k], At[m][k], acc[ai][bj][m][n], 0, 0, 0); __builtin_amdgcn_s_setprio(0); } while (0)
; #define PG8_WAIT_V(n) asm volatile("s_waitcnt vmcnt(" #n ")" ::: "memory")
; #define PG8_WAIT_L(n) asm volatile("s_waitcnt lgkmcnt(" #n ")" ::: "memory")
; #define PG8_BAR __builtin_amdgcn_s_barrier()
; #define PG8_SCHED __builtin_amdgcn_sched_barrier(0)
; template <class Epi, class Sched, bool ALIGN_EPI = false, bool SP2 = false>
; __device__ __forceinline__ void gemm_phase(PG8_LAS unsigned char* lds, const Gemm g, const Sched& S, const Epi& E) {
;     ...
;             PG8_WAIT_V(8); PG8_WAIT_L(0); PG8_BAR; PG8_MMA(1, 0, At, B0); PG8_MMA(1, 1, At, B1); PG8_BAR; PG8_SCHED;
;             PG8_LDB(B0, 1, 0); PG8_LDB(B1, 1, 1); PG8_SCHED; PG8_LDA(At, 1, 0); PG8_STAGE(PG8_SA(0, 1), a2 + hstep, voffA);
;             PG8_WAIT_V(8); PG8_WAIT_L(0); PG8_BAR; PG8_MMA(0, 0, At, B0); PG8_MMA(0, 1, At, B1); PG8_BAR; PG8_SCHED;
	s_setprio 1
	s_waitcnt lgkmcnt(0)
	v_mfma_f32_16x16x32_bf16 v[60:63], v[166:169], v[198:201], v[60:63]
	v_mfma_f32_16x16x32_bf16 v[56:59], v[174:177], v[198:201], v[56:59]
	v_mfma_f32_16x16x32_bf16 v[52:55], v[166:169], v[206:209], v[52:55]
	v_mfma_f32_16x16x32_bf16 v[44:47], v[174:177], v[206:209], v[44:47]
	v_mfma_f32_16x16x32_bf16 v[36:39], v[166:169], v[214:217], v[36:39]
	v_mfma_f32_16x16x32_bf16 v[28:31], v[174:177], v[214:217], v[28:31]
	v_mfma_f32_16x16x32_bf16 v[20:23], v[166:169], v[222:225], v[20:23]
	v_mfma_f32_16x16x32_bf16 v[12:15], v[174:177], v[222:225], v[12:15]
	v_mfma_f32_16x16x32_bf16 v[60:63], v[170:173], v[202:205], v[60:63]
	v_mfma_f32_16x16x32_bf16 v[56:59], v[178:181], v[202:205], v[56:59]
	v_mfma_f32_16x16x32_bf16 v[52:55], v[170:173], v[210:213], v[52:55]
	v_mfma_f32_16x16x32_bf16 v[44:47], v[178:181], v[210:213], v[44:47]
	v_mfma_f32_16x16x32_bf16 v[36:39], v[170:173], v[218:221], v[36:39]
	v_mfma_f32_16x16x32_bf16 v[28:31], v[178:181], v[218:221], v[28:31]
	v_mfma_f32_16x16x32_bf16 v[20:23], v[170:173], v[226:229], v[20:23]
	v_mfma_f32_16x16x32_bf16 v[12:15], v[178:181], v[226:229], v[12:15]
	s_setprio 0
	s_setprio 1
	v_mfma_f32_16x16x32_bf16 v[48:51], v[182:185], v[198:201], v[48:51]
	v_mfma_f32_16x16x32_bf16 v[40:43], v[190:193], v[198:201], v[40:43]
	v_mfma_f32_16x16x32_bf16 v[32:35], v[182:185], v[206:209], v[32:35]
	v_mfma_f32_16x16x32_bf16 v[24:27], v[190:193], v[206:209], v[24:27]
	v_mfma_f32_16x16x32_bf16 v[16:19], v[182:185], v[214:217], v[16:19]
	v_mfma_f32_16x16x32_bf16 v[8:11], v[190:193], v[214:217], v[8:11]
	v_mfma_f32_16x16x32_bf16 v[4:7], v[182:185], v[222:225], v[4:7]
	v_mfma_f32_16x16x32_bf16 v[0:3], v[190:193], v[222:225], v[0:3]
	v_mfma_f32_16x16x32_bf16 v[48:51], v[186:189], v[202:205], v[48:51]
	v_mfma_f32_16x16x32_bf16 v[40:43], v[194:197], v[202:205], v[40:43]
	v_mfma_f32_16x16x32_bf16 v[32:35], v[186:189], v[210:213], v[32:35]
	v_mfma_f32_16x16x32_bf16 v[24:27], v[194:197], v[210:213], v[24:27]
	v_mfma_f32_16x16x32_bf16 v[16:19], v[186:189], v[218:221], v[16:19]
	v_mfma_f32_16x16x32_bf16 v[8:11], v[194:197], v[218:221], v[8:11]
	s_barrier
	v_mfma_f32_16x16x32_bf16 v[4:7], v[186:189], v[226:229], v[4:7]
	v_mfma_f32_16x16x32_bf16 v[0:3], v[194:197], v[226:229], v[0:3]
	s_setprio 0
	ds_read_b128 v[166:169], v148
	ds_read_b128 v[170:173], v148 offset:1024
	ds_read_b128 v[174:177], v148 offset:2048
	ds_read_b128 v[178:181], v148 offset:3072
	ds_read_b128 v[182:185], v165
	ds_read_b128 v[186:189], v165 offset:1024
	ds_read_b128 v[190:193], v165 offset:2048
	ds_read_b128 v[194:197], v165 offset:3072
	s_add_u32 s52, s76, 0x200000
	s_addc_u32 s53, s77, 0
	s_mov_b32 m0, s33
	v_lshl_add_u64 v[238:239], s[52:53], 0, v[136:137]
	ds_read_b128 v[198:201], v164 offset:32768
	ds_read_b128 v[202:205], v164 offset:33792
	ds_read_b128 v[206:209], v164 offset:34816
	ds_read_b128 v[210:213], v164 offset:35840
	ds_read_b128 v[214:217], v164 offset:36864
	ds_read_b128 v[218:221], v164 offset:37888
	ds_read_b128 v[222:225], v164 offset:38912
	ds_read_b128 v[226:229], v164 offset:39936
	global_load_lds_dwordx4 v[238:239], off
	v_lshl_add_u64 v[238:239], s[52:53], 0, v[140:141]
	s_mov_b32 m0, s38
	s_nop 0
	global_load_lds_dwordx4 v[238:239], off
	s_waitcnt vmcnt(8)
	s_waitcnt lgkmcnt(0)
	s_barrier
	s_setprio 1
	s_waitcnt lgkmcnt(0)
	v_mfma_f32_16x16x32_bf16 v[124:127], v[166:169], v[198:201], v[124:127]
	v_mfma_f32_16x16x32_bf16 v[120:123], v[174:177], v[198:201], v[120:123]
	v_mfma_f32_16x16x32_bf16 v[116:119], v[166:169], v[206:209], v[116:119]
	v_mfma_f32_16x16x32_bf16 v[108:111], v[174:177], v[206:209], v[108:111]
	v_mfma_f32_16x16x32_bf16 v[100:103], v[166:169], v[214:217], v[100:103]
	v_mfma_f32_16x16x32_bf16 v[92:95], v[174:177], v[214:217], v[92:95]
	v_mfma_f32_16x16x32_bf16 v[84:87], v[166:169], v[222:225], v[84:87]
	v_mfma_f32_16x16x32_bf16 v[76:79], v[174:177], v[222:225], v[76:79]
	v_mfma_f32_16x16x32_bf16 v[124:127], v[170:173], v[202:205], v[124:127]
	v_mfma_f32_16x16x32_bf16 v[120:123], v[178:181], v[202:205], v[120:123]
	v_mfma_f32_16x16x32_bf16 v[116:119], v[170:173], v[210:213], v[116:119]
	v_mfma_f32_16x16x32_bf16 v[108:111], v[178:181], v[210:213], v[108:111]
	v_mfma_f32_16x16x32_bf16 v[100:103], v[170:173], v[218:221], v[100:103]
	v_mfma_f32_16x16x32_bf16 v[92:95], v[178:181], v[218:221], v[92:95]
	v_mfma_f32_16x16x32_bf16 v[84:87], v[170:173], v[226:229], v[84:87]
	v_mfma_f32_16x16x32_bf16 v[76:79], v[178:181], v[226:229], v[76:79]
	s_setprio 0
	s_setprio 1
	v_mfma_f32_16x16x32_bf16 v[112:115], v[182:185], v[198:201], v[112:115]
	v_mfma_f32_16x16x32_bf16 v[104:107], v[190:193], v[198:201], v[104:107]
	v_mfma_f32_16x16x32_bf16 v[96:99], v[182:185], v[206:209], v[96:99]
	v_mfma_f32_16x16x32_bf16 v[88:91], v[190:193], v[206:209], v[88:91]
	v_mfma_f32_16x16x32_bf16 v[80:83], v[182:185], v[214:217], v[80:83]
	v_mfma_f32_16x16x32_bf16 v[72:75], v[190:193], v[214:217], v[72:75]
	v_mfma_f32_16x16x32_bf16 v[68:71], v[182:185], v[222:225], v[68:71]
	v_mfma_f32_16x16x32_bf16 v[64:67], v[190:193], v[222:225], v[64:67]
	v_mfma_f32_16x16x32_bf16 v[112:115], v[186:189], v[202:205], v[112:115]
	v_mfma_f32_16x16x32_bf16 v[104:107], v[194:197], v[202:205], v[104:107]
	v_mfma_f32_16x16x32_bf16 v[96:99], v[186:189], v[210:213], v[96:99]
	v_mfma_f32_16x16x32_bf16 v[88:91], v[194:197], v[210:213], v[88:91]
	v_mfma_f32_16x16x32_bf16 v[80:83], v[186:189], v[218:221], v[80:83]
	v_mfma_f32_16x16x32_bf16 v[72:75], v[194:197], v[218:221], v[72:75]
	s_barrier
; #define PG8_STAGE(bufoff, gbase, voff) do { _Pragma("unroll") for (int _i = 0; _i < 2; ++_i) \
;         __builtin_amdgcn_global_load_lds((const unsigned*)((const char*)(gbase) + (voff)[_i]), (PG8_LAS unsigned*)(lds + (bufoff) + ldsw + _i * 8192), 16, 0, 0); } while (0)
; #define PG8_LDA(dst, b, h) do { _Pragma("unroll") for (int m = 0; m < 4; ++m) _Pragma("unroll") for (int k = 0; k < 2; ++k) dst[m][k] = *(const PG8_LAS bf16x8*)(lds + PG8_SA(b, h) + aoff + m * 2048 + k * 1024); } while (0)
; #define PG8_MMA(ai, bj, At, Bt) do { __builtin_amdgcn_s_setprio(1); _Pragma("unroll") for (int m = 0; m < 4; ++m) _Pragma("unroll") for (int n = 0; n < 2; ++n) _Pragma("unroll") for (int k = 0; k < 2; ++k) \
;         acc[ai][bj][m][n] = __builtin_amdgcn_mfma_f32_16x16x32_bf16(Bt[n][k], At[m][k], acc[ai][bj][m][n], 0, 0, 0); __builtin_amdgcn_s_setprio(0); } while (0)
; #define PG8_WAIT_V(n) asm volatile("s_waitcnt vmcnt(" #n ")" ::: "memory")
; #define PG8_WAIT_L(n) asm volatile("s_waitcnt lgkmcnt(" #n ")" ::: "memory")
; #define PG8_BAR __builtin_amdgcn_s_barrier()
; #define PG8_SCHED __builtin_amdgcn_sched_barrier(0)
; template <class Epi, class Sched, bool ALIGN_EPI = false, bool SP2 = false>
; __device__ __forceinline__ void gemm_phase(PG8_LAS unsigned char* lds, const Gemm g, const Sched& S, const Epi& E) {
;     ...
;             PG8_WAIT_V(8); PG8_WAIT_L(0); PG8_BAR; PG8_MMA(0, 0, At, B0); PG8_MMA(0, 1, At, B1); PG8_BAR; PG8_SCHED;
;             PG8_LDA(At, 1, 1); PG8_STAGE(PG8_SB(1, 0), b3, voffB); PG8_STAGE(PG8_SB(1, 1), b3 + hstep, voffB); PG8_STAGE(PG8_SA(1, 0), a3, voffA);
;             PG8_WAIT_V(8); PG8_WAIT_L(0); PG8_BAR; PG8_MMA(1, 0, At, B0); PG8_MMA(1, 1, At, B1); PG8_BAR; PG8_SCHED;
;     ...
;         if constexpr (ALIGN_EPI) { if (wr == 0) PG8_BAR; }
	v_mfma_f32_16x16x32_bf16 v[68:71], v[186:189], v[226:229], v[68:71]
	v_mfma_f32_16x16x32_bf16 v[64:67], v[194:197], v[226:229], v[64:67]
	s_setprio 0
	s_mov_b32 m0, s89
	v_lshl_add_u64 v[230:231], v[230:231], 0, s[12:13]
	ds_read_b128 v[198:201], v164 offset:49152
	ds_read_b128 v[202:205], v164 offset:50176
	ds_read_b128 v[206:209], v164 offset:51200
	ds_read_b128 v[210:213], v164 offset:52224
	ds_read_b128 v[214:217], v164 offset:53248
	ds_read_b128 v[218:221], v164 offset:54272
	ds_read_b128 v[222:225], v164 offset:55296
	ds_read_b128 v[226:229], v164 offset:56320
	global_load_lds_dwordx4 v[230:231], off
	s_add_i32 m0, s89, 0x2000
	s_add_u32 s52, s74, 0x200080
	v_lshl_add_u64 v[230:231], v[232:233], 0, s[12:13]
	s_addc_u32 s53, s75, 0
	s_add_i32 s56, s88, s3
	global_load_lds_dwordx4 v[230:231], off
	v_lshl_add_u64 v[230:231], s[52:53], 0, v[138:139]
	s_mov_b32 m0, s56
	s_nop 0
	global_load_lds_dwordx4 v[230:231], off
	v_lshl_add_u64 v[230:231], s[52:53], 0, v[142:143]
	s_add_i32 m0, s56, 0x2000
	s_nop 0
	global_load_lds_dwordx4 v[230:231], off
	v_lshl_add_u64 v[230:231], v[234:235], 0, s[12:13]
	s_mov_b32 m0, s71
	s_nop 0
	global_load_lds_dwordx4 v[230:231], off
	v_lshl_add_u64 v[230:231], v[236:237], 0, s[12:13]
	s_mov_b32 m0, s78
	s_nop 0
	global_load_lds_dwordx4 v[230:231], off
	s_waitcnt vmcnt(8)
	s_waitcnt lgkmcnt(0)
	s_barrier
	s_setprio 1
	s_waitcnt lgkmcnt(0)
	v_mfma_f32_16x16x32_bf16 v[60:63], v[166:169], v[198:201], v[60:63]
	v_mfma_f32_16x16x32_bf16 v[56:59], v[174:177], v[198:201], v[56:59]
	v_mfma_f32_16x16x32_bf16 v[52:55], v[166:169], v[206:209], v[52:55]
	v_mfma_f32_16x16x32_bf16 v[44:47], v[174:177], v[206:209], v[44:47]
	v_mfma_f32_16x16x32_bf16 v[36:39], v[166:169], v[214:217], v[36:39]
	v_mfma_f32_16x16x32_bf16 v[28:31], v[174:177], v[214:217], v[28:31]
	v_mfma_f32_16x16x32_bf16 v[20:23], v[166:169], v[222:225], v[20:23]
	v_mfma_f32_16x16x32_bf16 v[12:15], v[174:177], v[222:225], v[12:15]
	v_mfma_f32_16x16x32_bf16 v[60:63], v[170:173], v[202:205], v[60:63]
	v_mfma_f32_16x16x32_bf16 v[56:59], v[178:181], v[202:205], v[56:59]
	v_mfma_f32_16x16x32_bf16 v[52:55], v[170:173], v[210:213], v[52:55]
	v_mfma_f32_16x16x32_bf16 v[44:47], v[178:181], v[210:213], v[44:47]
	v_mfma_f32_16x16x32_bf16 v[36:39], v[170:173], v[218:221], v[36:39]
	v_mfma_f32_16x16x32_bf16 v[28:31], v[178:181], v[218:221], v[28:31]
	v_mfma_f32_16x16x32_bf16 v[20:23], v[170:173], v[226:229], v[20:23]
	v_mfma_f32_16x16x32_bf16 v[12:15], v[178:181], v[226:229], v[12:15]
	s_setprio 0
	s_setprio 1
	v_mfma_f32_16x16x32_bf16 v[48:51], v[182:185], v[198:201], v[48:51]
	v_mfma_f32_16x16x32_bf16 v[40:43], v[190:193], v[198:201], v[40:43]
	v_mfma_f32_16x16x32_bf16 v[32:35], v[182:185], v[206:209], v[32:35]
	v_mfma_f32_16x16x32_bf16 v[24:27], v[190:193], v[206:209], v[24:27]
	v_mfma_f32_16x16x32_bf16 v[16:19], v[182:185], v[214:217], v[16:19]
	v_mfma_f32_16x16x32_bf16 v[8:11], v[190:193], v[214:217], v[8:11]
	v_mfma_f32_16x16x32_bf16 v[4:7], v[182:185], v[222:225], v[4:7]
	v_mfma_f32_16x16x32_bf16 v[0:3], v[190:193], v[222:225], v[0:3]
	v_mfma_f32_16x16x32_bf16 v[48:51], v[186:189], v[202:205], v[48:51]
	v_mfma_f32_16x16x32_bf16 v[40:43], v[194:197], v[202:205], v[40:43]
	v_mfma_f32_16x16x32_bf16 v[32:35], v[186:189], v[210:213], v[32:35]
	v_mfma_f32_16x16x32_bf16 v[24:27], v[194:197], v[210:213], v[24:27]
	v_mfma_f32_16x16x32_bf16 v[16:19], v[186:189], v[218:221], v[16:19]
	v_mfma_f32_16x16x32_bf16 v[8:11], v[194:197], v[218:221], v[8:11]
	s_barrier
	v_mfma_f32_16x16x32_bf16 v[4:7], v[186:189], v[226:229], v[4:7]
	v_mfma_f32_16x16x32_bf16 v[0:3], v[194:197], v[226:229], v[0:3]
	s_setprio 0
	s_add_i32 s49, s49, 2
	s_add_u32 s72, s72, 0x100
	s_addc_u32 s73, s73, 0
	s_add_u32 s37, s37, 0x100
	s_addc_u32 s41, s41, 0
	s_cmp_gt_u32 s49, 29
	s_cbranch_scc0 .LBB0_660
	s_and_b64 vcc, exec, s[14:15]
	s_cbranch_vccz .LBB0_663
	s_barrier

; #define PG8_STAGE(bufoff, gbase, voff) do { _Pragma("unroll") for (int _i = 0; _i < 2; ++_i) \
;         __builtin_amdgcn_global_load_lds((const unsigned*)((const char*)(gbase) + (voff)[_i]), (PG8_LAS unsigned*)(lds + (bufoff) + ldsw + _i * 8192), 16, 0, 0); } while (0)
; #define PG8_LDA(dst, b, h) do { _Pragma("unroll") for (int m = 0; m < 4; ++m) _Pragma("unroll") for (int k = 0; k < 2; ++k) dst[m][k] = *(const PG8_LAS bf16x8*)(lds + PG8_SA(b, h) + aoff + m * 2048 + k * 1024); } while (0)
; #define PG8_LDB(dst, b, h) do { _Pragma("unroll") for (int n = 0; n < 2; ++n) _Pragma("unroll") for (int k = 0; k < 2; ++k) dst[n][k] = *(const PG8_LAS bf16x8*)(lds + PG8_SB(b, h) + boff + n * 2048 + k * 1024); } while (0)
; #define PG8_MMA(ai, bj, At, Bt) do { __builtin_amdgcn_s_setprio(1); _Pragma("unroll") for (int m = 0; m < 4; ++m) _Pragma("unroll") for (int n = 0; n < 2; ++n) _Pragma("unroll") for (int k = 0; k < 2; ++k) \
;         acc[ai][bj][m][n] = __builtin_amdgcn_mfma_f32_16x16x32_bf16(Bt[n][k], At[m][k], acc[ai][bj][m][n], 0, 0, 0); __builtin_amdgcn_s_setprio(0); } while (0)
; #define PG8_WAIT_V(n) asm volatile("s_waitcnt vmcnt(" #n ")" ::: "memory")
; #define PG8_WAIT_L(n) asm volatile("s_waitcnt lgkmcnt(" #n ")" ::: "memory")
; #define PG8_BAR __builtin_amdgcn_s_barrier()
; #define PG8_SCHED __builtin_amdgcn_sched_barrier(0)
; template <class Epi, class Sched, bool ALIGN_EPI = false, bool SP2 = false>
; __device__ __forceinline__ void gemm_phase(PG8_LAS unsigned char* lds, const Gemm g, const Sched& S, const Epi& E) {
;     ...
;         for (int t = 0; t < nt; t += 2) {
;             const bool last = (t == nt - 2);
;             const char* a1 = cA + (size_t)(t + 1) * kstep;
;             const char* a2 = last ? nA : cA + (size_t)(t + 2) * kstep; const char* b2 = last ? nB : cB + (size_t)(t + 2) * kstep;
;             const char* a3 = a2 + kstep; const char* b3 = b2 + kstep;
;             if constexpr (SP2) {
;             PG8_LDB(B0, 0, 0); PG8_LDB(B1, 0, 1); PG8_SCHED; PG8_LDA(At, 0, 0); PG8_STAGE(PG8_SA(1, 1), a1 + hstep, voffA);
;             PG8_WAIT_V(8); PG8_WAIT_L(0); PG8_BAR; PG8_MMA(0, 0, At, B0); PG8_MMA(0, 1, At, B1); PG8_BAR; PG8_SCHED;
.LBB0_809:
	ds_read_b128 v[128:131], v180
	ds_read_b128 v[132:135], v180 offset:1024
	ds_read_b128 v[136:139], v180 offset:2048
	ds_read_b128 v[140:143], v180 offset:3072
	ds_read_b128 v[160:163], v181
	ds_read_b128 v[164:167], v181 offset:1024
	ds_read_b128 v[184:187], v181 offset:2048
	ds_read_b128 v[188:191], v181 offset:3072
	s_add_u32 s52, s72, 0xfff80080
	s_addc_u32 s53, s73, -1
	s_cmp_eq_u32 s92, 28
	s_cselect_b32 s77, s5, s53
	s_cselect_b32 s76, s49, s52
	s_cselect_b32 s75, s45, s91
	s_cselect_b32 s74, s89, s90
	v_lshl_add_u64 v[168:169], s[72:73], 0, v[154:155]
	s_add_i32 m0, s71, 0xc000
	ds_read_b128 v[192:195], v182
	ds_read_b128 v[196:199], v182 offset:1024
	ds_read_b128 v[200:203], v182 offset:2048
	ds_read_b128 v[204:207], v182 offset:3072
	ds_read_b128 v[208:211], v182 offset:4096
	ds_read_b128 v[212:215], v182 offset:5120
	ds_read_b128 v[216:219], v182 offset:6144
	ds_read_b128 v[220:223], v182 offset:7168
	global_load_lds_dwordx4 v[168:169], off
	v_lshl_add_u64 v[168:169], s[72:73], 0, v[156:157]
	s_add_i32 m0, s71, 0xe000
	s_nop 0
	global_load_lds_dwordx4 v[168:169], off
	s_waitcnt vmcnt(8)
	s_waitcnt lgkmcnt(0)
	s_barrier
	s_setprio 1
	s_waitcnt lgkmcnt(0)
	v_mfma_f32_16x16x32_bf16 v[124:127], v[128:131], v[192:195], v[124:127]
	v_mfma_f32_16x16x32_bf16 v[120:123], v[136:139], v[192:195], v[120:123]
	v_mfma_f32_16x16x32_bf16 v[108:111], v[128:131], v[200:203], v[108:111]
	v_mfma_f32_16x16x32_bf16 v[104:107], v[136:139], v[200:203], v[104:107]
	v_mfma_f32_16x16x32_bf16 v[92:95], v[128:131], v[208:211], v[92:95]
	v_mfma_f32_16x16x32_bf16 v[88:91], v[136:139], v[208:211], v[88:91]
	v_mfma_f32_16x16x32_bf16 v[76:79], v[128:131], v[216:219], v[76:79]
	v_mfma_f32_16x16x32_bf16 v[72:75], v[136:139], v[216:219], v[72:75]
	v_mfma_f32_16x16x32_bf16 v[124:127], v[132:135], v[196:199], v[124:127]
	v_mfma_f32_16x16x32_bf16 v[120:123], v[140:143], v[196:199], v[120:123]
	v_mfma_f32_16x16x32_bf16 v[108:111], v[132:135], v[204:207], v[108:111]
	v_mfma_f32_16x16x32_bf16 v[104:107], v[140:143], v[204:207], v[104:107]
	v_mfma_f32_16x16x32_bf16 v[92:95], v[132:135], v[212:215], v[92:95]
	v_mfma_f32_16x16x32_bf16 v[88:91], v[140:143], v[212:215], v[88:91]
	v_mfma_f32_16x16x32_bf16 v[76:79], v[132:135], v[220:223], v[76:79]
	v_mfma_f32_16x16x32_bf16 v[72:75], v[140:143], v[220:223], v[72:75]
	s_setprio 0
	s_setprio 1
	v_mfma_f32_16x16x32_bf16 v[116:119], v[160:163], v[192:195], v[116:119]
	v_mfma_f32_16x16x32_bf16 v[112:115], v[184:187], v[192:195], v[112:115]
	v_mfma_f32_16x16x32_bf16 v[100:103], v[160:163], v[200:203], v[100:103]
	v_mfma_f32_16x16x32_bf16 v[96:99], v[184:187], v[200:203], v[96:99]
	v_mfma_f32_16x16x32_bf16 v[84:87], v[160:163], v[208:211], v[84:87]
	v_mfma_f32_16x16x32_bf16 v[80:83], v[184:187], v[208:211], v[80:83]
	v_mfma_f32_16x16x32_bf16 v[68:71], v[160:163], v[216:219], v[68:71]
	v_mfma_f32_16x16x32_bf16 v[64:67], v[184:187], v[216:219], v[64:67]
	v_mfma_f32_16x16x32_bf16 v[116:119], v[164:167], v[196:199], v[116:119]
	v_mfma_f32_16x16x32_bf16 v[112:115], v[188:191], v[196:199], v[112:115]
	v_mfma_f32_16x16x32_bf16 v[100:103], v[164:167], v[204:207], v[100:103]
	v_mfma_f32_16x16x32_bf16 v[96:99], v[188:191], v[204:207], v[96:99]
	v_mfma_f32_16x16x32_bf16 v[84:87], v[164:167], v[212:215], v[84:87]
	v_mfma_f32_16x16x32_bf16 v[80:83], v[188:191], v[212:215], v[80:83]
	s_barrier
	v_mfma_f32_16x16x32_bf16 v[68:71], v[164:167], v[220:223], v[68:71]
	v_mfma_f32_16x16x32_bf16 v[64:67], v[188:191], v[220:223], v[64:67]
	s_setprio 0
	s_add_i32 s52, s83, s78
	v_lshl_add_u64 v[168:169], s[74:75], 0, v[148:149]
	s_mov_b32 m0, s52
	ds_read_b128 v[192:195], v182 offset:16384
	ds_read_b128 v[196:199], v182 offset:17408
	ds_read_b128 v[200:203], v182 offset:18432
	ds_read_b128 v[204:207], v182 offset:19456
	ds_read_b128 v[208:211], v182 offset:20480
	ds_read_b128 v[212:215], v182 offset:21504
	ds_read_b128 v[216:219], v182 offset:22528
	ds_read_b128 v[220:223], v182 offset:23552
	global_load_lds_dwordx4 v[168:169], off
	s_add_i32 m0, s52, 0x2000
	s_add_u32 s52, s74, 0x80000
	v_lshl_add_u64 v[224:225], s[74:75], 0, v[152:153]
	s_addc_u32 s53, s75, 0
	s_add_i32 s56, s84, s78
	global_load_lds_dwordx4 v[224:225], off
	v_lshl_add_u64 v[226:227], s[52:53], 0, v[148:149]
	s_mov_b32 m0, s56
	v_lshl_add_u64 v[228:229], s[76:77], 0, v[150:151]
	global_load_lds_dwordx4 v[226:227], off
	v_lshl_add_u64 v[226:227], s[52:53], 0, v[152:153]
	s_add_i32 m0, s56, 0x2000
	s_nop 0
	global_load_lds_dwordx4 v[226:227], off
	v_lshl_add_u64 v[226:227], s[76:77], 0, v[144:145]
	s_mov_b32 m0, s71
	s_nop 0
	global_load_lds_dwordx4 v[226:227], off
	s_mov_b32 m0, s79
	s_nop 0
	global_load_lds_dwordx4 v[228:229], off
	s_waitcnt vmcnt(8)
	s_waitcnt lgkmcnt(0)
	s_barrier
; #define PG8_STAGE(bufoff, gbase, voff) do { _Pragma("unroll") for (int _i = 0; _i < 2; ++_i) \
;         __builtin_amdgcn_global_load_lds((const unsigned*)((const char*)(gbase) + (voff)[_i]), (PG8_LAS unsigned*)(lds + (bufoff) + ldsw + _i * 8192), 16, 0, 0); } while (0)
; #define PG8_LDA(dst, b, h) do { _Pragma("unroll") for (int m = 0; m < 4; ++m) _Pragma("unroll") for (int k = 0; k < 2; ++k) dst[m][k] = *(const PG8_LAS bf16x8*)(lds + PG8_SA(b, h) + aoff + m * 2048 + k * 1024); } while (0)
; #define PG8_LDB(dst, b, h) do { _Pragma("unroll") for (int n = 0; n < 2; ++n) _Pragma("unroll") for (int k = 0; k < 2; ++k) dst[n][k] = *(const PG8_LAS bf16x8*)(lds + PG8_SB(b, h) + boff + n * 2048 + k * 1024); } while (0)
; #define PG8_MMA(ai, bj, At, Bt) do { __builtin_amdgcn_s_setprio(1); _Pragma("unroll") for (int m = 0; m < 4; ++m) _Pragma("unroll") for (int n = 0; n < 2; ++n) _Pragma("unroll") for (int k = 0; k < 2; ++k) \
;         acc[ai][bj][m][n] = __builtin_amdgcn_mfma_f32_16x16x32_bf16(Bt[n][k], At[m][k], acc[ai][bj][m][n], 0, 0, 0); __builtin_amdgcn_s_setprio(0); } while (0)
; #define PG8_WAIT_V(n) asm volatile("s_waitcnt vmcnt(" #n ")" ::: "memory")
; #define PG8_WAIT_L(n) asm volatile("s_waitcnt lgkmcnt(" #n ")" ::: "memory")
; #define PG8_BAR __builtin_amdgcn_s_barrier()
; #define PG8_SCHED __builtin_amdgcn_sched_barrier(0)
; template <class Epi, class Sched, bool ALIGN_EPI = false, bool SP2 = false>
; __device__ __forceinline__ void gemm_phase(PG8_LAS unsigned char* lds, const Gemm g, const Sched& S, const Epi& E) {
;     ...
;             PG8_WAIT_V(8); PG8_WAIT_L(0); PG8_BAR; PG8_MMA(1, 0, At, B0); PG8_MMA(1, 1, At, B1); PG8_BAR; PG8_SCHED;
;             PG8_LDB(B0, 1, 0); PG8_LDB(B1, 1, 1); PG8_SCHED; PG8_LDA(At, 1, 0); PG8_STAGE(PG8_SA(0, 1), a2 + hstep, voffA);
;             PG8_WAIT_V(8); PG8_WAIT_L(0); PG8_BAR; PG8_MMA(0, 0, At, B0); PG8_MMA(0, 1, At, B1); PG8_BAR; PG8_SCHED;
	s_setprio 1
	s_waitcnt lgkmcnt(0)
	v_mfma_f32_16x16x32_bf16 v[60:63], v[128:131], v[192:195], v[60:63]
	v_mfma_f32_16x16x32_bf16 v[56:59], v[136:139], v[192:195], v[56:59]
	v_mfma_f32_16x16x32_bf16 v[44:47], v[128:131], v[200:203], v[44:47]
	v_mfma_f32_16x16x32_bf16 v[40:43], v[136:139], v[200:203], v[40:43]
	v_mfma_f32_16x16x32_bf16 v[28:31], v[128:131], v[208:211], v[28:31]
	v_mfma_f32_16x16x32_bf16 v[24:27], v[136:139], v[208:211], v[24:27]
	v_mfma_f32_16x16x32_bf16 v[12:15], v[128:131], v[216:219], v[12:15]
	v_mfma_f32_16x16x32_bf16 v[8:11], v[136:139], v[216:219], v[8:11]
	v_mfma_f32_16x16x32_bf16 v[60:63], v[132:135], v[196:199], v[60:63]
	v_mfma_f32_16x16x32_bf16 v[56:59], v[140:143], v[196:199], v[56:59]
	v_mfma_f32_16x16x32_bf16 v[44:47], v[132:135], v[204:207], v[44:47]
	v_mfma_f32_16x16x32_bf16 v[40:43], v[140:143], v[204:207], v[40:43]
	v_mfma_f32_16x16x32_bf16 v[28:31], v[132:135], v[212:215], v[28:31]
	v_mfma_f32_16x16x32_bf16 v[24:27], v[140:143], v[212:215], v[24:27]
	v_mfma_f32_16x16x32_bf16 v[12:15], v[132:135], v[220:223], v[12:15]
	v_mfma_f32_16x16x32_bf16 v[8:11], v[140:143], v[220:223], v[8:11]
	s_setprio 0
	s_setprio 1
	v_mfma_f32_16x16x32_bf16 v[52:55], v[160:163], v[192:195], v[52:55]
	v_mfma_f32_16x16x32_bf16 v[48:51], v[184:187], v[192:195], v[48:51]
	v_mfma_f32_16x16x32_bf16 v[36:39], v[160:163], v[200:203], v[36:39]
	v_mfma_f32_16x16x32_bf16 v[32:35], v[184:187], v[200:203], v[32:35]
	v_mfma_f32_16x16x32_bf16 v[20:23], v[160:163], v[208:211], v[20:23]
	v_mfma_f32_16x16x32_bf16 v[16:19], v[184:187], v[208:211], v[16:19]
	v_mfma_f32_16x16x32_bf16 v[4:7], v[160:163], v[216:219], v[4:7]
	v_mfma_f32_16x16x32_bf16 v[0:3], v[184:187], v[216:219], v[0:3]
	v_mfma_f32_16x16x32_bf16 v[52:55], v[164:167], v[196:199], v[52:55]
	v_mfma_f32_16x16x32_bf16 v[48:51], v[188:191], v[196:199], v[48:51]
	v_mfma_f32_16x16x32_bf16 v[36:39], v[164:167], v[204:207], v[36:39]
	v_mfma_f32_16x16x32_bf16 v[32:35], v[188:191], v[204:207], v[32:35]
	v_mfma_f32_16x16x32_bf16 v[20:23], v[164:167], v[212:215], v[20:23]
	v_mfma_f32_16x16x32_bf16 v[16:19], v[188:191], v[212:215], v[16:19]
	s_barrier
	v_mfma_f32_16x16x32_bf16 v[4:7], v[164:167], v[220:223], v[4:7]
	v_mfma_f32_16x16x32_bf16 v[0:3], v[188:191], v[220:223], v[0:3]
	s_setprio 0
	s_add_i32 s56, 0, 0x18000
	s_add_i32 s57, 0, 0x1c000
	v_add_u32_e32 v140, s56, v171
	v_add_u32_e32 v188, s57, v171
	ds_read_b128 v[128:131], v140
	ds_read_b128 v[132:135], v140 offset:1024
	ds_read_b128 v[136:139], v140 offset:2048
	ds_read_b128 v[140:143], v140 offset:3072
	ds_read_b128 v[160:163], v188
	ds_read_b128 v[164:167], v188 offset:1024
	ds_read_b128 v[184:187], v188 offset:2048
	ds_read_b128 v[188:191], v188 offset:3072
	s_add_u32 s52, s76, 0x80000
	s_addc_u32 s53, s77, 0
	s_mov_b32 m0, s80
	v_lshl_add_u64 v[230:231], s[52:53], 0, v[144:145]
	ds_read_b128 v[192:195], v182 offset:32768
	ds_read_b128 v[196:199], v182 offset:33792
	ds_read_b128 v[200:203], v182 offset:34816
	ds_read_b128 v[204:207], v182 offset:35840
	ds_read_b128 v[208:211], v182 offset:36864
	ds_read_b128 v[212:215], v182 offset:37888
	ds_read_b128 v[216:219], v182 offset:38912
	ds_read_b128 v[220:223], v182 offset:39936
	global_load_lds_dwordx4 v[230:231], off
	v_lshl_add_u64 v[230:231], s[52:53], 0, v[150:151]
	s_mov_b32 m0, s81
	s_nop 0
	global_load_lds_dwordx4 v[230:231], off
	s_waitcnt vmcnt(8)
	s_waitcnt lgkmcnt(0)
	s_barrier
	s_setprio 1
	s_waitcnt lgkmcnt(0)
	v_mfma_f32_16x16x32_bf16 v[124:127], v[128:131], v[192:195], v[124:127]
	v_mfma_f32_16x16x32_bf16 v[120:123], v[136:139], v[192:195], v[120:123]
	v_mfma_f32_16x16x32_bf16 v[108:111], v[128:131], v[200:203], v[108:111]
	v_mfma_f32_16x16x32_bf16 v[104:107], v[136:139], v[200:203], v[104:107]
	v_mfma_f32_16x16x32_bf16 v[92:95], v[128:131], v[208:211], v[92:95]
	v_mfma_f32_16x16x32_bf16 v[88:91], v[136:139], v[208:211], v[88:91]
	v_mfma_f32_16x16x32_bf16 v[76:79], v[128:131], v[216:219], v[76:79]
	v_mfma_f32_16x16x32_bf16 v[72:75], v[136:139], v[216:219], v[72:75]
	v_mfma_f32_16x16x32_bf16 v[124:127], v[132:135], v[196:199], v[124:127]
	v_mfma_f32_16x16x32_bf16 v[120:123], v[140:143], v[196:199], v[120:123]
	v_mfma_f32_16x16x32_bf16 v[108:111], v[132:135], v[204:207], v[108:111]
	v_mfma_f32_16x16x32_bf16 v[104:107], v[140:143], v[204:207], v[104:107]
	v_mfma_f32_16x16x32_bf16 v[92:95], v[132:135], v[212:215], v[92:95]
	v_mfma_f32_16x16x32_bf16 v[88:91], v[140:143], v[212:215], v[88:91]
	v_mfma_f32_16x16x32_bf16 v[76:79], v[132:135], v[220:223], v[76:79]
	v_mfma_f32_16x16x32_bf16 v[72:75], v[140:143], v[220:223], v[72:75]
	s_setprio 0
	s_setprio 1
	v_mfma_f32_16x16x32_bf16 v[116:119], v[160:163], v[192:195], v[116:119]
	v_mfma_f32_16x16x32_bf16 v[112:115], v[184:187], v[192:195], v[112:115]
	v_mfma_f32_16x16x32_bf16 v[100:103], v[160:163], v[200:203], v[100:103]
	v_mfma_f32_16x16x32_bf16 v[96:99], v[184:187], v[200:203], v[96:99]
	v_mfma_f32_16x16x32_bf16 v[84:87], v[160:163], v[208:211], v[84:87]
	v_mfma_f32_16x16x32_bf16 v[80:83], v[184:187], v[208:211], v[80:83]
	v_mfma_f32_16x16x32_bf16 v[68:71], v[160:163], v[216:219], v[68:71]
	v_mfma_f32_16x16x32_bf16 v[64:67], v[184:187], v[216:219], v[64:67]
	v_mfma_f32_16x16x32_bf16 v[116:119], v[164:167], v[196:199], v[116:119]
	v_mfma_f32_16x16x32_bf16 v[112:115], v[188:191], v[196:199], v[112:115]
	v_mfma_f32_16x16x32_bf16 v[100:103], v[164:167], v[204:207], v[100:103]
	v_mfma_f32_16x16x32_bf16 v[96:99], v[188:191], v[204:207], v[96:99]
	v_mfma_f32_16x16x32_bf16 v[84:87], v[164:167], v[212:215], v[84:87]
	v_mfma_f32_16x16x32_bf16 v[80:83], v[188:191], v[212:215], v[80:83]
	s_barrier
; #define PG8_STAGE(bufoff, gbase, voff) do { _Pragma("unroll") for (int _i = 0; _i < 2; ++_i) \
;         __builtin_amdgcn_global_load_lds((const unsigned*)((const char*)(gbase) + (voff)[_i]), (PG8_LAS unsigned*)(lds + (bufoff) + ldsw + _i * 8192), 16, 0, 0); } while (0)
; #define PG8_LDA(dst, b, h) do { _Pragma("unroll") for (int m = 0; m < 4; ++m) _Pragma("unroll") for (int k = 0; k < 2; ++k) dst[m][k] = *(const PG8_LAS bf16x8*)(lds + PG8_SA(b, h) + aoff + m * 2048 + k * 1024); } while (0)
; #define PG8_MMA(ai, bj, At, Bt) do { __builtin_amdgcn_s_setprio(1); _Pragma("unroll") for (int m = 0; m < 4; ++m) _Pragma("unroll") for (int n = 0; n < 2; ++n) _Pragma("unroll") for (int k = 0; k < 2; ++k) \
;         acc[ai][bj][m][n] = __builtin_amdgcn_mfma_f32_16x16x32_bf16(Bt[n][k], At[m][k], acc[ai][bj][m][n], 0, 0, 0); __builtin_amdgcn_s_setprio(0); } while (0)
; #define PG8_WAIT_V(n) asm volatile("s_waitcnt vmcnt(" #n ")" ::: "memory")
; #define PG8_WAIT_L(n) asm volatile("s_waitcnt lgkmcnt(" #n ")" ::: "memory")
; #define PG8_BAR __builtin_amdgcn_s_barrier()
; #define PG8_SCHED __builtin_amdgcn_sched_barrier(0)
; template <class Epi, class Sched, bool ALIGN_EPI = false, bool SP2 = false>
; __device__ __forceinline__ void gemm_phase(PG8_LAS unsigned char* lds, const Gemm g, const Sched& S, const Epi& E) {
;     ...
;             PG8_WAIT_V(8); PG8_WAIT_L(0); PG8_BAR; PG8_MMA(0, 0, At, B0); PG8_MMA(0, 1, At, B1); PG8_BAR; PG8_SCHED;
;             PG8_LDA(At, 1, 1); PG8_STAGE(PG8_SB(1, 0), b3, voffB); PG8_STAGE(PG8_SB(1, 1), b3 + hstep, voffB); PG8_STAGE(PG8_SA(1, 0), a3, voffA);
;             PG8_WAIT_V(8); PG8_WAIT_L(0); PG8_BAR; PG8_MMA(1, 0, At, B0); PG8_MMA(1, 1, At, B1); PG8_BAR; PG8_SCHED;
;     ...
;         if constexpr (ALIGN_EPI) { if (wr == 0) PG8_BAR; }
	v_mfma_f32_16x16x32_bf16 v[68:71], v[164:167], v[220:223], v[68:71]
	v_mfma_f32_16x16x32_bf16 v[64:67], v[188:191], v[220:223], v[64:67]
	s_setprio 0
	s_add_i32 s52, s56, s78
	v_lshl_add_u64 v[168:169], v[168:169], 0, s[40:41]
	s_mov_b32 m0, s52
	ds_read_b128 v[192:195], v182 offset:49152
	ds_read_b128 v[196:199], v182 offset:50176
	ds_read_b128 v[200:203], v182 offset:51200
	ds_read_b128 v[204:207], v182 offset:52224
	ds_read_b128 v[208:211], v182 offset:53248
	ds_read_b128 v[212:215], v182 offset:54272
	ds_read_b128 v[216:219], v182 offset:55296
	ds_read_b128 v[220:223], v182 offset:56320
	global_load_lds_dwordx4 v[168:169], off
	s_add_i32 m0, s52, 0x2000
	s_add_u32 s52, s74, 0x80080
	v_lshl_add_u64 v[168:169], v[224:225], 0, s[40:41]
	s_addc_u32 s53, s75, 0
	s_add_i32 s56, s57, s78
	global_load_lds_dwordx4 v[168:169], off
	v_lshl_add_u64 v[168:169], s[52:53], 0, v[148:149]
	s_mov_b32 m0, s56
	s_nop 0
	global_load_lds_dwordx4 v[168:169], off
	v_lshl_add_u64 v[168:169], s[52:53], 0, v[152:153]
	s_add_i32 m0, s56, 0x2000
	s_nop 0
	global_load_lds_dwordx4 v[168:169], off
	v_lshl_add_u64 v[168:169], v[226:227], 0, s[40:41]
	s_mov_b32 m0, s3
	s_nop 0
	global_load_lds_dwordx4 v[168:169], off
	v_lshl_add_u64 v[168:169], v[228:229], 0, s[40:41]
	s_mov_b32 m0, s28
	s_nop 0
	global_load_lds_dwordx4 v[168:169], off
	s_waitcnt vmcnt(8)
	s_waitcnt lgkmcnt(0)
	s_barrier
	s_setprio 1
	s_waitcnt lgkmcnt(0)
	v_mfma_f32_16x16x32_bf16 v[60:63], v[128:131], v[192:195], v[60:63]
	v_mfma_f32_16x16x32_bf16 v[56:59], v[136:139], v[192:195], v[56:59]
	v_mfma_f32_16x16x32_bf16 v[44:47], v[128:131], v[200:203], v[44:47]
	v_mfma_f32_16x16x32_bf16 v[40:43], v[136:139], v[200:203], v[40:43]
	v_mfma_f32_16x16x32_bf16 v[28:31], v[128:131], v[208:211], v[28:31]
	v_mfma_f32_16x16x32_bf16 v[24:27], v[136:139], v[208:211], v[24:27]
	v_mfma_f32_16x16x32_bf16 v[12:15], v[128:131], v[216:219], v[12:15]
	v_mfma_f32_16x16x32_bf16 v[8:11], v[136:139], v[216:219], v[8:11]
	v_mfma_f32_16x16x32_bf16 v[60:63], v[132:135], v[196:199], v[60:63]
	v_mfma_f32_16x16x32_bf16 v[56:59], v[140:143], v[196:199], v[56:59]
	v_mfma_f32_16x16x32_bf16 v[44:47], v[132:135], v[204:207], v[44:47]
	v_mfma_f32_16x16x32_bf16 v[40:43], v[140:143], v[204:207], v[40:43]
	v_mfma_f32_16x16x32_bf16 v[28:31], v[132:135], v[212:215], v[28:31]
	v_mfma_f32_16x16x32_bf16 v[24:27], v[140:143], v[212:215], v[24:27]
	v_mfma_f32_16x16x32_bf16 v[12:15], v[132:135], v[220:223], v[12:15]
	v_mfma_f32_16x16x32_bf16 v[8:11], v[140:143], v[220:223], v[8:11]
	s_setprio 0
	s_setprio 1
	v_mfma_f32_16x16x32_bf16 v[52:55], v[160:163], v[192:195], v[52:55]
	v_mfma_f32_16x16x32_bf16 v[48:51], v[184:187], v[192:195], v[48:51]
	v_mfma_f32_16x16x32_bf16 v[36:39], v[160:163], v[200:203], v[36:39]
	v_mfma_f32_16x16x32_bf16 v[32:35], v[184:187], v[200:203], v[32:35]
	v_mfma_f32_16x16x32_bf16 v[20:23], v[160:163], v[208:211], v[20:23]
	v_mfma_f32_16x16x32_bf16 v[16:19], v[184:187], v[208:211], v[16:19]
	v_mfma_f32_16x16x32_bf16 v[4:7], v[160:163], v[216:219], v[4:7]
	v_mfma_f32_16x16x32_bf16 v[0:3], v[184:187], v[216:219], v[0:3]
	v_mfma_f32_16x16x32_bf16 v[52:55], v[164:167], v[196:199], v[52:55]
	v_mfma_f32_16x16x32_bf16 v[48:51], v[188:191], v[196:199], v[48:51]
	v_mfma_f32_16x16x32_bf16 v[36:39], v[164:167], v[204:207], v[36:39]
	v_mfma_f32_16x16x32_bf16 v[32:35], v[188:191], v[204:207], v[32:35]
	v_mfma_f32_16x16x32_bf16 v[20:23], v[164:167], v[212:215], v[20:23]
	v_mfma_f32_16x16x32_bf16 v[16:19], v[188:191], v[212:215], v[16:19]
	s_barrier
	v_mfma_f32_16x16x32_bf16 v[4:7], v[164:167], v[220:223], v[4:7]
	v_mfma_f32_16x16x32_bf16 v[0:3], v[188:191], v[220:223], v[0:3]
	s_setprio 0
	s_add_i32 s92, s92, 2
	s_add_u32 s72, s72, 0x100
	s_addc_u32 s73, s73, 0
	s_add_u32 s90, s90, 0x100
	s_addc_u32 s91, s91, 0
	s_cmp_gt_u32 s92, 29
	s_cbranch_scc0 .LBB0_809
	s_and_b64 vcc, exec, s[42:43]
	s_cbranch_vccz .LBB0_812
	s_barrier

; #define PG8_STAGE(bufoff, gbase, voff) do { _Pragma("unroll") for (int _i = 0; _i < 2; ++_i) \
;         __builtin_amdgcn_global_load_lds((const unsigned*)((const char*)(gbase) + (voff)[_i]), (PG8_LAS unsigned*)(lds + (bufoff) + ldsw + _i * 8192), 16, 0, 0); } while (0)
; #define PG8_LDA(dst, b, h) do { _Pragma("unroll") for (int m = 0; m < 4; ++m) _Pragma("unroll") for (int k = 0; k < 2; ++k) dst[m][k] = *(const PG8_LAS bf16x8*)(lds + PG8_SA(b, h) + aoff + m * 2048 + k * 1024); } while (0)
; #define PG8_LDB(dst, b, h) do { _Pragma("unroll") for (int n = 0; n < 2; ++n) _Pragma("unroll") for (int k = 0; k < 2; ++k) dst[n][k] = *(const PG8_LAS bf16x8*)(lds + PG8_SB(b, h) + boff + n * 2048 + k * 1024); } while (0)
; #define PG8_MMA(ai, bj, At, Bt) do { __builtin_amdgcn_s_setprio(1); _Pragma("unroll") for (int m = 0; m < 4; ++m) _Pragma("unroll") for (int n = 0; n < 2; ++n) _Pragma("unroll") for (int k = 0; k < 2; ++k) \
;         acc[ai][bj][m][n] = __builtin_amdgcn_mfma_f32_16x16x32_bf16(Bt[n][k], At[m][k], acc[ai][bj][m][n], 0, 0, 0); __builtin_amdgcn_s_setprio(0); } while (0)
; #define PG8_WAIT_V(n) asm volatile("s_waitcnt vmcnt(" #n ")" ::: "memory")
; #define PG8_WAIT_L(n) asm volatile("s_waitcnt lgkmcnt(" #n ")" ::: "memory")
; #define PG8_BAR __builtin_amdgcn_s_barrier()
; #define PG8_SCHED __builtin_amdgcn_sched_barrier(0)
; template <class Epi, class Sched, bool ALIGN_EPI = false, bool SP2 = false>
; __device__ __forceinline__ void gemm_phase(PG8_LAS unsigned char* lds, const Gemm g, const Sched& S, const Epi& E) {
;     ...
;         for (int t = 0; t < nt; t += 2) {
;             const bool last = (t == nt - 2);
;             const char* a1 = cA + (size_t)(t + 1) * kstep;
;             const char* a2 = last ? nA : cA + (size_t)(t + 2) * kstep; const char* b2 = last ? nB : cB + (size_t)(t + 2) * kstep;
;             const char* a3 = a2 + kstep; const char* b3 = b2 + kstep;
;             if constexpr (SP2) {
;             PG8_LDB(B0, 0, 0); PG8_LDB(B1, 0, 1); PG8_SCHED; PG8_LDA(At, 0, 0); PG8_STAGE(PG8_SA(1, 1), a1 + hstep, voffA);
;             PG8_WAIT_V(8); PG8_WAIT_L(0); PG8_BAR; PG8_MMA(0, 0, At, B0); PG8_MMA(0, 1, At, B1); PG8_BAR; PG8_SCHED;
.LBB0_1051:
	ds_read_b128 v[128:131], v205
	ds_read_b128 v[132:135], v205 offset:1024
	ds_read_b128 v[154:157], v205 offset:2048
	ds_read_b128 v[158:161], v205 offset:3072
	ds_read_b128 v[162:165], v206
	ds_read_b128 v[166:169], v206 offset:1024
	ds_read_b128 v[170:173], v206 offset:2048
	ds_read_b128 v[174:177], v206 offset:3072
	s_add_u32 s54, s52, 0xfff80080
	s_addc_u32 s55, s53, -1
	s_cmp_eq_u32 s77, 28
	s_cselect_b32 s57, s43, s55
	s_cselect_b32 s56, s49, s54
	s_cselect_b32 s55, s37, s76
	s_cselect_b32 s54, s51, s75
	v_lshl_add_u64 v[218:219], s[52:53], 0, v[144:145]
	s_add_i32 m0, s61, 0xc000
	ds_read_b128 v[178:181], v207
	ds_read_b128 v[182:185], v207 offset:1024
	ds_read_b128 v[186:189], v207 offset:2048
	ds_read_b128 v[190:193], v207 offset:3072
	ds_read_b128 v[194:197], v207 offset:4096
	ds_read_b128 v[198:201], v207 offset:5120
	ds_read_b128 v[210:213], v207 offset:6144
	ds_read_b128 v[214:217], v207 offset:7168
	global_load_lds_dwordx4 v[218:219], off
	v_lshl_add_u64 v[218:219], s[52:53], 0, v[148:149]
	s_add_i32 m0, s61, 0xe000
	s_nop 0
	global_load_lds_dwordx4 v[218:219], off
	s_waitcnt vmcnt(8)
	s_waitcnt lgkmcnt(0)
	s_barrier
	s_setprio 1
	s_waitcnt lgkmcnt(0)
	v_mfma_f32_16x16x32_bf16 v[124:127], v[128:131], v[178:181], v[124:127]
	v_mfma_f32_16x16x32_bf16 v[120:123], v[154:157], v[178:181], v[120:123]
	v_mfma_f32_16x16x32_bf16 v[116:119], v[128:131], v[186:189], v[116:119]
	v_mfma_f32_16x16x32_bf16 v[112:115], v[154:157], v[186:189], v[112:115]
	v_mfma_f32_16x16x32_bf16 v[108:111], v[128:131], v[194:197], v[108:111]
	v_mfma_f32_16x16x32_bf16 v[104:107], v[154:157], v[194:197], v[104:107]
	v_mfma_f32_16x16x32_bf16 v[100:103], v[128:131], v[210:213], v[100:103]
	v_mfma_f32_16x16x32_bf16 v[96:99], v[154:157], v[210:213], v[96:99]
	v_mfma_f32_16x16x32_bf16 v[124:127], v[132:135], v[182:185], v[124:127]
	v_mfma_f32_16x16x32_bf16 v[120:123], v[158:161], v[182:185], v[120:123]
	v_mfma_f32_16x16x32_bf16 v[116:119], v[132:135], v[190:193], v[116:119]
	v_mfma_f32_16x16x32_bf16 v[112:115], v[158:161], v[190:193], v[112:115]
	v_mfma_f32_16x16x32_bf16 v[108:111], v[132:135], v[198:201], v[108:111]
	v_mfma_f32_16x16x32_bf16 v[104:107], v[158:161], v[198:201], v[104:107]
	v_mfma_f32_16x16x32_bf16 v[100:103], v[132:135], v[214:217], v[100:103]
	v_mfma_f32_16x16x32_bf16 v[96:99], v[158:161], v[214:217], v[96:99]
	s_setprio 0
	s_setprio 1
	v_mfma_f32_16x16x32_bf16 v[60:63], v[162:165], v[178:181], v[60:63]
	v_mfma_f32_16x16x32_bf16 v[56:59], v[170:173], v[178:181], v[56:59]
	v_mfma_f32_16x16x32_bf16 v[52:55], v[162:165], v[186:189], v[52:55]
	v_mfma_f32_16x16x32_bf16 v[48:51], v[170:173], v[186:189], v[48:51]
	v_mfma_f32_16x16x32_bf16 v[44:47], v[162:165], v[194:197], v[44:47]
	v_mfma_f32_16x16x32_bf16 v[40:43], v[170:173], v[194:197], v[40:43]
	v_mfma_f32_16x16x32_bf16 v[36:39], v[162:165], v[210:213], v[36:39]
	v_mfma_f32_16x16x32_bf16 v[32:35], v[170:173], v[210:213], v[32:35]
	v_mfma_f32_16x16x32_bf16 v[60:63], v[166:169], v[182:185], v[60:63]
	v_mfma_f32_16x16x32_bf16 v[56:59], v[174:177], v[182:185], v[56:59]
	v_mfma_f32_16x16x32_bf16 v[52:55], v[166:169], v[190:193], v[52:55]
	v_mfma_f32_16x16x32_bf16 v[48:51], v[174:177], v[190:193], v[48:51]
	v_mfma_f32_16x16x32_bf16 v[44:47], v[166:169], v[198:201], v[44:47]
	v_mfma_f32_16x16x32_bf16 v[40:43], v[174:177], v[198:201], v[40:43]
	s_barrier
	v_mfma_f32_16x16x32_bf16 v[36:39], v[166:169], v[214:217], v[36:39]
	v_mfma_f32_16x16x32_bf16 v[32:35], v[174:177], v[214:217], v[32:35]
	s_setprio 0
	s_add_i32 s78, s33, s60
	v_lshl_add_u64 v[218:219], s[54:55], 0, v[138:139]
	s_mov_b32 m0, s78
	ds_read_b128 v[178:181], v207 offset:16384
	ds_read_b128 v[182:185], v207 offset:17408
	ds_read_b128 v[186:189], v207 offset:18432
	ds_read_b128 v[190:193], v207 offset:19456
	ds_read_b128 v[194:197], v207 offset:20480
	ds_read_b128 v[198:201], v207 offset:21504
	ds_read_b128 v[210:213], v207 offset:22528
	ds_read_b128 v[214:217], v207 offset:23552
	global_load_lds_dwordx4 v[218:219], off
	s_add_i32 m0, s78, 0x2000
	s_add_u32 s78, s54, 0x80000
	v_lshl_add_u64 v[220:221], s[54:55], 0, v[142:143]
	s_addc_u32 s79, s55, 0
	s_add_i32 s80, s74, s60
	global_load_lds_dwordx4 v[220:221], off
	v_lshl_add_u64 v[222:223], s[78:79], 0, v[138:139]
	s_mov_b32 m0, s80
	v_lshl_add_u64 v[224:225], s[56:57], 0, v[140:141]
	global_load_lds_dwordx4 v[222:223], off
	v_lshl_add_u64 v[222:223], s[78:79], 0, v[142:143]
	s_add_i32 m0, s80, 0x2000
	s_nop 0
	global_load_lds_dwordx4 v[222:223], off
	v_lshl_add_u64 v[222:223], s[56:57], 0, v[136:137]
	s_mov_b32 m0, s61
	s_nop 0
	global_load_lds_dwordx4 v[222:223], off
	s_mov_b32 m0, s62
	s_nop 0
	global_load_lds_dwordx4 v[224:225], off
	s_waitcnt vmcnt(8)
	s_waitcnt lgkmcnt(0)
	s_barrier
; #define PG8_STAGE(bufoff, gbase, voff) do { _Pragma("unroll") for (int _i = 0; _i < 2; ++_i) \
;         __builtin_amdgcn_global_load_lds((const unsigned*)((const char*)(gbase) + (voff)[_i]), (PG8_LAS unsigned*)(lds + (bufoff) + ldsw + _i * 8192), 16, 0, 0); } while (0)
; #define PG8_LDA(dst, b, h) do { _Pragma("unroll") for (int m = 0; m < 4; ++m) _Pragma("unroll") for (int k = 0; k < 2; ++k) dst[m][k] = *(const PG8_LAS bf16x8*)(lds + PG8_SA(b, h) + aoff + m * 2048 + k * 1024); } while (0)
; #define PG8_LDB(dst, b, h) do { _Pragma("unroll") for (int n = 0; n < 2; ++n) _Pragma("unroll") for (int k = 0; k < 2; ++k) dst[n][k] = *(const PG8_LAS bf16x8*)(lds + PG8_SB(b, h) + boff + n * 2048 + k * 1024); } while (0)
; #define PG8_MMA(ai, bj, At, Bt) do { __builtin_amdgcn_s_setprio(1); _Pragma("unroll") for (int m = 0; m < 4; ++m) _Pragma("unroll") for (int n = 0; n < 2; ++n) _Pragma("unroll") for (int k = 0; k < 2; ++k) \
;         acc[ai][bj][m][n] = __builtin_amdgcn_mfma_f32_16x16x32_bf16(Bt[n][k], At[m][k], acc[ai][bj][m][n], 0, 0, 0); __builtin_amdgcn_s_setprio(0); } while (0)
; #define PG8_WAIT_V(n) asm volatile("s_waitcnt vmcnt(" #n ")" ::: "memory")
; #define PG8_WAIT_L(n) asm volatile("s_waitcnt lgkmcnt(" #n ")" ::: "memory")
; #define PG8_BAR __builtin_amdgcn_s_barrier()
; #define PG8_SCHED __builtin_amdgcn_sched_barrier(0)
; template <class Epi, class Sched, bool ALIGN_EPI = false, bool SP2 = false>
; __device__ __forceinline__ void gemm_phase(PG8_LAS unsigned char* lds, const Gemm g, const Sched& S, const Epi& E) {
;     ...
;             PG8_WAIT_V(8); PG8_WAIT_L(0); PG8_BAR; PG8_MMA(1, 0, At, B0); PG8_MMA(1, 1, At, B1); PG8_BAR; PG8_SCHED;
;             PG8_LDB(B0, 1, 0); PG8_LDB(B1, 1, 1); PG8_SCHED; PG8_LDA(At, 1, 0); PG8_STAGE(PG8_SA(0, 1), a2 + hstep, voffA);
;             PG8_WAIT_V(8); PG8_WAIT_L(0); PG8_BAR; PG8_MMA(0, 0, At, B0); PG8_MMA(0, 1, At, B1); PG8_BAR; PG8_SCHED;
	s_setprio 1
	s_waitcnt lgkmcnt(0)
	v_mfma_f32_16x16x32_bf16 v[92:95], v[128:131], v[178:181], v[92:95]
	v_mfma_f32_16x16x32_bf16 v[88:91], v[154:157], v[178:181], v[88:91]
	v_mfma_f32_16x16x32_bf16 v[84:87], v[128:131], v[186:189], v[84:87]
	v_mfma_f32_16x16x32_bf16 v[80:83], v[154:157], v[186:189], v[80:83]
	v_mfma_f32_16x16x32_bf16 v[76:79], v[128:131], v[194:197], v[76:79]
	v_mfma_f32_16x16x32_bf16 v[72:75], v[154:157], v[194:197], v[72:75]
	v_mfma_f32_16x16x32_bf16 v[68:71], v[128:131], v[210:213], v[68:71]
	v_mfma_f32_16x16x32_bf16 v[64:67], v[154:157], v[210:213], v[64:67]
	v_mfma_f32_16x16x32_bf16 v[92:95], v[132:135], v[182:185], v[92:95]
	v_mfma_f32_16x16x32_bf16 v[88:91], v[158:161], v[182:185], v[88:91]
	v_mfma_f32_16x16x32_bf16 v[84:87], v[132:135], v[190:193], v[84:87]
	v_mfma_f32_16x16x32_bf16 v[80:83], v[158:161], v[190:193], v[80:83]
	v_mfma_f32_16x16x32_bf16 v[76:79], v[132:135], v[198:201], v[76:79]
	v_mfma_f32_16x16x32_bf16 v[72:75], v[158:161], v[198:201], v[72:75]
	v_mfma_f32_16x16x32_bf16 v[68:71], v[132:135], v[214:217], v[68:71]
	v_mfma_f32_16x16x32_bf16 v[64:67], v[158:161], v[214:217], v[64:67]
	s_setprio 0
	s_setprio 1
	v_mfma_f32_16x16x32_bf16 v[28:31], v[162:165], v[178:181], v[28:31]
	v_mfma_f32_16x16x32_bf16 v[24:27], v[170:173], v[178:181], v[24:27]
	v_mfma_f32_16x16x32_bf16 v[20:23], v[162:165], v[186:189], v[20:23]
	v_mfma_f32_16x16x32_bf16 v[16:19], v[170:173], v[186:189], v[16:19]
	v_mfma_f32_16x16x32_bf16 v[12:15], v[162:165], v[194:197], v[12:15]
	v_mfma_f32_16x16x32_bf16 v[8:11], v[170:173], v[194:197], v[8:11]
	v_mfma_f32_16x16x32_bf16 v[4:7], v[162:165], v[210:213], v[4:7]
	v_mfma_f32_16x16x32_bf16 v[0:3], v[170:173], v[210:213], v[0:3]
	v_mfma_f32_16x16x32_bf16 v[28:31], v[166:169], v[182:185], v[28:31]
	v_mfma_f32_16x16x32_bf16 v[24:27], v[174:177], v[182:185], v[24:27]
	v_mfma_f32_16x16x32_bf16 v[20:23], v[166:169], v[190:193], v[20:23]
	v_mfma_f32_16x16x32_bf16 v[16:19], v[174:177], v[190:193], v[16:19]
	v_mfma_f32_16x16x32_bf16 v[12:15], v[166:169], v[198:201], v[12:15]
	v_mfma_f32_16x16x32_bf16 v[8:11], v[174:177], v[198:201], v[8:11]
	s_barrier
	v_mfma_f32_16x16x32_bf16 v[4:7], v[166:169], v[214:217], v[4:7]
	v_mfma_f32_16x16x32_bf16 v[0:3], v[174:177], v[214:217], v[0:3]
	s_setprio 0
	s_add_i32 s78, 0, 0x18000
	s_add_i32 s79, 0, 0x1c000
	v_add_u32_e32 v158, s78, v203
	v_add_u32_e32 v174, s79, v203
	ds_read_b128 v[128:131], v158
	ds_read_b128 v[132:135], v158 offset:1024
	ds_read_b128 v[154:157], v158 offset:2048
	ds_read_b128 v[158:161], v158 offset:3072
	ds_read_b128 v[162:165], v174
	ds_read_b128 v[166:169], v174 offset:1024
	ds_read_b128 v[170:173], v174 offset:2048
	ds_read_b128 v[174:177], v174 offset:3072
	s_add_u32 s56, s56, 0x80000
	s_addc_u32 s57, s57, 0
	s_mov_b32 m0, s63
	v_lshl_add_u64 v[226:227], s[56:57], 0, v[136:137]
	ds_read_b128 v[178:181], v207 offset:32768
	ds_read_b128 v[182:185], v207 offset:33792
	ds_read_b128 v[186:189], v207 offset:34816
	ds_read_b128 v[190:193], v207 offset:35840
	ds_read_b128 v[194:197], v207 offset:36864
	ds_read_b128 v[198:201], v207 offset:37888
	ds_read_b128 v[210:213], v207 offset:38912
	ds_read_b128 v[214:217], v207 offset:39936
	global_load_lds_dwordx4 v[226:227], off
	v_lshl_add_u64 v[226:227], s[56:57], 0, v[140:141]
	s_mov_b32 m0, s64
	s_nop 0
	global_load_lds_dwordx4 v[226:227], off
	s_waitcnt vmcnt(8)
	s_waitcnt lgkmcnt(0)
	s_barrier
	s_setprio 1
	s_waitcnt lgkmcnt(0)
	v_mfma_f32_16x16x32_bf16 v[124:127], v[128:131], v[178:181], v[124:127]
	v_mfma_f32_16x16x32_bf16 v[120:123], v[154:157], v[178:181], v[120:123]
	v_mfma_f32_16x16x32_bf16 v[116:119], v[128:131], v[186:189], v[116:119]
	v_mfma_f32_16x16x32_bf16 v[112:115], v[154:157], v[186:189], v[112:115]
	v_mfma_f32_16x16x32_bf16 v[108:111], v[128:131], v[194:197], v[108:111]
	v_mfma_f32_16x16x32_bf16 v[104:107], v[154:157], v[194:197], v[104:107]
	v_mfma_f32_16x16x32_bf16 v[100:103], v[128:131], v[210:213], v[100:103]
	v_mfma_f32_16x16x32_bf16 v[96:99], v[154:157], v[210:213], v[96:99]
	v_mfma_f32_16x16x32_bf16 v[124:127], v[132:135], v[182:185], v[124:127]
	v_mfma_f32_16x16x32_bf16 v[120:123], v[158:161], v[182:185], v[120:123]
	v_mfma_f32_16x16x32_bf16 v[116:119], v[132:135], v[190:193], v[116:119]
	v_mfma_f32_16x16x32_bf16 v[112:115], v[158:161], v[190:193], v[112:115]
	v_mfma_f32_16x16x32_bf16 v[108:111], v[132:135], v[198:201], v[108:111]
	v_mfma_f32_16x16x32_bf16 v[104:107], v[158:161], v[198:201], v[104:107]
	v_mfma_f32_16x16x32_bf16 v[100:103], v[132:135], v[214:217], v[100:103]
	v_mfma_f32_16x16x32_bf16 v[96:99], v[158:161], v[214:217], v[96:99]
	s_setprio 0
	s_setprio 1
	v_mfma_f32_16x16x32_bf16 v[60:63], v[162:165], v[178:181], v[60:63]
	v_mfma_f32_16x16x32_bf16 v[56:59], v[170:173], v[178:181], v[56:59]
	v_mfma_f32_16x16x32_bf16 v[52:55], v[162:165], v[186:189], v[52:55]
	v_mfma_f32_16x16x32_bf16 v[48:51], v[170:173], v[186:189], v[48:51]
	v_mfma_f32_16x16x32_bf16 v[44:47], v[162:165], v[194:197], v[44:47]
	v_mfma_f32_16x16x32_bf16 v[40:43], v[170:173], v[194:197], v[40:43]
	v_mfma_f32_16x16x32_bf16 v[36:39], v[162:165], v[210:213], v[36:39]
	v_mfma_f32_16x16x32_bf16 v[32:35], v[170:173], v[210:213], v[32:35]
	v_mfma_f32_16x16x32_bf16 v[60:63], v[166:169], v[182:185], v[60:63]
	v_mfma_f32_16x16x32_bf16 v[56:59], v[174:177], v[182:185], v[56:59]
	v_mfma_f32_16x16x32_bf16 v[52:55], v[166:169], v[190:193], v[52:55]
	v_mfma_f32_16x16x32_bf16 v[48:51], v[174:177], v[190:193], v[48:51]
	v_mfma_f32_16x16x32_bf16 v[44:47], v[166:169], v[198:201], v[44:47]
	v_mfma_f32_16x16x32_bf16 v[40:43], v[174:177], v[198:201], v[40:43]
	s_barrier
; #define PG8_STAGE(bufoff, gbase, voff) do { _Pragma("unroll") for (int _i = 0; _i < 2; ++_i) \
;         __builtin_amdgcn_global_load_lds((const unsigned*)((const char*)(gbase) + (voff)[_i]), (PG8_LAS unsigned*)(lds + (bufoff) + ldsw + _i * 8192), 16, 0, 0); } while (0)
; #define PG8_LDA(dst, b, h) do { _Pragma("unroll") for (int m = 0; m < 4; ++m) _Pragma("unroll") for (int k = 0; k < 2; ++k) dst[m][k] = *(const PG8_LAS bf16x8*)(lds + PG8_SA(b, h) + aoff + m * 2048 + k * 1024); } while (0)
; #define PG8_MMA(ai, bj, At, Bt) do { __builtin_amdgcn_s_setprio(1); _Pragma("unroll") for (int m = 0; m < 4; ++m) _Pragma("unroll") for (int n = 0; n < 2; ++n) _Pragma("unroll") for (int k = 0; k < 2; ++k) \
;         acc[ai][bj][m][n] = __builtin_amdgcn_mfma_f32_16x16x32_bf16(Bt[n][k], At[m][k], acc[ai][bj][m][n], 0, 0, 0); __builtin_amdgcn_s_setprio(0); } while (0)
; #define PG8_WAIT_V(n) asm volatile("s_waitcnt vmcnt(" #n ")" ::: "memory")
; #define PG8_WAIT_L(n) asm volatile("s_waitcnt lgkmcnt(" #n ")" ::: "memory")
; #define PG8_BAR __builtin_amdgcn_s_barrier()
; #define PG8_SCHED __builtin_amdgcn_sched_barrier(0)
; template <class Epi, class Sched, bool ALIGN_EPI = false, bool SP2 = false>
; __device__ __forceinline__ void gemm_phase(PG8_LAS unsigned char* lds, const Gemm g, const Sched& S, const Epi& E) {
;     ...
;             PG8_WAIT_V(8); PG8_WAIT_L(0); PG8_BAR; PG8_MMA(0, 0, At, B0); PG8_MMA(0, 1, At, B1); PG8_BAR; PG8_SCHED;
;             PG8_LDA(At, 1, 1); PG8_STAGE(PG8_SB(1, 0), b3, voffB); PG8_STAGE(PG8_SB(1, 1), b3 + hstep, voffB); PG8_STAGE(PG8_SA(1, 0), a3, voffA);
;             PG8_WAIT_V(8); PG8_WAIT_L(0); PG8_BAR; PG8_MMA(1, 0, At, B0); PG8_MMA(1, 1, At, B1); PG8_BAR; PG8_SCHED;
;     ...
;         if constexpr (ALIGN_EPI) { if (wr == 0) PG8_BAR; }
	v_mfma_f32_16x16x32_bf16 v[36:39], v[166:169], v[214:217], v[36:39]
	v_mfma_f32_16x16x32_bf16 v[32:35], v[174:177], v[214:217], v[32:35]
	s_setprio 0
	s_add_i32 s56, s78, s60
	v_lshl_add_u64 v[218:219], v[218:219], 0, s[12:13]
	s_mov_b32 m0, s56
	ds_read_b128 v[178:181], v207 offset:49152
	ds_read_b128 v[182:185], v207 offset:50176
	ds_read_b128 v[186:189], v207 offset:51200
	ds_read_b128 v[190:193], v207 offset:52224
	ds_read_b128 v[194:197], v207 offset:53248
	ds_read_b128 v[198:201], v207 offset:54272
	ds_read_b128 v[210:213], v207 offset:55296
	ds_read_b128 v[214:217], v207 offset:56320
	global_load_lds_dwordx4 v[218:219], off
	s_add_i32 m0, s56, 0x2000
	s_add_u32 s54, s54, 0x80080
	v_lshl_add_u64 v[218:219], v[220:221], 0, s[12:13]
	s_addc_u32 s55, s55, 0
	s_add_i32 s56, s79, s60
	global_load_lds_dwordx4 v[218:219], off
	v_lshl_add_u64 v[218:219], s[54:55], 0, v[138:139]
	s_mov_b32 m0, s56
	s_nop 0
	global_load_lds_dwordx4 v[218:219], off
	v_lshl_add_u64 v[218:219], s[54:55], 0, v[142:143]
	s_add_i32 m0, s56, 0x2000
	s_nop 0
	global_load_lds_dwordx4 v[218:219], off
	v_lshl_add_u64 v[218:219], v[222:223], 0, s[12:13]
	s_mov_b32 m0, s70
	s_nop 0
	global_load_lds_dwordx4 v[218:219], off
	v_lshl_add_u64 v[218:219], v[224:225], 0, s[12:13]
	s_mov_b32 m0, s71
	s_nop 0
	global_load_lds_dwordx4 v[218:219], off
	s_waitcnt vmcnt(8)
	s_waitcnt lgkmcnt(0)
	s_barrier
	s_setprio 1
	s_waitcnt lgkmcnt(0)
	v_mfma_f32_16x16x32_bf16 v[92:95], v[128:131], v[178:181], v[92:95]
	v_mfma_f32_16x16x32_bf16 v[88:91], v[154:157], v[178:181], v[88:91]
	v_mfma_f32_16x16x32_bf16 v[84:87], v[128:131], v[186:189], v[84:87]
	v_mfma_f32_16x16x32_bf16 v[80:83], v[154:157], v[186:189], v[80:83]
	v_mfma_f32_16x16x32_bf16 v[76:79], v[128:131], v[194:197], v[76:79]
	v_mfma_f32_16x16x32_bf16 v[72:75], v[154:157], v[194:197], v[72:75]
	v_mfma_f32_16x16x32_bf16 v[68:71], v[128:131], v[210:213], v[68:71]
	v_mfma_f32_16x16x32_bf16 v[64:67], v[154:157], v[210:213], v[64:67]
	v_mfma_f32_16x16x32_bf16 v[92:95], v[132:135], v[182:185], v[92:95]
	v_mfma_f32_16x16x32_bf16 v[88:91], v[158:161], v[182:185], v[88:91]
	v_mfma_f32_16x16x32_bf16 v[84:87], v[132:135], v[190:193], v[84:87]
	v_mfma_f32_16x16x32_bf16 v[80:83], v[158:161], v[190:193], v[80:83]
	v_mfma_f32_16x16x32_bf16 v[76:79], v[132:135], v[198:201], v[76:79]
	v_mfma_f32_16x16x32_bf16 v[72:75], v[158:161], v[198:201], v[72:75]
	v_mfma_f32_16x16x32_bf16 v[68:71], v[132:135], v[214:217], v[68:71]
	v_mfma_f32_16x16x32_bf16 v[64:67], v[158:161], v[214:217], v[64:67]
	s_setprio 0
	s_setprio 1
	v_mfma_f32_16x16x32_bf16 v[28:31], v[162:165], v[178:181], v[28:31]
	v_mfma_f32_16x16x32_bf16 v[24:27], v[170:173], v[178:181], v[24:27]
	v_mfma_f32_16x16x32_bf16 v[20:23], v[162:165], v[186:189], v[20:23]
	v_mfma_f32_16x16x32_bf16 v[16:19], v[170:173], v[186:189], v[16:19]
	v_mfma_f32_16x16x32_bf16 v[12:15], v[162:165], v[194:197], v[12:15]
	v_mfma_f32_16x16x32_bf16 v[8:11], v[170:173], v[194:197], v[8:11]
	v_mfma_f32_16x16x32_bf16 v[4:7], v[162:165], v[210:213], v[4:7]
	v_mfma_f32_16x16x32_bf16 v[0:3], v[170:173], v[210:213], v[0:3]
	v_mfma_f32_16x16x32_bf16 v[28:31], v[166:169], v[182:185], v[28:31]
	v_mfma_f32_16x16x32_bf16 v[24:27], v[174:177], v[182:185], v[24:27]
	v_mfma_f32_16x16x32_bf16 v[20:23], v[166:169], v[190:193], v[20:23]
	v_mfma_f32_16x16x32_bf16 v[16:19], v[174:177], v[190:193], v[16:19]
	v_mfma_f32_16x16x32_bf16 v[12:15], v[166:169], v[198:201], v[12:15]
	v_mfma_f32_16x16x32_bf16 v[8:11], v[174:177], v[198:201], v[8:11]
	s_barrier
	v_mfma_f32_16x16x32_bf16 v[4:7], v[166:169], v[214:217], v[4:7]
	v_mfma_f32_16x16x32_bf16 v[0:3], v[174:177], v[214:217], v[0:3]
	s_setprio 0
	s_add_i32 s77, s77, 2
	s_add_u32 s52, s52, 0x100
	s_addc_u32 s53, s53, 0
	s_add_u32 s75, s75, 0x100
	s_addc_u32 s76, s76, 0
	s_cmp_gt_u32 s77, 29
	s_cbranch_scc0 .LBB0_1051
	s_and_b64 vcc, exec, s[14:15]
	s_cbranch_vccz .LBB0_1054
	s_barrier

; #define PG8_STAGE(bufoff, gbase, voff) do { _Pragma("unroll") for (int _i = 0; _i < 2; ++_i) \
;         __builtin_amdgcn_global_load_lds((const unsigned*)((const char*)(gbase) + (voff)[_i]), (PG8_LAS unsigned*)(lds + (bufoff) + ldsw + _i * 8192), 16, 0, 0); } while (0)
; #define PG8_LDA(dst, b, h) do { _Pragma("unroll") for (int m = 0; m < 4; ++m) _Pragma("unroll") for (int k = 0; k < 2; ++k) dst[m][k] = *(const PG8_LAS bf16x8*)(lds + PG8_SA(b, h) + aoff + m * 2048 + k * 1024); } while (0)
; #define PG8_LDB(dst, b, h) do { _Pragma("unroll") for (int n = 0; n < 2; ++n) _Pragma("unroll") for (int k = 0; k < 2; ++k) dst[n][k] = *(const PG8_LAS bf16x8*)(lds + PG8_SB(b, h) + boff + n * 2048 + k * 1024); } while (0)
; #define PG8_MMA(ai, bj, At, Bt) do { __builtin_amdgcn_s_setprio(1); _Pragma("unroll") for (int m = 0; m < 4; ++m) _Pragma("unroll") for (int n = 0; n < 2; ++n) _Pragma("unroll") for (int k = 0; k < 2; ++k) \
;         acc[ai][bj][m][n] = __builtin_amdgcn_mfma_f32_16x16x32_bf16(Bt[n][k], At[m][k], acc[ai][bj][m][n], 0, 0, 0); __builtin_amdgcn_s_setprio(0); } while (0)
; #define PG8_WAIT_V(n) asm volatile("s_waitcnt vmcnt(" #n ")" ::: "memory")
; #define PG8_WAIT_L(n) asm volatile("s_waitcnt lgkmcnt(" #n ")" ::: "memory")
; #define PG8_BAR __builtin_amdgcn_s_barrier()
; #define PG8_SCHED __builtin_amdgcn_sched_barrier(0)
; template <class Epi, class Sched, bool ALIGN_EPI = false, bool SP2 = false>
; __device__ __forceinline__ void gemm_phase(PG8_LAS unsigned char* lds, const Gemm g, const Sched& S, const Epi& E) {
;     ...
;         for (int t = 0; t < nt; t += 2) {
;             const bool last = (t == nt - 2);
;             const char* a1 = cA + (size_t)(t + 1) * kstep;
;             const char* a2 = last ? nA : cA + (size_t)(t + 2) * kstep; const char* b2 = last ? nB : cB + (size_t)(t + 2) * kstep;
;             const char* a3 = a2 + kstep; const char* b3 = b2 + kstep;
;             if constexpr (SP2) {
;             PG8_LDB(B0, 0, 0); PG8_LDB(B1, 0, 1); PG8_SCHED; PG8_LDA(At, 0, 0); PG8_STAGE(PG8_SA(1, 1), a1 + hstep, voffA);
;             PG8_WAIT_V(8); PG8_WAIT_L(0); PG8_BAR; PG8_MMA(0, 0, At, B0); PG8_MMA(0, 1, At, B1); PG8_BAR; PG8_SCHED;
.LBB0_1142:
	ds_read_b128 v[80:83], v171
	ds_read_b128 v[84:87], v171 offset:1024
	ds_read_b128 v[88:91], v171 offset:2048
	ds_read_b128 v[92:95], v171 offset:3072
	ds_read_b128 v[164:167], v172
	ds_read_b128 v[176:179], v172 offset:1024
	ds_read_b128 v[180:183], v172 offset:2048
	ds_read_b128 v[184:187], v172 offset:3072
	s_add_u32 s44, s42, 0xfff80080
	s_addc_u32 s45, s43, -1
	s_cmp_eq_u32 s64, 28
	s_cselect_b32 s47, s15, s45
	s_cselect_b32 s46, s60, s44
	s_cselect_b32 s45, s13, s63
	s_cselect_b32 s44, s61, s62
	v_lshl_add_u64 v[220:221], s[42:43], 0, v[156:157]
	s_add_i32 m0, s41, 0xc000
	ds_read_b128 v[188:191], v173
	ds_read_b128 v[192:195], v173 offset:1024
	ds_read_b128 v[196:199], v173 offset:2048
	ds_read_b128 v[200:203], v173 offset:3072
	ds_read_b128 v[204:207], v173 offset:4096
	ds_read_b128 v[208:211], v173 offset:5120
	ds_read_b128 v[212:215], v173 offset:6144
	ds_read_b128 v[216:219], v173 offset:7168
	global_load_lds_dwordx4 v[220:221], off
	v_lshl_add_u64 v[220:221], s[42:43], 0, v[158:159]
	s_add_i32 m0, s41, 0xe000
	s_nop 0
	global_load_lds_dwordx4 v[220:221], off
	s_waitcnt vmcnt(8)
	s_waitcnt lgkmcnt(0)
	s_barrier
	s_setprio 1
	s_waitcnt lgkmcnt(0)
	v_mfma_f32_16x16x32_bf16 v[140:143], v[80:83], v[188:191], v[140:143]
	v_mfma_f32_16x16x32_bf16 v[136:139], v[88:91], v[188:191], v[136:139]
	v_mfma_f32_16x16x32_bf16 v[124:127], v[80:83], v[196:199], v[124:127]
	v_mfma_f32_16x16x32_bf16 v[120:123], v[88:91], v[196:199], v[120:123]
	v_mfma_f32_16x16x32_bf16 v[108:111], v[80:83], v[204:207], v[108:111]
	v_mfma_f32_16x16x32_bf16 v[104:107], v[88:91], v[204:207], v[104:107]
	v_mfma_f32_16x16x32_bf16 v[76:79], v[80:83], v[212:215], v[76:79]
	v_mfma_f32_16x16x32_bf16 v[72:75], v[88:91], v[212:215], v[72:75]
	v_mfma_f32_16x16x32_bf16 v[140:143], v[84:87], v[192:195], v[140:143]
	v_mfma_f32_16x16x32_bf16 v[136:139], v[92:95], v[192:195], v[136:139]
	v_mfma_f32_16x16x32_bf16 v[124:127], v[84:87], v[200:203], v[124:127]
	v_mfma_f32_16x16x32_bf16 v[120:123], v[92:95], v[200:203], v[120:123]
	v_mfma_f32_16x16x32_bf16 v[108:111], v[84:87], v[208:211], v[108:111]
	v_mfma_f32_16x16x32_bf16 v[104:107], v[92:95], v[208:211], v[104:107]
	v_mfma_f32_16x16x32_bf16 v[76:79], v[84:87], v[216:219], v[76:79]
	v_mfma_f32_16x16x32_bf16 v[72:75], v[92:95], v[216:219], v[72:75]
	s_setprio 0
	s_setprio 1
	v_mfma_f32_16x16x32_bf16 v[132:135], v[164:167], v[188:191], v[132:135]
	v_mfma_f32_16x16x32_bf16 v[128:131], v[180:183], v[188:191], v[128:131]
	v_mfma_f32_16x16x32_bf16 v[116:119], v[164:167], v[196:199], v[116:119]
	v_mfma_f32_16x16x32_bf16 v[112:115], v[180:183], v[196:199], v[112:115]
	v_mfma_f32_16x16x32_bf16 v[100:103], v[164:167], v[204:207], v[100:103]
	v_mfma_f32_16x16x32_bf16 v[96:99], v[180:183], v[204:207], v[96:99]
	v_mfma_f32_16x16x32_bf16 v[68:71], v[164:167], v[212:215], v[68:71]
	v_mfma_f32_16x16x32_bf16 v[64:67], v[180:183], v[212:215], v[64:67]
	v_mfma_f32_16x16x32_bf16 v[132:135], v[176:179], v[192:195], v[132:135]
	v_mfma_f32_16x16x32_bf16 v[128:131], v[184:187], v[192:195], v[128:131]
	v_mfma_f32_16x16x32_bf16 v[116:119], v[176:179], v[200:203], v[116:119]
	v_mfma_f32_16x16x32_bf16 v[112:115], v[184:187], v[200:203], v[112:115]
	v_mfma_f32_16x16x32_bf16 v[100:103], v[176:179], v[208:211], v[100:103]
	v_mfma_f32_16x16x32_bf16 v[96:99], v[184:187], v[208:211], v[96:99]
	s_barrier
	v_mfma_f32_16x16x32_bf16 v[68:71], v[176:179], v[216:219], v[68:71]
	v_mfma_f32_16x16x32_bf16 v[64:67], v[184:187], v[216:219], v[64:67]
	s_setprio 0
	s_add_i32 s65, s56, s33
	v_lshl_add_u64 v[220:221], s[44:45], 0, v[148:149]
	s_mov_b32 m0, s65
	ds_read_b128 v[188:191], v173 offset:16384
	ds_read_b128 v[192:195], v173 offset:17408
	ds_read_b128 v[196:199], v173 offset:18432
	ds_read_b128 v[200:203], v173 offset:19456
	ds_read_b128 v[204:207], v173 offset:20480
	ds_read_b128 v[208:211], v173 offset:21504
	ds_read_b128 v[212:215], v173 offset:22528
	ds_read_b128 v[216:219], v173 offset:23552
	global_load_lds_dwordx4 v[220:221], off
	s_add_i32 m0, s65, 0x2000
	s_add_u32 s66, s44, 0x80000
	v_lshl_add_u64 v[222:223], s[44:45], 0, v[152:153]
	s_addc_u32 s67, s45, 0
	s_add_i32 s65, s57, s33
	global_load_lds_dwordx4 v[222:223], off
	v_lshl_add_u64 v[224:225], s[66:67], 0, v[148:149]
	s_mov_b32 m0, s65
	v_lshl_add_u64 v[226:227], s[46:47], 0, v[150:151]
	global_load_lds_dwordx4 v[224:225], off
	v_lshl_add_u64 v[224:225], s[66:67], 0, v[152:153]
	s_add_i32 m0, s65, 0x2000
	s_nop 0
	global_load_lds_dwordx4 v[224:225], off
	v_lshl_add_u64 v[224:225], s[46:47], 0, v[144:145]
	s_mov_b32 m0, s41
	s_nop 0
	global_load_lds_dwordx4 v[224:225], off
	s_mov_b32 m0, s48
	s_nop 0
	global_load_lds_dwordx4 v[226:227], off
	s_waitcnt vmcnt(8)
	s_waitcnt lgkmcnt(0)
	s_barrier
; #define PG8_STAGE(bufoff, gbase, voff) do { _Pragma("unroll") for (int _i = 0; _i < 2; ++_i) \
;         __builtin_amdgcn_global_load_lds((const unsigned*)((const char*)(gbase) + (voff)[_i]), (PG8_LAS unsigned*)(lds + (bufoff) + ldsw + _i * 8192), 16, 0, 0); } while (0)
; #define PG8_LDA(dst, b, h) do { _Pragma("unroll") for (int m = 0; m < 4; ++m) _Pragma("unroll") for (int k = 0; k < 2; ++k) dst[m][k] = *(const PG8_LAS bf16x8*)(lds + PG8_SA(b, h) + aoff + m * 2048 + k * 1024); } while (0)
; #define PG8_LDB(dst, b, h) do { _Pragma("unroll") for (int n = 0; n < 2; ++n) _Pragma("unroll") for (int k = 0; k < 2; ++k) dst[n][k] = *(const PG8_LAS bf16x8*)(lds + PG8_SB(b, h) + boff + n * 2048 + k * 1024); } while (0)
; #define PG8_MMA(ai, bj, At, Bt) do { __builtin_amdgcn_s_setprio(1); _Pragma("unroll") for (int m = 0; m < 4; ++m) _Pragma("unroll") for (int n = 0; n < 2; ++n) _Pragma("unroll") for (int k = 0; k < 2; ++k) \
;         acc[ai][bj][m][n] = __builtin_amdgcn_mfma_f32_16x16x32_bf16(Bt[n][k], At[m][k], acc[ai][bj][m][n], 0, 0, 0); __builtin_amdgcn_s_setprio(0); } while (0)
; #define PG8_WAIT_V(n) asm volatile("s_waitcnt vmcnt(" #n ")" ::: "memory")
; #define PG8_WAIT_L(n) asm volatile("s_waitcnt lgkmcnt(" #n ")" ::: "memory")
; #define PG8_BAR __builtin_amdgcn_s_barrier()
; #define PG8_SCHED __builtin_amdgcn_sched_barrier(0)
; template <class Epi, class Sched, bool ALIGN_EPI = false, bool SP2 = false>
; __device__ __forceinline__ void gemm_phase(PG8_LAS unsigned char* lds, const Gemm g, const Sched& S, const Epi& E) {
;     ...
;             PG8_WAIT_V(8); PG8_WAIT_L(0); PG8_BAR; PG8_MMA(1, 0, At, B0); PG8_MMA(1, 1, At, B1); PG8_BAR; PG8_SCHED;
;             PG8_LDB(B0, 1, 0); PG8_LDB(B1, 1, 1); PG8_SCHED; PG8_LDA(At, 1, 0); PG8_STAGE(PG8_SA(0, 1), a2 + hstep, voffA);
;             PG8_WAIT_V(8); PG8_WAIT_L(0); PG8_BAR; PG8_MMA(0, 0, At, B0); PG8_MMA(0, 1, At, B1); PG8_BAR; PG8_SCHED;
	s_setprio 1
	s_waitcnt lgkmcnt(0)
	v_mfma_f32_16x16x32_bf16 v[60:63], v[80:83], v[188:191], v[60:63]
	v_mfma_f32_16x16x32_bf16 v[56:59], v[88:91], v[188:191], v[56:59]
	v_mfma_f32_16x16x32_bf16 v[44:47], v[80:83], v[196:199], v[44:47]
	v_mfma_f32_16x16x32_bf16 v[40:43], v[88:91], v[196:199], v[40:43]
	v_mfma_f32_16x16x32_bf16 v[28:31], v[80:83], v[204:207], v[28:31]
	v_mfma_f32_16x16x32_bf16 v[24:27], v[88:91], v[204:207], v[24:27]
	v_mfma_f32_16x16x32_bf16 v[12:15], v[80:83], v[212:215], v[12:15]
	v_mfma_f32_16x16x32_bf16 v[8:11], v[88:91], v[212:215], v[8:11]
	v_mfma_f32_16x16x32_bf16 v[60:63], v[84:87], v[192:195], v[60:63]
	v_mfma_f32_16x16x32_bf16 v[56:59], v[92:95], v[192:195], v[56:59]
	v_mfma_f32_16x16x32_bf16 v[44:47], v[84:87], v[200:203], v[44:47]
	v_mfma_f32_16x16x32_bf16 v[40:43], v[92:95], v[200:203], v[40:43]
	v_mfma_f32_16x16x32_bf16 v[28:31], v[84:87], v[208:211], v[28:31]
	v_mfma_f32_16x16x32_bf16 v[24:27], v[92:95], v[208:211], v[24:27]
	v_mfma_f32_16x16x32_bf16 v[12:15], v[84:87], v[216:219], v[12:15]
	v_mfma_f32_16x16x32_bf16 v[8:11], v[92:95], v[216:219], v[8:11]
	s_setprio 0
	s_setprio 1
	v_mfma_f32_16x16x32_bf16 v[52:55], v[164:167], v[188:191], v[52:55]
	v_mfma_f32_16x16x32_bf16 v[48:51], v[180:183], v[188:191], v[48:51]
	v_mfma_f32_16x16x32_bf16 v[36:39], v[164:167], v[196:199], v[36:39]
	v_mfma_f32_16x16x32_bf16 v[32:35], v[180:183], v[196:199], v[32:35]
	v_mfma_f32_16x16x32_bf16 v[20:23], v[164:167], v[204:207], v[20:23]
	v_mfma_f32_16x16x32_bf16 v[16:19], v[180:183], v[204:207], v[16:19]
	v_mfma_f32_16x16x32_bf16 v[4:7], v[164:167], v[212:215], v[4:7]
	v_mfma_f32_16x16x32_bf16 v[0:3], v[180:183], v[212:215], v[0:3]
	v_mfma_f32_16x16x32_bf16 v[52:55], v[176:179], v[192:195], v[52:55]
	v_mfma_f32_16x16x32_bf16 v[48:51], v[184:187], v[192:195], v[48:51]
	v_mfma_f32_16x16x32_bf16 v[36:39], v[176:179], v[200:203], v[36:39]
	v_mfma_f32_16x16x32_bf16 v[32:35], v[184:187], v[200:203], v[32:35]
	v_mfma_f32_16x16x32_bf16 v[20:23], v[176:179], v[208:211], v[20:23]
	v_mfma_f32_16x16x32_bf16 v[16:19], v[184:187], v[208:211], v[16:19]
	s_barrier
	v_mfma_f32_16x16x32_bf16 v[4:7], v[176:179], v[216:219], v[4:7]
	v_mfma_f32_16x16x32_bf16 v[0:3], v[184:187], v[216:219], v[0:3]
	s_setprio 0
	s_add_i32 s65, 0, 0x18000
	s_add_i32 s66, 0, 0x1c000
	v_add_u32_e32 v92, s65, v169
	v_add_u32_e32 v184, s66, v169
	ds_read_b128 v[80:83], v92
	ds_read_b128 v[84:87], v92 offset:1024
	ds_read_b128 v[88:91], v92 offset:2048
	ds_read_b128 v[92:95], v92 offset:3072
	ds_read_b128 v[164:167], v184
	ds_read_b128 v[176:179], v184 offset:1024
	ds_read_b128 v[180:183], v184 offset:2048
	ds_read_b128 v[184:187], v184 offset:3072
	s_add_u32 s46, s46, 0x80000
	s_addc_u32 s47, s47, 0
	s_mov_b32 m0, s49
	v_lshl_add_u64 v[228:229], s[46:47], 0, v[144:145]
	ds_read_b128 v[188:191], v173 offset:32768
	ds_read_b128 v[192:195], v173 offset:33792
	ds_read_b128 v[196:199], v173 offset:34816
	ds_read_b128 v[200:203], v173 offset:35840
	ds_read_b128 v[204:207], v173 offset:36864
	ds_read_b128 v[208:211], v173 offset:37888
	ds_read_b128 v[212:215], v173 offset:38912
	ds_read_b128 v[216:219], v173 offset:39936
	global_load_lds_dwordx4 v[228:229], off
	v_lshl_add_u64 v[228:229], s[46:47], 0, v[150:151]
	s_mov_b32 m0, s50
	s_nop 0
	global_load_lds_dwordx4 v[228:229], off
	s_waitcnt vmcnt(8)
	s_waitcnt lgkmcnt(0)
	s_barrier
	s_setprio 1
	s_waitcnt lgkmcnt(0)
	v_mfma_f32_16x16x32_bf16 v[140:143], v[80:83], v[188:191], v[140:143]
	v_mfma_f32_16x16x32_bf16 v[136:139], v[88:91], v[188:191], v[136:139]
	v_mfma_f32_16x16x32_bf16 v[124:127], v[80:83], v[196:199], v[124:127]
	v_mfma_f32_16x16x32_bf16 v[120:123], v[88:91], v[196:199], v[120:123]
	v_mfma_f32_16x16x32_bf16 v[108:111], v[80:83], v[204:207], v[108:111]
	v_mfma_f32_16x16x32_bf16 v[104:107], v[88:91], v[204:207], v[104:107]
	v_mfma_f32_16x16x32_bf16 v[76:79], v[80:83], v[212:215], v[76:79]
	v_mfma_f32_16x16x32_bf16 v[72:75], v[88:91], v[212:215], v[72:75]
	v_mfma_f32_16x16x32_bf16 v[140:143], v[84:87], v[192:195], v[140:143]
	v_mfma_f32_16x16x32_bf16 v[136:139], v[92:95], v[192:195], v[136:139]
	v_mfma_f32_16x16x32_bf16 v[124:127], v[84:87], v[200:203], v[124:127]
	v_mfma_f32_16x16x32_bf16 v[120:123], v[92:95], v[200:203], v[120:123]
	v_mfma_f32_16x16x32_bf16 v[108:111], v[84:87], v[208:211], v[108:111]
	v_mfma_f32_16x16x32_bf16 v[104:107], v[92:95], v[208:211], v[104:107]
	v_mfma_f32_16x16x32_bf16 v[76:79], v[84:87], v[216:219], v[76:79]
	v_mfma_f32_16x16x32_bf16 v[72:75], v[92:95], v[216:219], v[72:75]
	s_setprio 0
	s_setprio 1
	v_mfma_f32_16x16x32_bf16 v[132:135], v[164:167], v[188:191], v[132:135]
	v_mfma_f32_16x16x32_bf16 v[128:131], v[180:183], v[188:191], v[128:131]
	v_mfma_f32_16x16x32_bf16 v[116:119], v[164:167], v[196:199], v[116:119]
	v_mfma_f32_16x16x32_bf16 v[112:115], v[180:183], v[196:199], v[112:115]
	v_mfma_f32_16x16x32_bf16 v[100:103], v[164:167], v[204:207], v[100:103]
	v_mfma_f32_16x16x32_bf16 v[96:99], v[180:183], v[204:207], v[96:99]
	v_mfma_f32_16x16x32_bf16 v[68:71], v[164:167], v[212:215], v[68:71]
	v_mfma_f32_16x16x32_bf16 v[64:67], v[180:183], v[212:215], v[64:67]
	v_mfma_f32_16x16x32_bf16 v[132:135], v[176:179], v[192:195], v[132:135]
	v_mfma_f32_16x16x32_bf16 v[128:131], v[184:187], v[192:195], v[128:131]
	v_mfma_f32_16x16x32_bf16 v[116:119], v[176:179], v[200:203], v[116:119]
	v_mfma_f32_16x16x32_bf16 v[112:115], v[184:187], v[200:203], v[112:115]
	v_mfma_f32_16x16x32_bf16 v[100:103], v[176:179], v[208:211], v[100:103]
	v_mfma_f32_16x16x32_bf16 v[96:99], v[184:187], v[208:211], v[96:99]
	s_barrier
; #define PG8_STAGE(bufoff, gbase, voff) do { _Pragma("unroll") for (int _i = 0; _i < 2; ++_i) \
;         __builtin_amdgcn_global_load_lds((const unsigned*)((const char*)(gbase) + (voff)[_i]), (PG8_LAS unsigned*)(lds + (bufoff) + ldsw + _i * 8192), 16, 0, 0); } while (0)
; #define PG8_LDA(dst, b, h) do { _Pragma("unroll") for (int m = 0; m < 4; ++m) _Pragma("unroll") for (int k = 0; k < 2; ++k) dst[m][k] = *(const PG8_LAS bf16x8*)(lds + PG8_SA(b, h) + aoff + m * 2048 + k * 1024); } while (0)
; #define PG8_MMA(ai, bj, At, Bt) do { __builtin_amdgcn_s_setprio(1); _Pragma("unroll") for (int m = 0; m < 4; ++m) _Pragma("unroll") for (int n = 0; n < 2; ++n) _Pragma("unroll") for (int k = 0; k < 2; ++k) \
;         acc[ai][bj][m][n] = __builtin_amdgcn_mfma_f32_16x16x32_bf16(Bt[n][k], At[m][k], acc[ai][bj][m][n], 0, 0, 0); __builtin_amdgcn_s_setprio(0); } while (0)
; #define PG8_WAIT_V(n) asm volatile("s_waitcnt vmcnt(" #n ")" ::: "memory")
; #define PG8_WAIT_L(n) asm volatile("s_waitcnt lgkmcnt(" #n ")" ::: "memory")
; #define PG8_BAR __builtin_amdgcn_s_barrier()
; #define PG8_SCHED __builtin_amdgcn_sched_barrier(0)
; template <class Epi, class Sched, bool ALIGN_EPI = false, bool SP2 = false>
; __device__ __forceinline__ void gemm_phase(PG8_LAS unsigned char* lds, const Gemm g, const Sched& S, const Epi& E) {
;     ...
;             PG8_WAIT_V(8); PG8_WAIT_L(0); PG8_BAR; PG8_MMA(0, 0, At, B0); PG8_MMA(0, 1, At, B1); PG8_BAR; PG8_SCHED;
;             PG8_LDA(At, 1, 1); PG8_STAGE(PG8_SB(1, 0), b3, voffB); PG8_STAGE(PG8_SB(1, 1), b3 + hstep, voffB); PG8_STAGE(PG8_SA(1, 0), a3, voffA);
;             PG8_WAIT_V(8); PG8_WAIT_L(0); PG8_BAR; PG8_MMA(1, 0, At, B0); PG8_MMA(1, 1, At, B1); PG8_BAR; PG8_SCHED;
;     ...
;         if constexpr (ALIGN_EPI) { if (wr == 0) PG8_BAR; }
	v_mfma_f32_16x16x32_bf16 v[68:71], v[176:179], v[216:219], v[68:71]
	v_mfma_f32_16x16x32_bf16 v[64:67], v[184:187], v[216:219], v[64:67]
	s_setprio 0
	s_add_i32 s46, s65, s33
	v_lshl_add_u64 v[220:221], v[220:221], 0, s[8:9]
	s_mov_b32 m0, s46
	ds_read_b128 v[188:191], v173 offset:49152
	ds_read_b128 v[192:195], v173 offset:50176
	ds_read_b128 v[196:199], v173 offset:51200
	ds_read_b128 v[200:203], v173 offset:52224
	ds_read_b128 v[204:207], v173 offset:53248
	ds_read_b128 v[208:211], v173 offset:54272
	ds_read_b128 v[212:215], v173 offset:55296
	ds_read_b128 v[216:219], v173 offset:56320
	global_load_lds_dwordx4 v[220:221], off
	s_add_i32 m0, s46, 0x2000
	s_add_u32 s44, s44, 0x80080
	v_lshl_add_u64 v[220:221], v[222:223], 0, s[8:9]
	s_addc_u32 s45, s45, 0
	s_add_i32 s46, s66, s33
	global_load_lds_dwordx4 v[220:221], off
	v_lshl_add_u64 v[220:221], s[44:45], 0, v[148:149]
	s_mov_b32 m0, s46
	s_nop 0
	global_load_lds_dwordx4 v[220:221], off
	v_lshl_add_u64 v[220:221], s[44:45], 0, v[152:153]
	s_add_i32 m0, s46, 0x2000
	s_nop 0
	global_load_lds_dwordx4 v[220:221], off
	v_lshl_add_u64 v[220:221], v[224:225], 0, s[8:9]
	s_mov_b32 m0, s52
	s_nop 0
	global_load_lds_dwordx4 v[220:221], off
	v_lshl_add_u64 v[220:221], v[226:227], 0, s[8:9]
	s_mov_b32 m0, s53
	s_nop 0
	global_load_lds_dwordx4 v[220:221], off
	s_waitcnt vmcnt(8)
	s_waitcnt lgkmcnt(0)
	s_barrier
	s_setprio 1
	s_waitcnt lgkmcnt(0)
	v_mfma_f32_16x16x32_bf16 v[60:63], v[80:83], v[188:191], v[60:63]
	v_mfma_f32_16x16x32_bf16 v[56:59], v[88:91], v[188:191], v[56:59]
	v_mfma_f32_16x16x32_bf16 v[44:47], v[80:83], v[196:199], v[44:47]
	v_mfma_f32_16x16x32_bf16 v[40:43], v[88:91], v[196:199], v[40:43]
	v_mfma_f32_16x16x32_bf16 v[28:31], v[80:83], v[204:207], v[28:31]
	v_mfma_f32_16x16x32_bf16 v[24:27], v[88:91], v[204:207], v[24:27]
	v_mfma_f32_16x16x32_bf16 v[12:15], v[80:83], v[212:215], v[12:15]
	v_mfma_f32_16x16x32_bf16 v[8:11], v[88:91], v[212:215], v[8:11]
	v_mfma_f32_16x16x32_bf16 v[60:63], v[84:87], v[192:195], v[60:63]
	v_mfma_f32_16x16x32_bf16 v[56:59], v[92:95], v[192:195], v[56:59]
	v_mfma_f32_16x16x32_bf16 v[44:47], v[84:87], v[200:203], v[44:47]
	v_mfma_f32_16x16x32_bf16 v[40:43], v[92:95], v[200:203], v[40:43]
	v_mfma_f32_16x16x32_bf16 v[28:31], v[84:87], v[208:211], v[28:31]
	v_mfma_f32_16x16x32_bf16 v[24:27], v[92:95], v[208:211], v[24:27]
	v_mfma_f32_16x16x32_bf16 v[12:15], v[84:87], v[216:219], v[12:15]
	v_mfma_f32_16x16x32_bf16 v[8:11], v[92:95], v[216:219], v[8:11]
	s_setprio 0
	s_setprio 1
	v_mfma_f32_16x16x32_bf16 v[52:55], v[164:167], v[188:191], v[52:55]
	v_mfma_f32_16x16x32_bf16 v[48:51], v[180:183], v[188:191], v[48:51]
	v_mfma_f32_16x16x32_bf16 v[36:39], v[164:167], v[196:199], v[36:39]
	v_mfma_f32_16x16x32_bf16 v[32:35], v[180:183], v[196:199], v[32:35]
	v_mfma_f32_16x16x32_bf16 v[20:23], v[164:167], v[204:207], v[20:23]
	v_mfma_f32_16x16x32_bf16 v[16:19], v[180:183], v[204:207], v[16:19]
	v_mfma_f32_16x16x32_bf16 v[4:7], v[164:167], v[212:215], v[4:7]
	v_mfma_f32_16x16x32_bf16 v[0:3], v[180:183], v[212:215], v[0:3]
	v_mfma_f32_16x16x32_bf16 v[52:55], v[176:179], v[192:195], v[52:55]
	v_mfma_f32_16x16x32_bf16 v[48:51], v[184:187], v[192:195], v[48:51]
	v_mfma_f32_16x16x32_bf16 v[36:39], v[176:179], v[200:203], v[36:39]
	v_mfma_f32_16x16x32_bf16 v[32:35], v[184:187], v[200:203], v[32:35]
	v_mfma_f32_16x16x32_bf16 v[20:23], v[176:179], v[208:211], v[20:23]
	v_mfma_f32_16x16x32_bf16 v[16:19], v[184:187], v[208:211], v[16:19]
	s_barrier
	v_mfma_f32_16x16x32_bf16 v[4:7], v[176:179], v[216:219], v[4:7]
	v_mfma_f32_16x16x32_bf16 v[0:3], v[184:187], v[216:219], v[0:3]
	s_setprio 0
	s_add_i32 s64, s64, 2
	s_add_u32 s42, s42, 0x100
	s_addc_u32 s43, s43, 0
	s_add_u32 s62, s62, 0x100
	s_addc_u32 s63, s63, 0
	s_cmp_gt_u32 s64, 29
	s_cbranch_scc0 .LBB0_1142
	s_and_b64 vcc, exec, s[10:11]
	s_cbranch_vccz .LBB0_1145
	s_barrier

; #define PG8_STAGE(bufoff, gbase, voff) do { _Pragma("unroll") for (int _i = 0; _i < 2; ++_i) \
;         __builtin_amdgcn_global_load_lds((const unsigned*)((const char*)(gbase) + (voff)[_i]), (PG8_LAS unsigned*)(lds + (bufoff) + ldsw + _i * 8192), 16, 0, 0); } while (0)
; #define PG8_LDA(dst, b, h) do { _Pragma("unroll") for (int m = 0; m < 4; ++m) _Pragma("unroll") for (int k = 0; k < 2; ++k) dst[m][k] = *(const PG8_LAS bf16x8*)(lds + PG8_SA(b, h) + aoff + m * 2048 + k * 1024); } while (0)
; #define PG8_LDB(dst, b, h) do { _Pragma("unroll") for (int n = 0; n < 2; ++n) _Pragma("unroll") for (int k = 0; k < 2; ++k) dst[n][k] = *(const PG8_LAS bf16x8*)(lds + PG8_SB(b, h) + boff + n * 2048 + k * 1024); } while (0)
; #define PG8_MMA(ai, bj, At, Bt) do { __builtin_amdgcn_s_setprio(1); _Pragma("unroll") for (int m = 0; m < 4; ++m) _Pragma("unroll") for (int n = 0; n < 2; ++n) _Pragma("unroll") for (int k = 0; k < 2; ++k) \
;         acc[ai][bj][m][n] = __builtin_amdgcn_mfma_f32_16x16x32_bf16(Bt[n][k], At[m][k], acc[ai][bj][m][n], 0, 0, 0); __builtin_amdgcn_s_setprio(0); } while (0)
; #define PG8_WAIT_V(n) asm volatile("s_waitcnt vmcnt(" #n ")" ::: "memory")
; #define PG8_WAIT_L(n) asm volatile("s_waitcnt lgkmcnt(" #n ")" ::: "memory")
; #define PG8_BAR __builtin_amdgcn_s_barrier()
; #define PG8_SCHED __builtin_amdgcn_sched_barrier(0)
; template <class Epi, class Sched, bool ALIGN_EPI = false, bool SP2 = false>
; __device__ __forceinline__ void gemm_phase(PG8_LAS unsigned char* lds, const Gemm g, const Sched& S, const Epi& E) {
;     ...
;         for (int t = 0; t < nt; t += 2) {
;             const bool last = (t == nt - 2);
;             const char* a1 = cA + (size_t)(t + 1) * kstep;
;             const char* a2 = last ? nA : cA + (size_t)(t + 2) * kstep; const char* b2 = last ? nB : cB + (size_t)(t + 2) * kstep;
;             const char* a3 = a2 + kstep; const char* b3 = b2 + kstep;
;             if constexpr (SP2) {
;             PG8_LDB(B0, 0, 0); PG8_LDB(B1, 0, 1); PG8_SCHED; PG8_LDA(At, 0, 0); PG8_STAGE(PG8_SA(1, 1), a1 + hstep, voffA);
;             PG8_WAIT_V(8); PG8_WAIT_L(0); PG8_BAR; PG8_MMA(0, 0, At, B0); PG8_MMA(0, 1, At, B1); PG8_BAR; PG8_SCHED;
.LBB0_1219:
	ds_read_b128 v[128:131], v167
	ds_read_b128 v[132:135], v167 offset:1024
	ds_read_b128 v[154:157], v167 offset:2048
	ds_read_b128 v[158:161], v167 offset:3072
	ds_read_b128 v[170:173], v168
	ds_read_b128 v[174:177], v168 offset:1024
	ds_read_b128 v[178:181], v168 offset:2048
	ds_read_b128 v[182:185], v168 offset:3072
	s_add_u32 s42, s40, 0xffe00080
	s_addc_u32 s43, s41, -1
	s_cmpk_eq_i32 s63, 0x7c
	s_cselect_b32 s45, s15, s43
	s_cselect_b32 s44, s59, s42
	s_cselect_b32 s43, s13, s62
	s_cselect_b32 s42, s60, s61
	v_lshl_add_u64 v[162:163], s[40:41], 0, v[144:145]
	s_add_i32 m0, s39, 0xc000
	ds_read_b128 v[186:189], v169
	ds_read_b128 v[190:193], v169 offset:1024
	ds_read_b128 v[194:197], v169 offset:2048
	ds_read_b128 v[198:201], v169 offset:3072
	ds_read_b128 v[202:205], v169 offset:4096
	ds_read_b128 v[206:209], v169 offset:5120
	ds_read_b128 v[210:213], v169 offset:6144
	ds_read_b128 v[214:217], v169 offset:7168
	global_load_lds_dwordx4 v[162:163], off
	v_lshl_add_u64 v[162:163], s[40:41], 0, v[148:149]
	s_add_i32 m0, s39, 0xe000
	s_nop 0
	global_load_lds_dwordx4 v[162:163], off
	s_waitcnt vmcnt(8)
	s_waitcnt lgkmcnt(0)
	s_barrier
	s_setprio 1
	s_waitcnt lgkmcnt(0)
	v_mfma_f32_16x16x32_bf16 v[124:127], v[128:131], v[186:189], v[124:127]
	v_mfma_f32_16x16x32_bf16 v[120:123], v[154:157], v[186:189], v[120:123]
	v_mfma_f32_16x16x32_bf16 v[116:119], v[128:131], v[194:197], v[116:119]
	v_mfma_f32_16x16x32_bf16 v[112:115], v[154:157], v[194:197], v[112:115]
	v_mfma_f32_16x16x32_bf16 v[108:111], v[128:131], v[202:205], v[108:111]
	v_mfma_f32_16x16x32_bf16 v[104:107], v[154:157], v[202:205], v[104:107]
	v_mfma_f32_16x16x32_bf16 v[100:103], v[128:131], v[210:213], v[100:103]
	v_mfma_f32_16x16x32_bf16 v[96:99], v[154:157], v[210:213], v[96:99]
	v_mfma_f32_16x16x32_bf16 v[124:127], v[132:135], v[190:193], v[124:127]
	v_mfma_f32_16x16x32_bf16 v[120:123], v[158:161], v[190:193], v[120:123]
	v_mfma_f32_16x16x32_bf16 v[116:119], v[132:135], v[198:201], v[116:119]
	v_mfma_f32_16x16x32_bf16 v[112:115], v[158:161], v[198:201], v[112:115]
	v_mfma_f32_16x16x32_bf16 v[108:111], v[132:135], v[206:209], v[108:111]
	v_mfma_f32_16x16x32_bf16 v[104:107], v[158:161], v[206:209], v[104:107]
	v_mfma_f32_16x16x32_bf16 v[100:103], v[132:135], v[214:217], v[100:103]
	v_mfma_f32_16x16x32_bf16 v[96:99], v[158:161], v[214:217], v[96:99]
	s_setprio 0
	s_setprio 1
	v_mfma_f32_16x16x32_bf16 v[68:71], v[170:173], v[186:189], v[68:71]
	v_mfma_f32_16x16x32_bf16 v[60:63], v[178:181], v[186:189], v[60:63]
	v_mfma_f32_16x16x32_bf16 v[52:55], v[170:173], v[194:197], v[52:55]
	v_mfma_f32_16x16x32_bf16 v[48:51], v[178:181], v[194:197], v[48:51]
	v_mfma_f32_16x16x32_bf16 v[44:47], v[170:173], v[202:205], v[44:47]
	v_mfma_f32_16x16x32_bf16 v[40:43], v[178:181], v[202:205], v[40:43]
	v_mfma_f32_16x16x32_bf16 v[36:39], v[170:173], v[210:213], v[36:39]
	v_mfma_f32_16x16x32_bf16 v[32:35], v[178:181], v[210:213], v[32:35]
	v_mfma_f32_16x16x32_bf16 v[68:71], v[174:177], v[190:193], v[68:71]
	v_mfma_f32_16x16x32_bf16 v[60:63], v[182:185], v[190:193], v[60:63]
	v_mfma_f32_16x16x32_bf16 v[52:55], v[174:177], v[198:201], v[52:55]
	v_mfma_f32_16x16x32_bf16 v[48:51], v[182:185], v[198:201], v[48:51]
	v_mfma_f32_16x16x32_bf16 v[44:47], v[174:177], v[206:209], v[44:47]
	v_mfma_f32_16x16x32_bf16 v[40:43], v[182:185], v[206:209], v[40:43]
	s_barrier
	v_mfma_f32_16x16x32_bf16 v[36:39], v[174:177], v[214:217], v[36:39]
	v_mfma_f32_16x16x32_bf16 v[32:35], v[182:185], v[214:217], v[32:35]
	s_setprio 0
	s_add_i32 s64, s56, s33
	v_lshl_add_u64 v[162:163], s[42:43], 0, v[138:139]
	s_mov_b32 m0, s64
	ds_read_b128 v[186:189], v169 offset:16384
	ds_read_b128 v[190:193], v169 offset:17408
	ds_read_b128 v[194:197], v169 offset:18432
	ds_read_b128 v[198:201], v169 offset:19456
	ds_read_b128 v[202:205], v169 offset:20480
	ds_read_b128 v[206:209], v169 offset:21504
	ds_read_b128 v[210:213], v169 offset:22528
	ds_read_b128 v[214:217], v169 offset:23552
	global_load_lds_dwordx4 v[162:163], off
	s_add_i32 m0, s64, 0x2000
	s_add_u32 s64, s42, 0x200000
	v_lshl_add_u64 v[218:219], s[42:43], 0, v[142:143]
	s_addc_u32 s65, s43, 0
	s_add_i32 s66, s57, s33
	global_load_lds_dwordx4 v[218:219], off
	v_lshl_add_u64 v[220:221], s[64:65], 0, v[138:139]
	s_mov_b32 m0, s66
	v_lshl_add_u64 v[222:223], s[44:45], 0, v[140:141]
	global_load_lds_dwordx4 v[220:221], off
	v_lshl_add_u64 v[220:221], s[64:65], 0, v[142:143]
	s_add_i32 m0, s66, 0x2000
	s_nop 0
	global_load_lds_dwordx4 v[220:221], off
	v_lshl_add_u64 v[220:221], s[44:45], 0, v[136:137]
	s_mov_b32 m0, s39
	s_nop 0
	global_load_lds_dwordx4 v[220:221], off
	s_mov_b32 m0, s46
	s_nop 0
	global_load_lds_dwordx4 v[222:223], off
	s_waitcnt vmcnt(8)
	s_waitcnt lgkmcnt(0)
	s_barrier
; #define PG8_STAGE(bufoff, gbase, voff) do { _Pragma("unroll") for (int _i = 0; _i < 2; ++_i) \
;         __builtin_amdgcn_global_load_lds((const unsigned*)((const char*)(gbase) + (voff)[_i]), (PG8_LAS unsigned*)(lds + (bufoff) + ldsw + _i * 8192), 16, 0, 0); } while (0)
; #define PG8_LDA(dst, b, h) do { _Pragma("unroll") for (int m = 0; m < 4; ++m) _Pragma("unroll") for (int k = 0; k < 2; ++k) dst[m][k] = *(const PG8_LAS bf16x8*)(lds + PG8_SA(b, h) + aoff + m * 2048 + k * 1024); } while (0)
; #define PG8_LDB(dst, b, h) do { _Pragma("unroll") for (int n = 0; n < 2; ++n) _Pragma("unroll") for (int k = 0; k < 2; ++k) dst[n][k] = *(const PG8_LAS bf16x8*)(lds + PG8_SB(b, h) + boff + n * 2048 + k * 1024); } while (0)
; #define PG8_MMA(ai, bj, At, Bt) do { __builtin_amdgcn_s_setprio(1); _Pragma("unroll") for (int m = 0; m < 4; ++m) _Pragma("unroll") for (int n = 0; n < 2; ++n) _Pragma("unroll") for (int k = 0; k < 2; ++k) \
;         acc[ai][bj][m][n] = __builtin_amdgcn_mfma_f32_16x16x32_bf16(Bt[n][k], At[m][k], acc[ai][bj][m][n], 0, 0, 0); __builtin_amdgcn_s_setprio(0); } while (0)
; #define PG8_WAIT_V(n) asm volatile("s_waitcnt vmcnt(" #n ")" ::: "memory")
; #define PG8_WAIT_L(n) asm volatile("s_waitcnt lgkmcnt(" #n ")" ::: "memory")
; #define PG8_BAR __builtin_amdgcn_s_barrier()
; #define PG8_SCHED __builtin_amdgcn_sched_barrier(0)
; template <class Epi, class Sched, bool ALIGN_EPI = false, bool SP2 = false>
; __device__ __forceinline__ void gemm_phase(PG8_LAS unsigned char* lds, const Gemm g, const Sched& S, const Epi& E) {
;     ...
;             PG8_WAIT_V(8); PG8_WAIT_L(0); PG8_BAR; PG8_MMA(1, 0, At, B0); PG8_MMA(1, 1, At, B1); PG8_BAR; PG8_SCHED;
;             PG8_LDB(B0, 1, 0); PG8_LDB(B1, 1, 1); PG8_SCHED; PG8_LDA(At, 1, 0); PG8_STAGE(PG8_SA(0, 1), a2 + hstep, voffA);
;             PG8_WAIT_V(8); PG8_WAIT_L(0); PG8_BAR; PG8_MMA(0, 0, At, B0); PG8_MMA(0, 1, At, B1); PG8_BAR; PG8_SCHED;
	s_setprio 1
	s_waitcnt lgkmcnt(0)
	v_mfma_f32_16x16x32_bf16 v[92:95], v[128:131], v[186:189], v[92:95]
	v_mfma_f32_16x16x32_bf16 v[88:91], v[154:157], v[186:189], v[88:91]
	v_mfma_f32_16x16x32_bf16 v[84:87], v[128:131], v[194:197], v[84:87]
	v_mfma_f32_16x16x32_bf16 v[80:83], v[154:157], v[194:197], v[80:83]
	v_mfma_f32_16x16x32_bf16 v[76:79], v[128:131], v[202:205], v[76:79]
	v_mfma_f32_16x16x32_bf16 v[72:75], v[154:157], v[202:205], v[72:75]
	v_mfma_f32_16x16x32_bf16 v[64:67], v[128:131], v[210:213], v[64:67]
	v_mfma_f32_16x16x32_bf16 v[56:59], v[154:157], v[210:213], v[56:59]
	v_mfma_f32_16x16x32_bf16 v[92:95], v[132:135], v[190:193], v[92:95]
	v_mfma_f32_16x16x32_bf16 v[88:91], v[158:161], v[190:193], v[88:91]
	v_mfma_f32_16x16x32_bf16 v[84:87], v[132:135], v[198:201], v[84:87]
	v_mfma_f32_16x16x32_bf16 v[80:83], v[158:161], v[198:201], v[80:83]
	v_mfma_f32_16x16x32_bf16 v[76:79], v[132:135], v[206:209], v[76:79]
	v_mfma_f32_16x16x32_bf16 v[72:75], v[158:161], v[206:209], v[72:75]
	v_mfma_f32_16x16x32_bf16 v[64:67], v[132:135], v[214:217], v[64:67]
	v_mfma_f32_16x16x32_bf16 v[56:59], v[158:161], v[214:217], v[56:59]
	s_setprio 0
	s_setprio 1
	v_mfma_f32_16x16x32_bf16 v[28:31], v[170:173], v[186:189], v[28:31]
	v_mfma_f32_16x16x32_bf16 v[24:27], v[178:181], v[186:189], v[24:27]
	v_mfma_f32_16x16x32_bf16 v[20:23], v[170:173], v[194:197], v[20:23]
	v_mfma_f32_16x16x32_bf16 v[16:19], v[178:181], v[194:197], v[16:19]
	v_mfma_f32_16x16x32_bf16 v[12:15], v[170:173], v[202:205], v[12:15]
	v_mfma_f32_16x16x32_bf16 v[8:11], v[178:181], v[202:205], v[8:11]
	v_mfma_f32_16x16x32_bf16 v[4:7], v[170:173], v[210:213], v[4:7]
	v_mfma_f32_16x16x32_bf16 v[0:3], v[178:181], v[210:213], v[0:3]
	v_mfma_f32_16x16x32_bf16 v[28:31], v[174:177], v[190:193], v[28:31]
	v_mfma_f32_16x16x32_bf16 v[24:27], v[182:185], v[190:193], v[24:27]
	v_mfma_f32_16x16x32_bf16 v[20:23], v[174:177], v[198:201], v[20:23]
	v_mfma_f32_16x16x32_bf16 v[16:19], v[182:185], v[198:201], v[16:19]
	v_mfma_f32_16x16x32_bf16 v[12:15], v[174:177], v[206:209], v[12:15]
	v_mfma_f32_16x16x32_bf16 v[8:11], v[182:185], v[206:209], v[8:11]
	s_barrier
	v_mfma_f32_16x16x32_bf16 v[4:7], v[174:177], v[214:217], v[4:7]
	v_mfma_f32_16x16x32_bf16 v[0:3], v[182:185], v[214:217], v[0:3]
	s_setprio 0
	s_add_i32 s64, 0, 0x18000
	s_add_i32 s65, 0, 0x1c000
	v_add_u32_e32 v158, s64, v165
	v_add_u32_e32 v182, s65, v165
	ds_read_b128 v[128:131], v158
	ds_read_b128 v[132:135], v158 offset:1024
	ds_read_b128 v[154:157], v158 offset:2048
	ds_read_b128 v[158:161], v158 offset:3072
	ds_read_b128 v[170:173], v182
	ds_read_b128 v[174:177], v182 offset:1024
	ds_read_b128 v[178:181], v182 offset:2048
	ds_read_b128 v[182:185], v182 offset:3072
	s_add_u32 s44, s44, 0x200000
	s_addc_u32 s45, s45, 0
	s_mov_b32 m0, s47
	v_lshl_add_u64 v[224:225], s[44:45], 0, v[136:137]
	ds_read_b128 v[186:189], v169 offset:32768
	ds_read_b128 v[190:193], v169 offset:33792
	ds_read_b128 v[194:197], v169 offset:34816
	ds_read_b128 v[198:201], v169 offset:35840
	ds_read_b128 v[202:205], v169 offset:36864
	ds_read_b128 v[206:209], v169 offset:37888
	ds_read_b128 v[210:213], v169 offset:38912
	ds_read_b128 v[214:217], v169 offset:39936
	global_load_lds_dwordx4 v[224:225], off
	v_lshl_add_u64 v[224:225], s[44:45], 0, v[140:141]
	s_mov_b32 m0, s48
	s_nop 0
	global_load_lds_dwordx4 v[224:225], off
	s_waitcnt vmcnt(8)
	s_waitcnt lgkmcnt(0)
	s_barrier
	s_setprio 1
	s_waitcnt lgkmcnt(0)
	v_mfma_f32_16x16x32_bf16 v[124:127], v[128:131], v[186:189], v[124:127]
	v_mfma_f32_16x16x32_bf16 v[120:123], v[154:157], v[186:189], v[120:123]
	v_mfma_f32_16x16x32_bf16 v[116:119], v[128:131], v[194:197], v[116:119]
	v_mfma_f32_16x16x32_bf16 v[112:115], v[154:157], v[194:197], v[112:115]
	v_mfma_f32_16x16x32_bf16 v[108:111], v[128:131], v[202:205], v[108:111]
	v_mfma_f32_16x16x32_bf16 v[104:107], v[154:157], v[202:205], v[104:107]
	v_mfma_f32_16x16x32_bf16 v[100:103], v[128:131], v[210:213], v[100:103]
	v_mfma_f32_16x16x32_bf16 v[96:99], v[154:157], v[210:213], v[96:99]
	v_mfma_f32_16x16x32_bf16 v[124:127], v[132:135], v[190:193], v[124:127]
	v_mfma_f32_16x16x32_bf16 v[120:123], v[158:161], v[190:193], v[120:123]
	v_mfma_f32_16x16x32_bf16 v[116:119], v[132:135], v[198:201], v[116:119]
	v_mfma_f32_16x16x32_bf16 v[112:115], v[158:161], v[198:201], v[112:115]
	v_mfma_f32_16x16x32_bf16 v[108:111], v[132:135], v[206:209], v[108:111]
	v_mfma_f32_16x16x32_bf16 v[104:107], v[158:161], v[206:209], v[104:107]
	v_mfma_f32_16x16x32_bf16 v[100:103], v[132:135], v[214:217], v[100:103]
	v_mfma_f32_16x16x32_bf16 v[96:99], v[158:161], v[214:217], v[96:99]
	s_setprio 0
	s_setprio 1
	v_mfma_f32_16x16x32_bf16 v[68:71], v[170:173], v[186:189], v[68:71]
	v_mfma_f32_16x16x32_bf16 v[60:63], v[178:181], v[186:189], v[60:63]
	v_mfma_f32_16x16x32_bf16 v[52:55], v[170:173], v[194:197], v[52:55]
	v_mfma_f32_16x16x32_bf16 v[48:51], v[178:181], v[194:197], v[48:51]
	v_mfma_f32_16x16x32_bf16 v[44:47], v[170:173], v[202:205], v[44:47]
	v_mfma_f32_16x16x32_bf16 v[40:43], v[178:181], v[202:205], v[40:43]
	v_mfma_f32_16x16x32_bf16 v[36:39], v[170:173], v[210:213], v[36:39]
	v_mfma_f32_16x16x32_bf16 v[32:35], v[178:181], v[210:213], v[32:35]
	v_mfma_f32_16x16x32_bf16 v[68:71], v[174:177], v[190:193], v[68:71]
	v_mfma_f32_16x16x32_bf16 v[60:63], v[182:185], v[190:193], v[60:63]
	v_mfma_f32_16x16x32_bf16 v[52:55], v[174:177], v[198:201], v[52:55]
	v_mfma_f32_16x16x32_bf16 v[48:51], v[182:185], v[198:201], v[48:51]
	v_mfma_f32_16x16x32_bf16 v[44:47], v[174:177], v[206:209], v[44:47]
	v_mfma_f32_16x16x32_bf16 v[40:43], v[182:185], v[206:209], v[40:43]
	s_barrier
; #define PG8_STAGE(bufoff, gbase, voff) do { _Pragma("unroll") for (int _i = 0; _i < 2; ++_i) \
;         __builtin_amdgcn_global_load_lds((const unsigned*)((const char*)(gbase) + (voff)[_i]), (PG8_LAS unsigned*)(lds + (bufoff) + ldsw + _i * 8192), 16, 0, 0); } while (0)
; #define PG8_LDA(dst, b, h) do { _Pragma("unroll") for (int m = 0; m < 4; ++m) _Pragma("unroll") for (int k = 0; k < 2; ++k) dst[m][k] = *(const PG8_LAS bf16x8*)(lds + PG8_SA(b, h) + aoff + m * 2048 + k * 1024); } while (0)
; #define PG8_MMA(ai, bj, At, Bt) do { __builtin_amdgcn_s_setprio(1); _Pragma("unroll") for (int m = 0; m < 4; ++m) _Pragma("unroll") for (int n = 0; n < 2; ++n) _Pragma("unroll") for (int k = 0; k < 2; ++k) \
;         acc[ai][bj][m][n] = __builtin_amdgcn_mfma_f32_16x16x32_bf16(Bt[n][k], At[m][k], acc[ai][bj][m][n], 0, 0, 0); __builtin_amdgcn_s_setprio(0); } while (0)
; #define PG8_WAIT_V(n) asm volatile("s_waitcnt vmcnt(" #n ")" ::: "memory")
; #define PG8_WAIT_L(n) asm volatile("s_waitcnt lgkmcnt(" #n ")" ::: "memory")
; #define PG8_BAR __builtin_amdgcn_s_barrier()
; #define PG8_SCHED __builtin_amdgcn_sched_barrier(0)
; template <class Epi, class Sched, bool ALIGN_EPI = false, bool SP2 = false>
; __device__ __forceinline__ void gemm_phase(PG8_LAS unsigned char* lds, const Gemm g, const Sched& S, const Epi& E) {
;     ...
;             PG8_WAIT_V(8); PG8_WAIT_L(0); PG8_BAR; PG8_MMA(0, 0, At, B0); PG8_MMA(0, 1, At, B1); PG8_BAR; PG8_SCHED;
;             PG8_LDA(At, 1, 1); PG8_STAGE(PG8_SB(1, 0), b3, voffB); PG8_STAGE(PG8_SB(1, 1), b3 + hstep, voffB); PG8_STAGE(PG8_SA(1, 0), a3, voffA);
;             PG8_WAIT_V(8); PG8_WAIT_L(0); PG8_BAR; PG8_MMA(1, 0, At, B0); PG8_MMA(1, 1, At, B1); PG8_BAR; PG8_SCHED;
;     ...
;         if constexpr (ALIGN_EPI) { if (wr == 0) PG8_BAR; }
	v_mfma_f32_16x16x32_bf16 v[36:39], v[174:177], v[214:217], v[36:39]
	v_mfma_f32_16x16x32_bf16 v[32:35], v[182:185], v[214:217], v[32:35]
	s_setprio 0
	s_add_i32 s44, s64, s33
	v_lshl_add_u64 v[162:163], v[162:163], 0, s[8:9]
	s_mov_b32 m0, s44
	ds_read_b128 v[186:189], v169 offset:49152
	ds_read_b128 v[190:193], v169 offset:50176
	ds_read_b128 v[194:197], v169 offset:51200
	ds_read_b128 v[198:201], v169 offset:52224
	ds_read_b128 v[202:205], v169 offset:53248
	ds_read_b128 v[206:209], v169 offset:54272
	ds_read_b128 v[210:213], v169 offset:55296
	ds_read_b128 v[214:217], v169 offset:56320
	global_load_lds_dwordx4 v[162:163], off
	s_add_i32 m0, s44, 0x2000
	s_add_u32 s42, s42, 0x200080
	v_lshl_add_u64 v[162:163], v[218:219], 0, s[8:9]
	s_addc_u32 s43, s43, 0
	s_add_i32 s44, s65, s33
	global_load_lds_dwordx4 v[162:163], off
	v_lshl_add_u64 v[162:163], s[42:43], 0, v[138:139]
	s_mov_b32 m0, s44
	s_nop 0
	global_load_lds_dwordx4 v[162:163], off
	v_lshl_add_u64 v[162:163], s[42:43], 0, v[142:143]
	s_add_i32 m0, s44, 0x2000
	s_nop 0
	global_load_lds_dwordx4 v[162:163], off
	v_lshl_add_u64 v[162:163], v[220:221], 0, s[8:9]
	s_mov_b32 m0, s52
	s_nop 0
	global_load_lds_dwordx4 v[162:163], off
	v_lshl_add_u64 v[162:163], v[222:223], 0, s[8:9]
	s_mov_b32 m0, s53
	s_nop 0
	global_load_lds_dwordx4 v[162:163], off
	s_waitcnt vmcnt(8)
	s_waitcnt lgkmcnt(0)
	s_barrier
	s_setprio 1
	s_waitcnt lgkmcnt(0)
	v_mfma_f32_16x16x32_bf16 v[92:95], v[128:131], v[186:189], v[92:95]
	v_mfma_f32_16x16x32_bf16 v[88:91], v[154:157], v[186:189], v[88:91]
	v_mfma_f32_16x16x32_bf16 v[84:87], v[128:131], v[194:197], v[84:87]
	v_mfma_f32_16x16x32_bf16 v[80:83], v[154:157], v[194:197], v[80:83]
	v_mfma_f32_16x16x32_bf16 v[76:79], v[128:131], v[202:205], v[76:79]
	v_mfma_f32_16x16x32_bf16 v[72:75], v[154:157], v[202:205], v[72:75]
	v_mfma_f32_16x16x32_bf16 v[64:67], v[128:131], v[210:213], v[64:67]
	v_mfma_f32_16x16x32_bf16 v[56:59], v[154:157], v[210:213], v[56:59]
	v_mfma_f32_16x16x32_bf16 v[92:95], v[132:135], v[190:193], v[92:95]
	v_mfma_f32_16x16x32_bf16 v[88:91], v[158:161], v[190:193], v[88:91]
	v_mfma_f32_16x16x32_bf16 v[84:87], v[132:135], v[198:201], v[84:87]
	v_mfma_f32_16x16x32_bf16 v[80:83], v[158:161], v[198:201], v[80:83]
	v_mfma_f32_16x16x32_bf16 v[76:79], v[132:135], v[206:209], v[76:79]
	v_mfma_f32_16x16x32_bf16 v[72:75], v[158:161], v[206:209], v[72:75]
	v_mfma_f32_16x16x32_bf16 v[64:67], v[132:135], v[214:217], v[64:67]
	v_mfma_f32_16x16x32_bf16 v[56:59], v[158:161], v[214:217], v[56:59]
	s_setprio 0
	s_setprio 1
	v_mfma_f32_16x16x32_bf16 v[28:31], v[170:173], v[186:189], v[28:31]
	v_mfma_f32_16x16x32_bf16 v[24:27], v[178:181], v[186:189], v[24:27]
	v_mfma_f32_16x16x32_bf16 v[20:23], v[170:173], v[194:197], v[20:23]
	v_mfma_f32_16x16x32_bf16 v[16:19], v[178:181], v[194:197], v[16:19]
	v_mfma_f32_16x16x32_bf16 v[12:15], v[170:173], v[202:205], v[12:15]
	v_mfma_f32_16x16x32_bf16 v[8:11], v[178:181], v[202:205], v[8:11]
	v_mfma_f32_16x16x32_bf16 v[4:7], v[170:173], v[210:213], v[4:7]
	v_mfma_f32_16x16x32_bf16 v[0:3], v[178:181], v[210:213], v[0:3]
	v_mfma_f32_16x16x32_bf16 v[28:31], v[174:177], v[190:193], v[28:31]
	v_mfma_f32_16x16x32_bf16 v[24:27], v[182:185], v[190:193], v[24:27]
	v_mfma_f32_16x16x32_bf16 v[20:23], v[174:177], v[198:201], v[20:23]
	v_mfma_f32_16x16x32_bf16 v[16:19], v[182:185], v[198:201], v[16:19]
	v_mfma_f32_16x16x32_bf16 v[12:15], v[174:177], v[206:209], v[12:15]
	v_mfma_f32_16x16x32_bf16 v[8:11], v[182:185], v[206:209], v[8:11]
	s_barrier
	v_mfma_f32_16x16x32_bf16 v[4:7], v[174:177], v[214:217], v[4:7]
	v_mfma_f32_16x16x32_bf16 v[0:3], v[182:185], v[214:217], v[0:3]
	s_setprio 0
	s_add_i32 s63, s63, 2
	s_add_u32 s40, s40, 0x100
	s_addc_u32 s41, s41, 0
	s_add_u32 s61, s61, 0x100
	s_addc_u32 s62, s62, 0
	s_cmpk_gt_u32 s63, 0x7d
	s_cbranch_scc0 .LBB0_1219
	s_and_b64 vcc, exec, s[10:11]
	s_cbranch_vccz .LBB0_1222
	s_barrier
